# XCD-local grid barriers: row phases own the rows whose GEMM tiles run on their XCD; 20 of 31 barriers skip L2 write-back and the cross-XCD level (runtime-checked placement, global fallback)
# speedup vs baseline: 1.0395x; 1.0395x over previous
; DI int olane() { int l; asm volatile("v_mbcnt_lo_u32_b32 %0, -1, 0\n\tv_mbcnt_hi_u32_b32 %0, -1, %0" : "=v"(l)); return l; }
; #define LAS __attribute__((address_space(3)))
; DI unsigned xb_add(unsigned* p, unsigned v) { return __hip_atomic_fetch_add(p, v, __ATOMIC_RELAXED, __HIP_MEMORY_SCOPE_AGENT); }
; DI unsigned xb_xcc_id() { return (unsigned)__builtin_amdgcn_s_getreg((3 << 11) | 20) & 0xFu; }
; DI XcdBarrier xcd_barrier_post(unsigned* bar, volatile LAS unsigned* st, const int gw) {
;     XcdBarrier b; b.bar = bar; b.x = xb_xcc_id(); b.st = st;
;     if (gw == 0 && olane() == 0) (void)xb_add(&bar[XB_XCNT(b.x)], 1u);
;     return b;
; }
; __global__ void __launch_bounds__(NTHREADS) fwd_kernel(Params p) {
;     __shared__ __attribute__((aligned(16))) char lds[LDS_BYTES];
;     cg::grid_group grid = cg::this_grid();
;     __shared__ __attribute__((aligned(16))) unsigned xb_words[4];
;     if (threadIdx.x < 4) xb_words[threadIdx.x] = 0u;
;     __syncthreads();
;     const int g_wave = __builtin_amdgcn_readfirstlane((int)(threadIdx.x >> 6));
;     (void)xcd_barrier_post((unsigned*)(p.ws + OFF_BAR), (volatile LAS unsigned*)&xb_words, g_wave);
_Z10fwd_kernel6Params:
	s_load_dwordx4 s[28:31], s[0:1], 0x68
	s_add_u32 s4, s0, 0x80
	s_addc_u32 s5, s1, 0
	v_and_b32_e32 v1, 0x3ff, v0
	v_writelane_b32 v254, s4, 0
	v_cmp_gt_u32_e32 vcc, 4, v1
	s_nop 0
	v_writelane_b32 v254, s5, 1
	s_and_saveexec_b64 s[4:5], vcc
	v_mov_b32_e32 v2, 0x20040
	v_lshl_add_u32 v2, v1, 2, v2
	v_mov_b32_e32 v3, 0
	ds_write_b32 v2, v3
	s_or_b64 exec, exec, s[4:5]
	s_waitcnt lgkmcnt(0)
	s_add_u32 s6, s28, 0x156c1000
	v_readfirstlane_b32 s4, v1
	s_addc_u32 s7, s29, 0
	s_load_dwordx2 s[70:71], s[0:1], 0x80
	s_load_dword s3, s[0:1], 0x88
	v_writelane_b32 v254, s6, 2
	s_cmp_lt_u32 s4, 64
	s_waitcnt lgkmcnt(0)
	v_writelane_b32 v254, s7, 3
	s_cselect_b64 s[6:7], -1, 0
	v_writelane_b32 v254, s6, 4
	s_barrier
	s_nop 0
	v_writelane_b32 v254, s7, 5
	v_writelane_b32 v254, s4, 6
	s_cmp_gt_u32 s4, 63
	s_getreg_b32 s8, hwreg(HW_REG_XCC_ID, 0, 4)
	s_cbranch_scc1 .LBB0_7
	v_mbcnt_lo_u32_b32 v2, -1, 0
	v_mbcnt_hi_u32_b32 v2, -1, v2
	s_nop 0
	v_cmp_eq_u32_e32 vcc, 0, v2
	s_and_saveexec_b64 s[4:5], vcc
	s_cbranch_execz .LBB0_6
	s_mov_b64 s[6:7], exec
	v_mbcnt_lo_u32_b32 v2, s6, 0
	v_mbcnt_hi_u32_b32 v2, s7, v2
	v_cmp_eq_u32_e32 vcc, 0, v2
	s_and_b64 s[10:11], exec, vcc
	s_mov_b64 exec, s[10:11]
	s_cbranch_execz .LBB0_6
	s_lshl_b32 s8, s8, 8
	s_bcnt1_i32_b64 s6, s[6:7]
	s_and_b32 s8, s8, 0xf00
	v_mov_b32_e32 v3, s6
	v_readlane_b32 s6, v254, 2
	v_mov_b32_e32 v2, s8
	v_readlane_b32 s7, v254, 3
	s_lshr_b32 s12, s8, 8
	s_and_b32 s13, s2, 7
	s_lshl_b32 s13, s13, 2
	s_add_i32 s13, s13, 0x280
	s_lshl_b32 s12, 1, s12
	v_mov_b32_e32 v4, s13
	v_mov_b32_e32 v5, s12
	s_nop 4
	global_atomic_or v4, v5, s[6:7]
	s_waitcnt vmcnt(0)
	s_nop 4
	global_atomic_add v2, v3, s[6:7] offset:1024

; DI void row_phase(const bf16_t* msrc, const float* xsrc, float* xdst, const float* g_post, const float* g_next, bf16_t* hdst, const int gw) {
;     ...
;     for (int rowb = wg * RB; rowb < M_TOK; rowb += nw * RB) {
;         f32x4 xv[RB][4], mv[RB][4];
; #pragma unroll
;         for (int r = 0; r < RB; ++r)
; #pragma unroll
;             for (int j = 0; j < 4; ++j) xv[r][j] = *(const f32x4*)(xsrc + (size_t)(rowb + r) * DM + lane * 4 + 256 * j);
;         if (msrc) {
; #pragma unroll
;             for (int r = 0; r < RB; ++r)
; #pragma unroll
;                 for (int j = 0; j < 4; ++j) { const u32x2 mw = *(const u32x2*)(msrc + (size_t)(rowb + r) * DM + lane * 4 + 256 * j);
;                     mv[r][j] = (f32x4){__uint_as_float(mw[0] << 16), __uint_as_float(mw[0] & 0xffff0000u), __uint_as_float(mw[1] << 16), __uint_as_float(mw[1] & 0xffff0000u)}; }
;             float ss[RB];
; #pragma unroll
;             for (int r = 0; r < RB; ++r) { ss[r] = 0.f;
; #pragma unroll
;                 for (int j = 0; j < 4; ++j) ss[r] += mv[r][j][0] * mv[r][j][0] + mv[r][j][1] * mv[r][j][1] + mv[r][j][2] * mv[r][j][2] + mv[r][j][3] * mv[r][j][3]; }
; #pragma unroll
;             for (int o = 32; o >= 1; o >>= 1)
; #pragma unroll
;                 for (int r = 0; r < RB; ++r) ss[r] += shx(ss[r], o);
; #pragma unroll
;             for (int j = 0; j < 4; ++j) { const f32x4 g = *(const f32x4*)(g_post + lane * 4 + 256 * j);
; #pragma unroll
;                 for (int r = 0; r < RB; ++r) { const float r1 = rsqrtf(ss[r] * (1.f / DM) + EPS); xv[r][j] = xv[r][j] + mv[r][j] * r1 * g; *(f32x4*)(xdst + (size_t)(rowb + r) * DM + lane * 4 + 256 * j) = xv[r][j]; } }
;         }
;         if (hdst) {
;             float ss[RB];
; #pragma unroll
;             for (int r = 0; r < RB; ++r) { ss[r] = 0.f;
; #pragma unroll
;                 for (int j = 0; j < 4; ++j) ss[r] += xv[r][j][0] * xv[r][j][0] + xv[r][j][1] * xv[r][j][1] + xv[r][j][2] * xv[r][j][2] + xv[r][j][3] * xv[r][j][3]; }
; #pragma unroll
;             for (int o = 32; o >= 1; o >>= 1)
; #pragma unroll
;                 for (int r = 0; r < RB; ++r) ss[r] += shx(ss[r], o);
; #pragma unroll
;             for (int j = 0; j < 4; ++j) { const f32x4 g = *(const f32x4*)(g_next + lane * 4 + 256 * j);
; #pragma unroll
.Lrow_r1:
	v_writelane_b32 v3, s4, 0
	v_writelane_b32 v3, s5, 1
	v_writelane_b32 v3, s6, 2
	v_writelane_b32 v3, s7, 3
	v_writelane_b32 v3, s8, 4
	v_writelane_b32 v3, s9, 5
	v_writelane_b32 v3, s10, 6
	v_writelane_b32 v3, s11, 7
	v_writelane_b32 v3, s12, 8
	v_writelane_b32 v3, s13, 9
	v_writelane_b32 v3, s14, 10
	v_writelane_b32 v3, s15, 11
	v_writelane_b32 v3, s16, 12
	v_writelane_b32 v3, s17, 13
	v_writelane_b32 v3, s18, 14
	v_writelane_b32 v3, s19, 15
	v_writelane_b32 v3, s20, 16
	v_writelane_b32 v3, s21, 17
	v_writelane_b32 v3, s22, 18
	v_writelane_b32 v3, s23, 19
	v_writelane_b32 v3, s24, 20
	v_writelane_b32 v3, s25, 21
	s_waitcnt vmcnt(0) lgkmcnt(0)
	v_mbcnt_lo_u32_b32 v0, -1, 0
	v_mbcnt_hi_u32_b32 v0, -1, v0
	v_lshlrev_b32_e32 v1, 5, v0
	v_lshlrev_b32_e32 v2, 4, v0
	s_lshr_b32 s4, s71, 6
	s_and_b32 s5, s2, 7
	s_lshl_b32 s5, s5, 8
	s_lshr_b32 s24, s2, 3
	s_lshl_b32 s24, s24, 3
	s_add_i32 s5, s5, s24
	s_add_i32 s5, s5, s4
	s_lshl_b32 s24, s5, 15
	s_lshl_b32 s25, s5, 14
	v_readlane_b32 s8, v254, 62
	v_readlane_b32 s9, v254, 63
	v_readlane_b32 s6, v255, 2
	v_readlane_b32 s7, v255, 3
	v_readlane_b32 s4, v255, 6
	v_readlane_b32 s16, v255, 10
	v_readlane_b32 s17, v255, 11
	s_nop 1
	s_cmp_eq_u32 s4, 0
	s_cselect_b32 s6, s6, s8
	s_cselect_b32 s7, s7, s9
	s_add_u32 s6, s6, s24
	s_addc_u32 s7, s7, 0
	s_add_u32 s8, s8, s24
	s_addc_u32 s9, s9, 0
	s_add_u32 s10, s68, 0x10681000
	s_addc_u32 s11, s69, 0
	s_add_u32 s10, s10, s25
	s_addc_u32 s11, s11, 0
	s_add_u32 s12, s10, 0x2000000
	s_addc_u32 s13, s11, 0
	s_add_u32 s14, s82, s25
	s_addc_u32 s15, s83, 0
	s_add_u32 s18, s16, 0x1000
	s_addc_u32 s19, s17, 0
	global_load_dwordx4 v[40:43], v1, s[18:19] offset:0
	global_load_dwordx4 v[44:47], v1, s[18:19] offset:16
	global_load_dwordx4 v[48:51], v1, s[18:19] offset:2048
	global_load_dwordx4 v[52:55], v1, s[18:19] offset:2064
	s_add_u32 s18, s16, 0x2000
	s_addc_u32 s19, s17, 0
	global_load_dwordx4 v[56:59], v1, s[18:19] offset:0
	global_load_dwordx4 v[60:63], v1, s[18:19] offset:16
	global_load_dwordx4 v[64:67], v1, s[18:19] offset:2048
	global_load_dwordx4 v[68:71], v1, s[18:19] offset:2064
	global_load_dwordx4 v[96:99], v1, s[6:7] offset:0
	global_load_dwordx4 v[100:103], v1, s[6:7] offset:16
	global_load_dwordx4 v[104:107], v1, s[6:7] offset:2048
	global_load_dwordx4 v[108:111], v1, s[6:7] offset:2064
	global_load_dwordx4 v[112:115], v2, s[10:11]
	global_load_dwordx4 v[116:119], v2, s[10:11] offset:1024
	s_add_u32 s6, s6, 0x1000
	s_addc_u32 s7, s7, 0
	s_add_u32 s10, s10, 0x800
	s_addc_u32 s11, s11, 0
	global_load_dwordx4 v[128:131], v1, s[6:7] offset:0
	global_load_dwordx4 v[132:135], v1, s[6:7] offset:16
	global_load_dwordx4 v[136:139], v1, s[6:7] offset:2048
	global_load_dwordx4 v[140:143], v1, s[6:7] offset:2064
	global_load_dwordx4 v[144:147], v2, s[10:11]
	global_load_dwordx4 v[148:151], v2, s[10:11] offset:1024
	s_add_u32 s6, s6, 0x1000
	s_addc_u32 s7, s7, 0
	s_add_u32 s10, s10, 0x800
	s_addc_u32 s11, s11, 0
	global_load_dwordx4 v[160:163], v1, s[6:7] offset:0
	global_load_dwordx4 v[164:167], v1, s[6:7] offset:16
	global_load_dwordx4 v[168:171], v1, s[6:7] offset:2048
	global_load_dwordx4 v[172:175], v1, s[6:7] offset:2064
	global_load_dwordx4 v[176:179], v2, s[10:11]
	global_load_dwordx4 v[180:183], v2, s[10:11] offset:1024
	s_add_u32 s6, s6, 0x1000
	s_addc_u32 s7, s7, 0
	s_add_u32 s10, s10, 0x800
	s_addc_u32 s11, s11, 0
	s_waitcnt vmcnt(12)
	v_lshlrev_b32_e32 v208, 16, v112
	v_and_b32_e32 v209, 0xffff0000, v112
	v_lshlrev_b32_e32 v210, 16, v113
	v_and_b32_e32 v211, 0xffff0000, v113
	v_lshlrev_b32_e32 v212, 16, v114
	v_and_b32_e32 v213, 0xffff0000, v114
	v_lshlrev_b32_e32 v214, 16, v115
	v_and_b32_e32 v215, 0xffff0000, v115
	v_lshlrev_b32_e32 v216, 16, v116
	v_and_b32_e32 v217, 0xffff0000, v116
	v_lshlrev_b32_e32 v218, 16, v117
	v_and_b32_e32 v219, 0xffff0000, v117
	v_lshlrev_b32_e32 v220, 16, v118
	v_and_b32_e32 v221, 0xffff0000, v118
	v_lshlrev_b32_e32 v222, 16, v119
	v_and_b32_e32 v223, 0xffff0000, v119
	v_mul_f32_e32 v224, v208, v208
	v_fmac_f32_e32 v224, v209, v209
	v_fmac_f32_e32 v224, v210, v210
	v_fmac_f32_e32 v224, v211, v211
	v_fmac_f32_e32 v224, v212, v212
	v_fmac_f32_e32 v224, v213, v213
	v_fmac_f32_e32 v224, v214, v214
	v_fmac_f32_e32 v224, v215, v215
	v_fmac_f32_e32 v224, v216, v216
	v_fmac_f32_e32 v224, v217, v217
	v_fmac_f32_e32 v224, v218, v218
	v_fmac_f32_e32 v224, v219, v219
	v_fmac_f32_e32 v224, v220, v220
	v_fmac_f32_e32 v224, v221, v221
	v_fmac_f32_e32 v224, v222, v222
	v_fmac_f32_e32 v224, v223, v223
	s_nop 1
	v_add_f32_dpp v224, v224, v224 quad_perm:[1,0,3,2] row_mask:0xf bank_mask:0xf
	s_nop 1
	v_add_f32_dpp v224, v224, v224 quad_perm:[2,3,0,1] row_mask:0xf bank_mask:0xf
	s_nop 1
	v_add_f32_dpp v224, v224, v224 row_ror:4 row_mask:0xf bank_mask:0xf
	s_nop 1
	v_add_f32_dpp v224, v224, v224 row_ror:8 row_mask:0xf bank_mask:0xf
	s_nop 1
	v_readlane_b32 s20, v224, 0
	v_readlane_b32 s21, v224, 16
	v_readlane_b32 s22, v224, 32
	v_readlane_b32 s23, v224, 48
	s_nop 1
	v_mov_b32_e32 v225, s20
	v_add_f32_e32 v225, s21, v225
	v_add_f32_e32 v225, s22, v225
	v_add_f32_e32 v225, s23, v225
	v_mov_b32_e32 v226, 0x358637bd
	v_fmac_f32_e32 v226, 0x3a800000, v225
	v_rsq_f32_e32 v226, v226
	s_nop 0
	v_mul_f32_e32 v208, v208, v226
	v_mul_f32_e32 v209, v209, v226
	v_mul_f32_e32 v210, v210, v226
	v_mul_f32_e32 v211, v211, v226
	v_mul_f32_e32 v212, v212, v226
	v_mul_f32_e32 v213, v213, v226
	v_mul_f32_e32 v214, v214, v226
	v_mul_f32_e32 v215, v215, v226
	v_mul_f32_e32 v216, v216, v226
	v_mul_f32_e32 v217, v217, v226
	v_mul_f32_e32 v218, v218, v226
	v_mul_f32_e32 v219, v219, v226
	v_mul_f32_e32 v220, v220, v226
	v_mul_f32_e32 v221, v221, v226
; DI unsigned pk_bf16(float a, float b) { f32x2_t v = {a, b}; bf16x2_t r = __builtin_convertvector(v, bf16x2_t); return __builtin_bit_cast(unsigned, r); }
; DI void row_phase(const bf16_t* msrc, const float* xsrc, float* xdst, const float* g_post, const float* g_next, bf16_t* hdst, const int gw) {
;     ...
;                 for (int j = 0; j < 4; ++j) { const u32x2 mw = *(const u32x2*)(msrc + (size_t)(rowb + r) * DM + lane * 4 + 256 * j);
;                     mv[r][j] = (f32x4){__uint_as_float(mw[0] << 16), __uint_as_float(mw[0] & 0xffff0000u), __uint_as_float(mw[1] << 16), __uint_as_float(mw[1] & 0xffff0000u)}; }
;             float ss[RB];
; #pragma unroll
;             for (int r = 0; r < RB; ++r) { ss[r] = 0.f;
; #pragma unroll
;                 for (int j = 0; j < 4; ++j) ss[r] += mv[r][j][0] * mv[r][j][0] + mv[r][j][1] * mv[r][j][1] + mv[r][j][2] * mv[r][j][2] + mv[r][j][3] * mv[r][j][3]; }
; #pragma unroll
;             for (int o = 32; o >= 1; o >>= 1)
; #pragma unroll
;                 for (int r = 0; r < RB; ++r) ss[r] += shx(ss[r], o);
; #pragma unroll
;             for (int j = 0; j < 4; ++j) { const f32x4 g = *(const f32x4*)(g_post + lane * 4 + 256 * j);
; #pragma unroll
;                 for (int r = 0; r < RB; ++r) { const float r1 = rsqrtf(ss[r] * (1.f / DM) + EPS); xv[r][j] = xv[r][j] + mv[r][j] * r1 * g; *(f32x4*)(xdst + (size_t)(rowb + r) * DM + lane * 4 + 256 * j) = xv[r][j]; } }
;         }
;         if (hdst) {
;             float ss[RB];
; #pragma unroll
;             for (int r = 0; r < RB; ++r) { ss[r] = 0.f;
; #pragma unroll
;                 for (int j = 0; j < 4; ++j) ss[r] += xv[r][j][0] * xv[r][j][0] + xv[r][j][1] * xv[r][j][1] + xv[r][j][2] * xv[r][j][2] + xv[r][j][3] * xv[r][j][3]; }
; #pragma unroll
;             for (int o = 32; o >= 1; o >>= 1)
; #pragma unroll
;                 for (int r = 0; r < RB; ++r) ss[r] += shx(ss[r], o);
; #pragma unroll
;             for (int j = 0; j < 4; ++j) { const f32x4 g = *(const f32x4*)(g_next + lane * 4 + 256 * j);
; #pragma unroll
;                 for (int r = 0; r < RB; ++r) { const float r2 = rsqrtf(ss[r] * (1.f / DM) + EPS); const f32x4 hv = xv[r][j] * r2 * g;
;                     u32x2 o; o[0] = pk_bf16(hv[0], hv[1]); o[1] = pk_bf16(hv[2], hv[3]); *(u32x2*)(hdst + (size_t)(rowb + r) * DM + lane * 4 + 256 * j) = o; } }
	v_mul_f32_e32 v222, v222, v226
	v_mul_f32_e32 v223, v223, v226
	v_fmac_f32_e32 v96, v208, v40
	v_fmac_f32_e32 v97, v209, v41
	v_fmac_f32_e32 v98, v210, v42
	v_fmac_f32_e32 v99, v211, v43
	v_fmac_f32_e32 v100, v212, v44
	v_fmac_f32_e32 v101, v213, v45
	v_fmac_f32_e32 v102, v214, v46
	v_fmac_f32_e32 v103, v215, v47
	v_fmac_f32_e32 v104, v216, v48
	v_fmac_f32_e32 v105, v217, v49
	v_fmac_f32_e32 v106, v218, v50
	v_fmac_f32_e32 v107, v219, v51
	v_fmac_f32_e32 v108, v220, v52
	v_fmac_f32_e32 v109, v221, v53
	v_fmac_f32_e32 v110, v222, v54
	v_fmac_f32_e32 v111, v223, v55
	v_mul_f32_e32 v224, v96, v96
	v_fmac_f32_e32 v224, v97, v97
	v_fmac_f32_e32 v224, v98, v98
	v_fmac_f32_e32 v224, v99, v99
	v_fmac_f32_e32 v224, v100, v100
	v_fmac_f32_e32 v224, v101, v101
	v_fmac_f32_e32 v224, v102, v102
	v_fmac_f32_e32 v224, v103, v103
	v_fmac_f32_e32 v224, v104, v104
	v_fmac_f32_e32 v224, v105, v105
	v_fmac_f32_e32 v224, v106, v106
	v_fmac_f32_e32 v224, v107, v107
	v_fmac_f32_e32 v224, v108, v108
	v_fmac_f32_e32 v224, v109, v109
	v_fmac_f32_e32 v224, v110, v110
	v_fmac_f32_e32 v224, v111, v111
	s_nop 1
	v_add_f32_dpp v224, v224, v224 quad_perm:[1,0,3,2] row_mask:0xf bank_mask:0xf
	s_nop 1
	v_add_f32_dpp v224, v224, v224 quad_perm:[2,3,0,1] row_mask:0xf bank_mask:0xf
	s_nop 1
	v_add_f32_dpp v224, v224, v224 row_ror:4 row_mask:0xf bank_mask:0xf
	s_nop 1
	v_add_f32_dpp v224, v224, v224 row_ror:8 row_mask:0xf bank_mask:0xf
	s_nop 1
	v_readlane_b32 s20, v224, 0
	v_readlane_b32 s21, v224, 16
	v_readlane_b32 s22, v224, 32
	v_readlane_b32 s23, v224, 48
	s_nop 1
	v_mov_b32_e32 v225, s20
	v_add_f32_e32 v225, s21, v225
	v_add_f32_e32 v225, s22, v225
	v_add_f32_e32 v225, s23, v225
	v_mov_b32_e32 v226, 0x358637bd
	v_fmac_f32_e32 v226, 0x3a800000, v225
	v_rsq_f32_e32 v226, v226
	s_nop 0
	v_mul_f32_e32 v208, v96, v226
	v_mul_f32_e32 v209, v97, v226
	v_mul_f32_e32 v210, v98, v226
	v_mul_f32_e32 v211, v99, v226
	v_mul_f32_e32 v212, v100, v226
	v_mul_f32_e32 v213, v101, v226
	v_mul_f32_e32 v214, v102, v226
	v_mul_f32_e32 v215, v103, v226
	v_mul_f32_e32 v216, v104, v226
	v_mul_f32_e32 v217, v105, v226
	v_mul_f32_e32 v218, v106, v226
	v_mul_f32_e32 v219, v107, v226
	v_mul_f32_e32 v220, v108, v226
	v_mul_f32_e32 v221, v109, v226
	v_mul_f32_e32 v222, v110, v226
	v_mul_f32_e32 v223, v111, v226
	v_mul_f32_e32 v208, v208, v56
	v_mul_f32_e32 v209, v209, v57
	v_mul_f32_e32 v210, v210, v58
	v_mul_f32_e32 v211, v211, v59
	v_mul_f32_e32 v212, v212, v60
	v_mul_f32_e32 v213, v213, v61
	v_mul_f32_e32 v214, v214, v62
	v_mul_f32_e32 v215, v215, v63
	v_mul_f32_e32 v216, v216, v64
	v_mul_f32_e32 v217, v217, v65
	v_mul_f32_e32 v218, v218, v66
	v_mul_f32_e32 v219, v219, v67
	v_mul_f32_e32 v220, v220, v68
	v_mul_f32_e32 v221, v221, v69
	v_mul_f32_e32 v222, v222, v70
	v_mul_f32_e32 v223, v223, v71
	v_cvt_pk_bf16_f32 v112, v208, v209
	v_cvt_pk_bf16_f32 v113, v210, v211
	v_cvt_pk_bf16_f32 v114, v212, v213
	v_cvt_pk_bf16_f32 v115, v214, v215
	v_cvt_pk_bf16_f32 v116, v216, v217
	v_cvt_pk_bf16_f32 v117, v218, v219
	v_cvt_pk_bf16_f32 v118, v220, v221
	v_cvt_pk_bf16_f32 v119, v222, v223
	global_store_dwordx4 v2, v[112:115], s[14:15]
	global_store_dwordx4 v2, v[116:119], s[14:15] offset:1024
	s_add_u32 s14, s14, 0x800
	s_addc_u32 s15, s15, 0
	global_load_dwordx4 v[96:99], v1, s[6:7] offset:0
	global_load_dwordx4 v[100:103], v1, s[6:7] offset:16
	global_load_dwordx4 v[104:107], v1, s[6:7] offset:2048
	global_load_dwordx4 v[108:111], v1, s[6:7] offset:2064
	global_load_dwordx4 v[112:115], v2, s[10:11]
	global_load_dwordx4 v[116:119], v2, s[10:11] offset:1024
	s_add_u32 s6, s6, 0x1000
	s_addc_u32 s7, s7, 0
	s_add_u32 s10, s10, 0x800
	s_addc_u32 s11, s11, 0
	s_waitcnt vmcnt(14)
	v_lshlrev_b32_e32 v208, 16, v144
	v_and_b32_e32 v209, 0xffff0000, v144
	v_lshlrev_b32_e32 v210, 16, v145
	v_and_b32_e32 v211, 0xffff0000, v145
	v_lshlrev_b32_e32 v212, 16, v146
	v_and_b32_e32 v213, 0xffff0000, v146
	v_lshlrev_b32_e32 v214, 16, v147
	v_and_b32_e32 v215, 0xffff0000, v147
	v_lshlrev_b32_e32 v216, 16, v148
	v_and_b32_e32 v217, 0xffff0000, v148
	v_lshlrev_b32_e32 v218, 16, v149
	v_and_b32_e32 v219, 0xffff0000, v149
	v_lshlrev_b32_e32 v220, 16, v150
	v_and_b32_e32 v221, 0xffff0000, v150
	v_lshlrev_b32_e32 v222, 16, v151
	v_and_b32_e32 v223, 0xffff0000, v151
	v_mul_f32_e32 v224, v208, v208
	v_fmac_f32_e32 v224, v209, v209
	v_fmac_f32_e32 v224, v210, v210
	v_fmac_f32_e32 v224, v211, v211
	v_fmac_f32_e32 v224, v212, v212
	v_fmac_f32_e32 v224, v213, v213
	v_fmac_f32_e32 v224, v214, v214
	v_fmac_f32_e32 v224, v215, v215
	v_fmac_f32_e32 v224, v216, v216
	v_fmac_f32_e32 v224, v217, v217
	v_fmac_f32_e32 v224, v218, v218
	v_fmac_f32_e32 v224, v219, v219
	v_fmac_f32_e32 v224, v220, v220
	v_fmac_f32_e32 v224, v221, v221
	v_fmac_f32_e32 v224, v222, v222
	v_fmac_f32_e32 v224, v223, v223
	s_nop 1
	v_add_f32_dpp v224, v224, v224 quad_perm:[1,0,3,2] row_mask:0xf bank_mask:0xf
	s_nop 1
	v_add_f32_dpp v224, v224, v224 quad_perm:[2,3,0,1] row_mask:0xf bank_mask:0xf
	s_nop 1
	v_add_f32_dpp v224, v224, v224 row_ror:4 row_mask:0xf bank_mask:0xf
	s_nop 1
	v_add_f32_dpp v224, v224, v224 row_ror:8 row_mask:0xf bank_mask:0xf
	s_nop 1
	v_readlane_b32 s20, v224, 0
	v_readlane_b32 s21, v224, 16
	v_readlane_b32 s22, v224, 32
	v_readlane_b32 s23, v224, 48
	s_nop 1
	v_mov_b32_e32 v225, s20
	v_add_f32_e32 v225, s21, v225
	v_add_f32_e32 v225, s22, v225
	v_add_f32_e32 v225, s23, v225
	v_mov_b32_e32 v226, 0x358637bd
	v_fmac_f32_e32 v226, 0x3a800000, v225
	v_rsq_f32_e32 v226, v226
	s_nop 0
	v_mul_f32_e32 v208, v208, v226
	v_mul_f32_e32 v209, v209, v226
	v_mul_f32_e32 v210, v210, v226
	v_mul_f32_e32 v211, v211, v226
	v_mul_f32_e32 v212, v212, v226
; DI unsigned pk_bf16(float a, float b) { f32x2_t v = {a, b}; bf16x2_t r = __builtin_convertvector(v, bf16x2_t); return __builtin_bit_cast(unsigned, r); }
; DI void row_phase(const bf16_t* msrc, const float* xsrc, float* xdst, const float* g_post, const float* g_next, bf16_t* hdst, const int gw) {
;     ...
;                 for (int j = 0; j < 4; ++j) { const u32x2 mw = *(const u32x2*)(msrc + (size_t)(rowb + r) * DM + lane * 4 + 256 * j);
;                     mv[r][j] = (f32x4){__uint_as_float(mw[0] << 16), __uint_as_float(mw[0] & 0xffff0000u), __uint_as_float(mw[1] << 16), __uint_as_float(mw[1] & 0xffff0000u)}; }
;             float ss[RB];
; #pragma unroll
;             for (int r = 0; r < RB; ++r) { ss[r] = 0.f;
; #pragma unroll
;                 for (int j = 0; j < 4; ++j) ss[r] += mv[r][j][0] * mv[r][j][0] + mv[r][j][1] * mv[r][j][1] + mv[r][j][2] * mv[r][j][2] + mv[r][j][3] * mv[r][j][3]; }
; #pragma unroll
;             for (int o = 32; o >= 1; o >>= 1)
; #pragma unroll
;                 for (int r = 0; r < RB; ++r) ss[r] += shx(ss[r], o);
; #pragma unroll
;             for (int j = 0; j < 4; ++j) { const f32x4 g = *(const f32x4*)(g_post + lane * 4 + 256 * j);
; #pragma unroll
;                 for (int r = 0; r < RB; ++r) { const float r1 = rsqrtf(ss[r] * (1.f / DM) + EPS); xv[r][j] = xv[r][j] + mv[r][j] * r1 * g; *(f32x4*)(xdst + (size_t)(rowb + r) * DM + lane * 4 + 256 * j) = xv[r][j]; } }
;         }
;         if (hdst) {
;             float ss[RB];
; #pragma unroll
;             for (int r = 0; r < RB; ++r) { ss[r] = 0.f;
; #pragma unroll
;                 for (int j = 0; j < 4; ++j) ss[r] += xv[r][j][0] * xv[r][j][0] + xv[r][j][1] * xv[r][j][1] + xv[r][j][2] * xv[r][j][2] + xv[r][j][3] * xv[r][j][3]; }
; #pragma unroll
;             for (int o = 32; o >= 1; o >>= 1)
; #pragma unroll
;                 for (int r = 0; r < RB; ++r) ss[r] += shx(ss[r], o);
; #pragma unroll
;             for (int j = 0; j < 4; ++j) { const f32x4 g = *(const f32x4*)(g_next + lane * 4 + 256 * j);
; #pragma unroll
;                 for (int r = 0; r < RB; ++r) { const float r2 = rsqrtf(ss[r] * (1.f / DM) + EPS); const f32x4 hv = xv[r][j] * r2 * g;
;                     u32x2 o; o[0] = pk_bf16(hv[0], hv[1]); o[1] = pk_bf16(hv[2], hv[3]); *(u32x2*)(hdst + (size_t)(rowb + r) * DM + lane * 4 + 256 * j) = o; } }
	v_mul_f32_e32 v213, v213, v226
	v_mul_f32_e32 v214, v214, v226
	v_mul_f32_e32 v215, v215, v226
	v_mul_f32_e32 v216, v216, v226
	v_mul_f32_e32 v217, v217, v226
	v_mul_f32_e32 v218, v218, v226
	v_mul_f32_e32 v219, v219, v226
	v_mul_f32_e32 v220, v220, v226
	v_mul_f32_e32 v221, v221, v226
	v_mul_f32_e32 v222, v222, v226
	v_mul_f32_e32 v223, v223, v226
	v_fmac_f32_e32 v128, v208, v40
	v_fmac_f32_e32 v129, v209, v41
	v_fmac_f32_e32 v130, v210, v42
	v_fmac_f32_e32 v131, v211, v43
	v_fmac_f32_e32 v132, v212, v44
	v_fmac_f32_e32 v133, v213, v45
	v_fmac_f32_e32 v134, v214, v46
	v_fmac_f32_e32 v135, v215, v47
	v_fmac_f32_e32 v136, v216, v48
	v_fmac_f32_e32 v137, v217, v49
	v_fmac_f32_e32 v138, v218, v50
	v_fmac_f32_e32 v139, v219, v51
	v_fmac_f32_e32 v140, v220, v52
	v_fmac_f32_e32 v141, v221, v53
	v_fmac_f32_e32 v142, v222, v54
	v_fmac_f32_e32 v143, v223, v55
	v_mul_f32_e32 v224, v128, v128
	v_fmac_f32_e32 v224, v129, v129
	v_fmac_f32_e32 v224, v130, v130
	v_fmac_f32_e32 v224, v131, v131
	v_fmac_f32_e32 v224, v132, v132
	v_fmac_f32_e32 v224, v133, v133
	v_fmac_f32_e32 v224, v134, v134
	v_fmac_f32_e32 v224, v135, v135
	v_fmac_f32_e32 v224, v136, v136
	v_fmac_f32_e32 v224, v137, v137
	v_fmac_f32_e32 v224, v138, v138
	v_fmac_f32_e32 v224, v139, v139
	v_fmac_f32_e32 v224, v140, v140
	v_fmac_f32_e32 v224, v141, v141
	v_fmac_f32_e32 v224, v142, v142
	v_fmac_f32_e32 v224, v143, v143
	s_nop 1
	v_add_f32_dpp v224, v224, v224 quad_perm:[1,0,3,2] row_mask:0xf bank_mask:0xf
	s_nop 1
	v_add_f32_dpp v224, v224, v224 quad_perm:[2,3,0,1] row_mask:0xf bank_mask:0xf
	s_nop 1
	v_add_f32_dpp v224, v224, v224 row_ror:4 row_mask:0xf bank_mask:0xf
	s_nop 1
	v_add_f32_dpp v224, v224, v224 row_ror:8 row_mask:0xf bank_mask:0xf
	s_nop 1
	v_readlane_b32 s20, v224, 0
	v_readlane_b32 s21, v224, 16
	v_readlane_b32 s22, v224, 32
	v_readlane_b32 s23, v224, 48
	s_nop 1
	v_mov_b32_e32 v225, s20
	v_add_f32_e32 v225, s21, v225
	v_add_f32_e32 v225, s22, v225
	v_add_f32_e32 v225, s23, v225
	v_mov_b32_e32 v226, 0x358637bd
	v_fmac_f32_e32 v226, 0x3a800000, v225
	v_rsq_f32_e32 v226, v226
	s_nop 0
	v_mul_f32_e32 v208, v128, v226
	v_mul_f32_e32 v209, v129, v226
	v_mul_f32_e32 v210, v130, v226
	v_mul_f32_e32 v211, v131, v226
	v_mul_f32_e32 v212, v132, v226
	v_mul_f32_e32 v213, v133, v226
	v_mul_f32_e32 v214, v134, v226
	v_mul_f32_e32 v215, v135, v226
	v_mul_f32_e32 v216, v136, v226
	v_mul_f32_e32 v217, v137, v226
	v_mul_f32_e32 v218, v138, v226
	v_mul_f32_e32 v219, v139, v226
	v_mul_f32_e32 v220, v140, v226
	v_mul_f32_e32 v221, v141, v226
	v_mul_f32_e32 v222, v142, v226
	v_mul_f32_e32 v223, v143, v226
	v_mul_f32_e32 v208, v208, v56
	v_mul_f32_e32 v209, v209, v57
	v_mul_f32_e32 v210, v210, v58
	v_mul_f32_e32 v211, v211, v59
	v_mul_f32_e32 v212, v212, v60
	v_mul_f32_e32 v213, v213, v61
	v_mul_f32_e32 v214, v214, v62
	v_mul_f32_e32 v215, v215, v63
	v_mul_f32_e32 v216, v216, v64
	v_mul_f32_e32 v217, v217, v65
	v_mul_f32_e32 v218, v218, v66
	v_mul_f32_e32 v219, v219, v67
	v_mul_f32_e32 v220, v220, v68
	v_mul_f32_e32 v221, v221, v69
	v_mul_f32_e32 v222, v222, v70
	v_mul_f32_e32 v223, v223, v71
	v_cvt_pk_bf16_f32 v144, v208, v209
	v_cvt_pk_bf16_f32 v145, v210, v211
	v_cvt_pk_bf16_f32 v146, v212, v213
	v_cvt_pk_bf16_f32 v147, v214, v215
	v_cvt_pk_bf16_f32 v148, v216, v217
	v_cvt_pk_bf16_f32 v149, v218, v219
	v_cvt_pk_bf16_f32 v150, v220, v221
	v_cvt_pk_bf16_f32 v151, v222, v223
	global_store_dwordx4 v2, v[144:147], s[14:15]
	global_store_dwordx4 v2, v[148:151], s[14:15] offset:1024
	s_add_u32 s14, s14, 0x800
	s_addc_u32 s15, s15, 0
	global_load_dwordx4 v[128:131], v1, s[6:7] offset:0
	global_load_dwordx4 v[132:135], v1, s[6:7] offset:16
	global_load_dwordx4 v[136:139], v1, s[6:7] offset:2048
	global_load_dwordx4 v[140:143], v1, s[6:7] offset:2064
	global_load_dwordx4 v[144:147], v2, s[10:11]
	global_load_dwordx4 v[148:151], v2, s[10:11] offset:1024
	s_add_u32 s6, s6, 0x1000
	s_addc_u32 s7, s7, 0
	s_add_u32 s10, s10, 0x800
	s_addc_u32 s11, s11, 0
	s_waitcnt vmcnt(16)
	v_lshlrev_b32_e32 v208, 16, v176
	v_and_b32_e32 v209, 0xffff0000, v176
	v_lshlrev_b32_e32 v210, 16, v177
	v_and_b32_e32 v211, 0xffff0000, v177
	v_lshlrev_b32_e32 v212, 16, v178
	v_and_b32_e32 v213, 0xffff0000, v178
	v_lshlrev_b32_e32 v214, 16, v179
	v_and_b32_e32 v215, 0xffff0000, v179
	v_lshlrev_b32_e32 v216, 16, v180
	v_and_b32_e32 v217, 0xffff0000, v180
	v_lshlrev_b32_e32 v218, 16, v181
	v_and_b32_e32 v219, 0xffff0000, v181
	v_lshlrev_b32_e32 v220, 16, v182
	v_and_b32_e32 v221, 0xffff0000, v182
	v_lshlrev_b32_e32 v222, 16, v183
	v_and_b32_e32 v223, 0xffff0000, v183
	v_mul_f32_e32 v224, v208, v208
	v_fmac_f32_e32 v224, v209, v209
	v_fmac_f32_e32 v224, v210, v210
	v_fmac_f32_e32 v224, v211, v211
	v_fmac_f32_e32 v224, v212, v212
	v_fmac_f32_e32 v224, v213, v213
	v_fmac_f32_e32 v224, v214, v214
	v_fmac_f32_e32 v224, v215, v215
	v_fmac_f32_e32 v224, v216, v216
	v_fmac_f32_e32 v224, v217, v217
	v_fmac_f32_e32 v224, v218, v218
	v_fmac_f32_e32 v224, v219, v219
	v_fmac_f32_e32 v224, v220, v220
	v_fmac_f32_e32 v224, v221, v221
	v_fmac_f32_e32 v224, v222, v222
	v_fmac_f32_e32 v224, v223, v223
	s_nop 1
	v_add_f32_dpp v224, v224, v224 quad_perm:[1,0,3,2] row_mask:0xf bank_mask:0xf
	s_nop 1
	v_add_f32_dpp v224, v224, v224 quad_perm:[2,3,0,1] row_mask:0xf bank_mask:0xf
	s_nop 1
	v_add_f32_dpp v224, v224, v224 row_ror:4 row_mask:0xf bank_mask:0xf
	s_nop 1
	v_add_f32_dpp v224, v224, v224 row_ror:8 row_mask:0xf bank_mask:0xf
	s_nop 1
	v_readlane_b32 s20, v224, 0
	v_readlane_b32 s21, v224, 16
	v_readlane_b32 s22, v224, 32
	v_readlane_b32 s23, v224, 48
	s_nop 1
	v_mov_b32_e32 v225, s20
	v_add_f32_e32 v225, s21, v225
	v_add_f32_e32 v225, s22, v225
; DI unsigned pk_bf16(float a, float b) { f32x2_t v = {a, b}; bf16x2_t r = __builtin_convertvector(v, bf16x2_t); return __builtin_bit_cast(unsigned, r); }
; DI void row_phase(const bf16_t* msrc, const float* xsrc, float* xdst, const float* g_post, const float* g_next, bf16_t* hdst, const int gw) {
;     ...
;                 for (int j = 0; j < 4; ++j) { const u32x2 mw = *(const u32x2*)(msrc + (size_t)(rowb + r) * DM + lane * 4 + 256 * j);
;                     mv[r][j] = (f32x4){__uint_as_float(mw[0] << 16), __uint_as_float(mw[0] & 0xffff0000u), __uint_as_float(mw[1] << 16), __uint_as_float(mw[1] & 0xffff0000u)}; }
;             float ss[RB];
; #pragma unroll
;             for (int r = 0; r < RB; ++r) { ss[r] = 0.f;
; #pragma unroll
;                 for (int j = 0; j < 4; ++j) ss[r] += mv[r][j][0] * mv[r][j][0] + mv[r][j][1] * mv[r][j][1] + mv[r][j][2] * mv[r][j][2] + mv[r][j][3] * mv[r][j][3]; }
; #pragma unroll
;             for (int o = 32; o >= 1; o >>= 1)
; #pragma unroll
;                 for (int r = 0; r < RB; ++r) ss[r] += shx(ss[r], o);
; #pragma unroll
;             for (int j = 0; j < 4; ++j) { const f32x4 g = *(const f32x4*)(g_post + lane * 4 + 256 * j);
; #pragma unroll
;                 for (int r = 0; r < RB; ++r) { const float r1 = rsqrtf(ss[r] * (1.f / DM) + EPS); xv[r][j] = xv[r][j] + mv[r][j] * r1 * g; *(f32x4*)(xdst + (size_t)(rowb + r) * DM + lane * 4 + 256 * j) = xv[r][j]; } }
;         }
;         if (hdst) {
;             float ss[RB];
; #pragma unroll
;             for (int r = 0; r < RB; ++r) { ss[r] = 0.f;
; #pragma unroll
;                 for (int j = 0; j < 4; ++j) ss[r] += xv[r][j][0] * xv[r][j][0] + xv[r][j][1] * xv[r][j][1] + xv[r][j][2] * xv[r][j][2] + xv[r][j][3] * xv[r][j][3]; }
; #pragma unroll
;             for (int o = 32; o >= 1; o >>= 1)
; #pragma unroll
;                 for (int r = 0; r < RB; ++r) ss[r] += shx(ss[r], o);
; #pragma unroll
;             for (int j = 0; j < 4; ++j) { const f32x4 g = *(const f32x4*)(g_next + lane * 4 + 256 * j);
; #pragma unroll
;                 for (int r = 0; r < RB; ++r) { const float r2 = rsqrtf(ss[r] * (1.f / DM) + EPS); const f32x4 hv = xv[r][j] * r2 * g;
;                     u32x2 o; o[0] = pk_bf16(hv[0], hv[1]); o[1] = pk_bf16(hv[2], hv[3]); *(u32x2*)(hdst + (size_t)(rowb + r) * DM + lane * 4 + 256 * j) = o; } }
	v_add_f32_e32 v225, s23, v225
	v_mov_b32_e32 v226, 0x358637bd
	v_fmac_f32_e32 v226, 0x3a800000, v225
	v_rsq_f32_e32 v226, v226
	s_nop 0
	v_mul_f32_e32 v208, v208, v226
	v_mul_f32_e32 v209, v209, v226
	v_mul_f32_e32 v210, v210, v226
	v_mul_f32_e32 v211, v211, v226
	v_mul_f32_e32 v212, v212, v226
	v_mul_f32_e32 v213, v213, v226
	v_mul_f32_e32 v214, v214, v226
	v_mul_f32_e32 v215, v215, v226
	v_mul_f32_e32 v216, v216, v226
	v_mul_f32_e32 v217, v217, v226
	v_mul_f32_e32 v218, v218, v226
	v_mul_f32_e32 v219, v219, v226
	v_mul_f32_e32 v220, v220, v226
	v_mul_f32_e32 v221, v221, v226
	v_mul_f32_e32 v222, v222, v226
	v_mul_f32_e32 v223, v223, v226
	v_fmac_f32_e32 v160, v208, v40
	v_fmac_f32_e32 v161, v209, v41
	v_fmac_f32_e32 v162, v210, v42
	v_fmac_f32_e32 v163, v211, v43
	v_fmac_f32_e32 v164, v212, v44
	v_fmac_f32_e32 v165, v213, v45
	v_fmac_f32_e32 v166, v214, v46
	v_fmac_f32_e32 v167, v215, v47
	v_fmac_f32_e32 v168, v216, v48
	v_fmac_f32_e32 v169, v217, v49
	v_fmac_f32_e32 v170, v218, v50
	v_fmac_f32_e32 v171, v219, v51
	v_fmac_f32_e32 v172, v220, v52
	v_fmac_f32_e32 v173, v221, v53
	v_fmac_f32_e32 v174, v222, v54
	v_fmac_f32_e32 v175, v223, v55
	v_mul_f32_e32 v224, v160, v160
	v_fmac_f32_e32 v224, v161, v161
	v_fmac_f32_e32 v224, v162, v162
	v_fmac_f32_e32 v224, v163, v163
	v_fmac_f32_e32 v224, v164, v164
	v_fmac_f32_e32 v224, v165, v165
	v_fmac_f32_e32 v224, v166, v166
	v_fmac_f32_e32 v224, v167, v167
	v_fmac_f32_e32 v224, v168, v168
	v_fmac_f32_e32 v224, v169, v169
	v_fmac_f32_e32 v224, v170, v170
	v_fmac_f32_e32 v224, v171, v171
	v_fmac_f32_e32 v224, v172, v172
	v_fmac_f32_e32 v224, v173, v173
	v_fmac_f32_e32 v224, v174, v174
	v_fmac_f32_e32 v224, v175, v175
	s_nop 1
	v_add_f32_dpp v224, v224, v224 quad_perm:[1,0,3,2] row_mask:0xf bank_mask:0xf
	s_nop 1
	v_add_f32_dpp v224, v224, v224 quad_perm:[2,3,0,1] row_mask:0xf bank_mask:0xf
	s_nop 1
	v_add_f32_dpp v224, v224, v224 row_ror:4 row_mask:0xf bank_mask:0xf
	s_nop 1
	v_add_f32_dpp v224, v224, v224 row_ror:8 row_mask:0xf bank_mask:0xf
	s_nop 1
	v_readlane_b32 s20, v224, 0
	v_readlane_b32 s21, v224, 16
	v_readlane_b32 s22, v224, 32
	v_readlane_b32 s23, v224, 48
	s_nop 1
	v_mov_b32_e32 v225, s20
	v_add_f32_e32 v225, s21, v225
	v_add_f32_e32 v225, s22, v225
	v_add_f32_e32 v225, s23, v225
	v_mov_b32_e32 v226, 0x358637bd
	v_fmac_f32_e32 v226, 0x3a800000, v225
	v_rsq_f32_e32 v226, v226
	s_nop 0
	v_mul_f32_e32 v208, v160, v226
	v_mul_f32_e32 v209, v161, v226
	v_mul_f32_e32 v210, v162, v226
	v_mul_f32_e32 v211, v163, v226
	v_mul_f32_e32 v212, v164, v226
	v_mul_f32_e32 v213, v165, v226
	v_mul_f32_e32 v214, v166, v226
	v_mul_f32_e32 v215, v167, v226
	v_mul_f32_e32 v216, v168, v226
	v_mul_f32_e32 v217, v169, v226
	v_mul_f32_e32 v218, v170, v226
	v_mul_f32_e32 v219, v171, v226
	v_mul_f32_e32 v220, v172, v226
	v_mul_f32_e32 v221, v173, v226
	v_mul_f32_e32 v222, v174, v226
	v_mul_f32_e32 v223, v175, v226
	v_mul_f32_e32 v208, v208, v56
	v_mul_f32_e32 v209, v209, v57
	v_mul_f32_e32 v210, v210, v58
	v_mul_f32_e32 v211, v211, v59
	v_mul_f32_e32 v212, v212, v60
	v_mul_f32_e32 v213, v213, v61
	v_mul_f32_e32 v214, v214, v62
	v_mul_f32_e32 v215, v215, v63
	v_mul_f32_e32 v216, v216, v64
	v_mul_f32_e32 v217, v217, v65
	v_mul_f32_e32 v218, v218, v66
	v_mul_f32_e32 v219, v219, v67
	v_mul_f32_e32 v220, v220, v68
	v_mul_f32_e32 v221, v221, v69
	v_mul_f32_e32 v222, v222, v70
	v_mul_f32_e32 v223, v223, v71
	v_cvt_pk_bf16_f32 v176, v208, v209
	v_cvt_pk_bf16_f32 v177, v210, v211
	v_cvt_pk_bf16_f32 v178, v212, v213
	v_cvt_pk_bf16_f32 v179, v214, v215
	v_cvt_pk_bf16_f32 v180, v216, v217
	v_cvt_pk_bf16_f32 v181, v218, v219
	v_cvt_pk_bf16_f32 v182, v220, v221
	v_cvt_pk_bf16_f32 v183, v222, v223
	global_store_dwordx4 v2, v[176:179], s[14:15]
	global_store_dwordx4 v2, v[180:183], s[14:15] offset:1024
	s_add_u32 s14, s14, 0x800
	s_addc_u32 s15, s15, 0
	global_load_dwordx4 v[160:163], v1, s[6:7] offset:0
	global_load_dwordx4 v[164:167], v1, s[6:7] offset:16
	global_load_dwordx4 v[168:171], v1, s[6:7] offset:2048
	global_load_dwordx4 v[172:175], v1, s[6:7] offset:2064
	global_load_dwordx4 v[176:179], v2, s[10:11]
	global_load_dwordx4 v[180:183], v2, s[10:11] offset:1024
	s_add_u32 s6, s6, 0x1000
	s_addc_u32 s7, s7, 0
	s_add_u32 s10, s10, 0x800
	s_addc_u32 s11, s11, 0
	s_waitcnt vmcnt(16)
; DI unsigned pk_bf16(float a, float b) { f32x2_t v = {a, b}; bf16x2_t r = __builtin_convertvector(v, bf16x2_t); return __builtin_bit_cast(unsigned, r); }
; DI void row_phase(const bf16_t* msrc, const float* xsrc, float* xdst, const float* g_post, const float* g_next, bf16_t* hdst, const int gw) {
;     ...
;                 for (int j = 0; j < 4; ++j) { const u32x2 mw = *(const u32x2*)(msrc + (size_t)(rowb + r) * DM + lane * 4 + 256 * j);
;                     mv[r][j] = (f32x4){__uint_as_float(mw[0] << 16), __uint_as_float(mw[0] & 0xffff0000u), __uint_as_float(mw[1] << 16), __uint_as_float(mw[1] & 0xffff0000u)}; }
;             float ss[RB];
; #pragma unroll
;             for (int r = 0; r < RB; ++r) { ss[r] = 0.f;
; #pragma unroll
;                 for (int j = 0; j < 4; ++j) ss[r] += mv[r][j][0] * mv[r][j][0] + mv[r][j][1] * mv[r][j][1] + mv[r][j][2] * mv[r][j][2] + mv[r][j][3] * mv[r][j][3]; }
; #pragma unroll
;             for (int o = 32; o >= 1; o >>= 1)
; #pragma unroll
;                 for (int r = 0; r < RB; ++r) ss[r] += shx(ss[r], o);
; #pragma unroll
;             for (int j = 0; j < 4; ++j) { const f32x4 g = *(const f32x4*)(g_post + lane * 4 + 256 * j);
; #pragma unroll
;                 for (int r = 0; r < RB; ++r) { const float r1 = rsqrtf(ss[r] * (1.f / DM) + EPS); xv[r][j] = xv[r][j] + mv[r][j] * r1 * g; *(f32x4*)(xdst + (size_t)(rowb + r) * DM + lane * 4 + 256 * j) = xv[r][j]; } }
;         }
;         if (hdst) {
;             float ss[RB];
; #pragma unroll
;             for (int r = 0; r < RB; ++r) { ss[r] = 0.f;
; #pragma unroll
;                 for (int j = 0; j < 4; ++j) ss[r] += xv[r][j][0] * xv[r][j][0] + xv[r][j][1] * xv[r][j][1] + xv[r][j][2] * xv[r][j][2] + xv[r][j][3] * xv[r][j][3]; }
; #pragma unroll
;             for (int o = 32; o >= 1; o >>= 1)
; #pragma unroll
;                 for (int r = 0; r < RB; ++r) ss[r] += shx(ss[r], o);
; #pragma unroll
;             for (int j = 0; j < 4; ++j) { const f32x4 g = *(const f32x4*)(g_next + lane * 4 + 256 * j);
; #pragma unroll
;                 for (int r = 0; r < RB; ++r) { const float r2 = rsqrtf(ss[r] * (1.f / DM) + EPS); const f32x4 hv = xv[r][j] * r2 * g;
;                     u32x2 o; o[0] = pk_bf16(hv[0], hv[1]); o[1] = pk_bf16(hv[2], hv[3]); *(u32x2*)(hdst + (size_t)(rowb + r) * DM + lane * 4 + 256 * j) = o; } }
	v_lshlrev_b32_e32 v208, 16, v112
	v_and_b32_e32 v209, 0xffff0000, v112
	v_lshlrev_b32_e32 v210, 16, v113
	v_and_b32_e32 v211, 0xffff0000, v113
	v_lshlrev_b32_e32 v212, 16, v114
	v_and_b32_e32 v213, 0xffff0000, v114
	v_lshlrev_b32_e32 v214, 16, v115
	v_and_b32_e32 v215, 0xffff0000, v115
	v_lshlrev_b32_e32 v216, 16, v116
	v_and_b32_e32 v217, 0xffff0000, v116
	v_lshlrev_b32_e32 v218, 16, v117
	v_and_b32_e32 v219, 0xffff0000, v117
	v_lshlrev_b32_e32 v220, 16, v118
	v_and_b32_e32 v221, 0xffff0000, v118
	v_lshlrev_b32_e32 v222, 16, v119
	v_and_b32_e32 v223, 0xffff0000, v119
	v_mul_f32_e32 v224, v208, v208
	v_fmac_f32_e32 v224, v209, v209
	v_fmac_f32_e32 v224, v210, v210
	v_fmac_f32_e32 v224, v211, v211
	v_fmac_f32_e32 v224, v212, v212
	v_fmac_f32_e32 v224, v213, v213
	v_fmac_f32_e32 v224, v214, v214
	v_fmac_f32_e32 v224, v215, v215
	v_fmac_f32_e32 v224, v216, v216
	v_fmac_f32_e32 v224, v217, v217
	v_fmac_f32_e32 v224, v218, v218
	v_fmac_f32_e32 v224, v219, v219
	v_fmac_f32_e32 v224, v220, v220
	v_fmac_f32_e32 v224, v221, v221
	v_fmac_f32_e32 v224, v222, v222
	v_fmac_f32_e32 v224, v223, v223
	s_nop 1
	v_add_f32_dpp v224, v224, v224 quad_perm:[1,0,3,2] row_mask:0xf bank_mask:0xf
	s_nop 1
	v_add_f32_dpp v224, v224, v224 quad_perm:[2,3,0,1] row_mask:0xf bank_mask:0xf
	s_nop 1
	v_add_f32_dpp v224, v224, v224 row_ror:4 row_mask:0xf bank_mask:0xf
	s_nop 1
	v_add_f32_dpp v224, v224, v224 row_ror:8 row_mask:0xf bank_mask:0xf
	s_nop 1
	v_readlane_b32 s20, v224, 0
	v_readlane_b32 s21, v224, 16
	v_readlane_b32 s22, v224, 32
	v_readlane_b32 s23, v224, 48
	s_nop 1
	v_mov_b32_e32 v225, s20
	v_add_f32_e32 v225, s21, v225
	v_add_f32_e32 v225, s22, v225
	v_add_f32_e32 v225, s23, v225
	v_mov_b32_e32 v226, 0x358637bd
	v_fmac_f32_e32 v226, 0x3a800000, v225
	v_rsq_f32_e32 v226, v226
	s_nop 0
	v_mul_f32_e32 v208, v208, v226
	v_mul_f32_e32 v209, v209, v226
	v_mul_f32_e32 v210, v210, v226
	v_mul_f32_e32 v211, v211, v226
	v_mul_f32_e32 v212, v212, v226
	v_mul_f32_e32 v213, v213, v226
	v_mul_f32_e32 v214, v214, v226
	v_mul_f32_e32 v215, v215, v226
	v_mul_f32_e32 v216, v216, v226
	v_mul_f32_e32 v217, v217, v226
	v_mul_f32_e32 v218, v218, v226
	v_mul_f32_e32 v219, v219, v226
	v_mul_f32_e32 v220, v220, v226
	v_mul_f32_e32 v221, v221, v226
	v_mul_f32_e32 v222, v222, v226
	v_mul_f32_e32 v223, v223, v226
	v_fmac_f32_e32 v96, v208, v40
	v_fmac_f32_e32 v97, v209, v41
	v_fmac_f32_e32 v98, v210, v42
	v_fmac_f32_e32 v99, v211, v43
	v_fmac_f32_e32 v100, v212, v44
	v_fmac_f32_e32 v101, v213, v45
	v_fmac_f32_e32 v102, v214, v46
	v_fmac_f32_e32 v103, v215, v47
	v_fmac_f32_e32 v104, v216, v48
	v_fmac_f32_e32 v105, v217, v49
	v_fmac_f32_e32 v106, v218, v50
	v_fmac_f32_e32 v107, v219, v51
	v_fmac_f32_e32 v108, v220, v52
	v_fmac_f32_e32 v109, v221, v53
	v_fmac_f32_e32 v110, v222, v54
	v_fmac_f32_e32 v111, v223, v55
	v_mul_f32_e32 v224, v96, v96
	v_fmac_f32_e32 v224, v97, v97
	v_fmac_f32_e32 v224, v98, v98
	v_fmac_f32_e32 v224, v99, v99
	v_fmac_f32_e32 v224, v100, v100
	v_fmac_f32_e32 v224, v101, v101
	v_fmac_f32_e32 v224, v102, v102
	v_fmac_f32_e32 v224, v103, v103
	v_fmac_f32_e32 v224, v104, v104
	v_fmac_f32_e32 v224, v105, v105
	v_fmac_f32_e32 v224, v106, v106
	v_fmac_f32_e32 v224, v107, v107
	v_fmac_f32_e32 v224, v108, v108
	v_fmac_f32_e32 v224, v109, v109
	v_fmac_f32_e32 v224, v110, v110
	v_fmac_f32_e32 v224, v111, v111
	s_nop 1
	v_add_f32_dpp v224, v224, v224 quad_perm:[1,0,3,2] row_mask:0xf bank_mask:0xf
	s_nop 1
	v_add_f32_dpp v224, v224, v224 quad_perm:[2,3,0,1] row_mask:0xf bank_mask:0xf
	s_nop 1
	v_add_f32_dpp v224, v224, v224 row_ror:4 row_mask:0xf bank_mask:0xf
	s_nop 1
	v_add_f32_dpp v224, v224, v224 row_ror:8 row_mask:0xf bank_mask:0xf
	s_nop 1
	v_readlane_b32 s20, v224, 0
	v_readlane_b32 s21, v224, 16
	v_readlane_b32 s22, v224, 32
	v_readlane_b32 s23, v224, 48
	s_nop 1
	v_mov_b32_e32 v225, s20
	v_add_f32_e32 v225, s21, v225
	v_add_f32_e32 v225, s22, v225
	v_add_f32_e32 v225, s23, v225
	v_mov_b32_e32 v226, 0x358637bd
	v_fmac_f32_e32 v226, 0x3a800000, v225
	v_rsq_f32_e32 v226, v226
	s_nop 0
	v_mul_f32_e32 v208, v96, v226
	v_mul_f32_e32 v209, v97, v226
	v_mul_f32_e32 v210, v98, v226
	v_mul_f32_e32 v211, v99, v226
	v_mul_f32_e32 v212, v100, v226
	v_mul_f32_e32 v213, v101, v226
	v_mul_f32_e32 v214, v102, v226
	v_mul_f32_e32 v215, v103, v226
	v_mul_f32_e32 v216, v104, v226
	v_mul_f32_e32 v217, v105, v226
	v_mul_f32_e32 v218, v106, v226
	v_mul_f32_e32 v219, v107, v226
	v_mul_f32_e32 v220, v108, v226
	v_mul_f32_e32 v221, v109, v226
	v_mul_f32_e32 v222, v110, v226
	v_mul_f32_e32 v223, v111, v226
	v_mul_f32_e32 v208, v208, v56
	v_mul_f32_e32 v209, v209, v57
	v_mul_f32_e32 v210, v210, v58
	v_mul_f32_e32 v211, v211, v59
	v_mul_f32_e32 v212, v212, v60
	v_mul_f32_e32 v213, v213, v61
	v_mul_f32_e32 v214, v214, v62
	v_mul_f32_e32 v215, v215, v63
	v_mul_f32_e32 v216, v216, v64
	v_mul_f32_e32 v217, v217, v65
	v_mul_f32_e32 v218, v218, v66
	v_mul_f32_e32 v219, v219, v67
	v_mul_f32_e32 v220, v220, v68
	v_mul_f32_e32 v221, v221, v69
	v_mul_f32_e32 v222, v222, v70
	v_mul_f32_e32 v223, v223, v71
	v_cvt_pk_bf16_f32 v112, v208, v209
	v_cvt_pk_bf16_f32 v113, v210, v211
	v_cvt_pk_bf16_f32 v114, v212, v213
	v_cvt_pk_bf16_f32 v115, v214, v215
	v_cvt_pk_bf16_f32 v116, v216, v217
	v_cvt_pk_bf16_f32 v117, v218, v219
	v_cvt_pk_bf16_f32 v118, v220, v221
	v_cvt_pk_bf16_f32 v119, v222, v223
	global_store_dwordx4 v2, v[112:115], s[14:15]
	global_store_dwordx4 v2, v[116:119], s[14:15] offset:1024
	s_add_u32 s14, s14, 0x800
	s_addc_u32 s15, s15, 0
	global_load_dwordx4 v[96:99], v1, s[6:7] offset:0
	global_load_dwordx4 v[100:103], v1, s[6:7] offset:16
	global_load_dwordx4 v[104:107], v1, s[6:7] offset:2048
	global_load_dwordx4 v[108:111], v1, s[6:7] offset:2064
	global_load_dwordx4 v[112:115], v2, s[10:11]
	global_load_dwordx4 v[116:119], v2, s[10:11] offset:1024
	s_add_u32 s6, s6, 0x1000
	s_addc_u32 s7, s7, 0
	s_add_u32 s10, s10, 0x800
	s_addc_u32 s11, s11, 0
	s_waitcnt vmcnt(16)
; DI unsigned pk_bf16(float a, float b) { f32x2_t v = {a, b}; bf16x2_t r = __builtin_convertvector(v, bf16x2_t); return __builtin_bit_cast(unsigned, r); }
; DI void row_phase(const bf16_t* msrc, const float* xsrc, float* xdst, const float* g_post, const float* g_next, bf16_t* hdst, const int gw) {
;     ...
;                 for (int j = 0; j < 4; ++j) { const u32x2 mw = *(const u32x2*)(msrc + (size_t)(rowb + r) * DM + lane * 4 + 256 * j);
;                     mv[r][j] = (f32x4){__uint_as_float(mw[0] << 16), __uint_as_float(mw[0] & 0xffff0000u), __uint_as_float(mw[1] << 16), __uint_as_float(mw[1] & 0xffff0000u)}; }
;             float ss[RB];
; #pragma unroll
;             for (int r = 0; r < RB; ++r) { ss[r] = 0.f;
; #pragma unroll
;                 for (int j = 0; j < 4; ++j) ss[r] += mv[r][j][0] * mv[r][j][0] + mv[r][j][1] * mv[r][j][1] + mv[r][j][2] * mv[r][j][2] + mv[r][j][3] * mv[r][j][3]; }
; #pragma unroll
;             for (int o = 32; o >= 1; o >>= 1)
; #pragma unroll
;                 for (int r = 0; r < RB; ++r) ss[r] += shx(ss[r], o);
; #pragma unroll
;             for (int j = 0; j < 4; ++j) { const f32x4 g = *(const f32x4*)(g_post + lane * 4 + 256 * j);
; #pragma unroll
;                 for (int r = 0; r < RB; ++r) { const float r1 = rsqrtf(ss[r] * (1.f / DM) + EPS); xv[r][j] = xv[r][j] + mv[r][j] * r1 * g; *(f32x4*)(xdst + (size_t)(rowb + r) * DM + lane * 4 + 256 * j) = xv[r][j]; } }
;         }
;         if (hdst) {
;             float ss[RB];
; #pragma unroll
;             for (int r = 0; r < RB; ++r) { ss[r] = 0.f;
; #pragma unroll
;                 for (int j = 0; j < 4; ++j) ss[r] += xv[r][j][0] * xv[r][j][0] + xv[r][j][1] * xv[r][j][1] + xv[r][j][2] * xv[r][j][2] + xv[r][j][3] * xv[r][j][3]; }
; #pragma unroll
;             for (int o = 32; o >= 1; o >>= 1)
; #pragma unroll
;                 for (int r = 0; r < RB; ++r) ss[r] += shx(ss[r], o);
; #pragma unroll
;             for (int j = 0; j < 4; ++j) { const f32x4 g = *(const f32x4*)(g_next + lane * 4 + 256 * j);
; #pragma unroll
;                 for (int r = 0; r < RB; ++r) { const float r2 = rsqrtf(ss[r] * (1.f / DM) + EPS); const f32x4 hv = xv[r][j] * r2 * g;
;                     u32x2 o; o[0] = pk_bf16(hv[0], hv[1]); o[1] = pk_bf16(hv[2], hv[3]); *(u32x2*)(hdst + (size_t)(rowb + r) * DM + lane * 4 + 256 * j) = o; } }
	v_lshlrev_b32_e32 v208, 16, v144
	v_and_b32_e32 v209, 0xffff0000, v144
	v_lshlrev_b32_e32 v210, 16, v145
	v_and_b32_e32 v211, 0xffff0000, v145
	v_lshlrev_b32_e32 v212, 16, v146
	v_and_b32_e32 v213, 0xffff0000, v146
	v_lshlrev_b32_e32 v214, 16, v147
	v_and_b32_e32 v215, 0xffff0000, v147
	v_lshlrev_b32_e32 v216, 16, v148
	v_and_b32_e32 v217, 0xffff0000, v148
	v_lshlrev_b32_e32 v218, 16, v149
	v_and_b32_e32 v219, 0xffff0000, v149
	v_lshlrev_b32_e32 v220, 16, v150
	v_and_b32_e32 v221, 0xffff0000, v150
	v_lshlrev_b32_e32 v222, 16, v151
	v_and_b32_e32 v223, 0xffff0000, v151
	v_mul_f32_e32 v224, v208, v208
	v_fmac_f32_e32 v224, v209, v209
	v_fmac_f32_e32 v224, v210, v210
	v_fmac_f32_e32 v224, v211, v211
	v_fmac_f32_e32 v224, v212, v212
	v_fmac_f32_e32 v224, v213, v213
	v_fmac_f32_e32 v224, v214, v214
	v_fmac_f32_e32 v224, v215, v215
	v_fmac_f32_e32 v224, v216, v216
	v_fmac_f32_e32 v224, v217, v217
	v_fmac_f32_e32 v224, v218, v218
	v_fmac_f32_e32 v224, v219, v219
	v_fmac_f32_e32 v224, v220, v220
	v_fmac_f32_e32 v224, v221, v221
	v_fmac_f32_e32 v224, v222, v222
	v_fmac_f32_e32 v224, v223, v223
	s_nop 1
	v_add_f32_dpp v224, v224, v224 quad_perm:[1,0,3,2] row_mask:0xf bank_mask:0xf
	s_nop 1
	v_add_f32_dpp v224, v224, v224 quad_perm:[2,3,0,1] row_mask:0xf bank_mask:0xf
	s_nop 1
	v_add_f32_dpp v224, v224, v224 row_ror:4 row_mask:0xf bank_mask:0xf
	s_nop 1
	v_add_f32_dpp v224, v224, v224 row_ror:8 row_mask:0xf bank_mask:0xf
	s_nop 1
	v_readlane_b32 s20, v224, 0
	v_readlane_b32 s21, v224, 16
	v_readlane_b32 s22, v224, 32
	v_readlane_b32 s23, v224, 48
	s_nop 1
	v_mov_b32_e32 v225, s20
	v_add_f32_e32 v225, s21, v225
	v_add_f32_e32 v225, s22, v225
	v_add_f32_e32 v225, s23, v225
	v_mov_b32_e32 v226, 0x358637bd
	v_fmac_f32_e32 v226, 0x3a800000, v225
	v_rsq_f32_e32 v226, v226
	s_nop 0
	v_mul_f32_e32 v208, v208, v226
	v_mul_f32_e32 v209, v209, v226
	v_mul_f32_e32 v210, v210, v226
	v_mul_f32_e32 v211, v211, v226
	v_mul_f32_e32 v212, v212, v226
	v_mul_f32_e32 v213, v213, v226
	v_mul_f32_e32 v214, v214, v226
	v_mul_f32_e32 v215, v215, v226
	v_mul_f32_e32 v216, v216, v226
	v_mul_f32_e32 v217, v217, v226
	v_mul_f32_e32 v218, v218, v226
	v_mul_f32_e32 v219, v219, v226
	v_mul_f32_e32 v220, v220, v226
	v_mul_f32_e32 v221, v221, v226
	v_mul_f32_e32 v222, v222, v226
	v_mul_f32_e32 v223, v223, v226
	v_fmac_f32_e32 v128, v208, v40
	v_fmac_f32_e32 v129, v209, v41
	v_fmac_f32_e32 v130, v210, v42
	v_fmac_f32_e32 v131, v211, v43
	v_fmac_f32_e32 v132, v212, v44
	v_fmac_f32_e32 v133, v213, v45
	v_fmac_f32_e32 v134, v214, v46
	v_fmac_f32_e32 v135, v215, v47
	v_fmac_f32_e32 v136, v216, v48
	v_fmac_f32_e32 v137, v217, v49
	v_fmac_f32_e32 v138, v218, v50
	v_fmac_f32_e32 v139, v219, v51
	v_fmac_f32_e32 v140, v220, v52
	v_fmac_f32_e32 v141, v221, v53
	v_fmac_f32_e32 v142, v222, v54
	v_fmac_f32_e32 v143, v223, v55
	v_mul_f32_e32 v224, v128, v128
	v_fmac_f32_e32 v224, v129, v129
	v_fmac_f32_e32 v224, v130, v130
	v_fmac_f32_e32 v224, v131, v131
	v_fmac_f32_e32 v224, v132, v132
	v_fmac_f32_e32 v224, v133, v133
	v_fmac_f32_e32 v224, v134, v134
	v_fmac_f32_e32 v224, v135, v135
	v_fmac_f32_e32 v224, v136, v136
	v_fmac_f32_e32 v224, v137, v137
	v_fmac_f32_e32 v224, v138, v138
	v_fmac_f32_e32 v224, v139, v139
	v_fmac_f32_e32 v224, v140, v140
	v_fmac_f32_e32 v224, v141, v141
	v_fmac_f32_e32 v224, v142, v142
	v_fmac_f32_e32 v224, v143, v143
	s_nop 1
	v_add_f32_dpp v224, v224, v224 quad_perm:[1,0,3,2] row_mask:0xf bank_mask:0xf
	s_nop 1
	v_add_f32_dpp v224, v224, v224 quad_perm:[2,3,0,1] row_mask:0xf bank_mask:0xf
	s_nop 1
	v_add_f32_dpp v224, v224, v224 row_ror:4 row_mask:0xf bank_mask:0xf
	s_nop 1
	v_add_f32_dpp v224, v224, v224 row_ror:8 row_mask:0xf bank_mask:0xf
	s_nop 1
	v_readlane_b32 s20, v224, 0
	v_readlane_b32 s21, v224, 16
	v_readlane_b32 s22, v224, 32
	v_readlane_b32 s23, v224, 48
	s_nop 1
	v_mov_b32_e32 v225, s20
	v_add_f32_e32 v225, s21, v225
	v_add_f32_e32 v225, s22, v225
	v_add_f32_e32 v225, s23, v225
	v_mov_b32_e32 v226, 0x358637bd
	v_fmac_f32_e32 v226, 0x3a800000, v225
	v_rsq_f32_e32 v226, v226
	s_nop 0
	v_mul_f32_e32 v208, v128, v226
	v_mul_f32_e32 v209, v129, v226
	v_mul_f32_e32 v210, v130, v226
	v_mul_f32_e32 v211, v131, v226
	v_mul_f32_e32 v212, v132, v226
	v_mul_f32_e32 v213, v133, v226
	v_mul_f32_e32 v214, v134, v226
	v_mul_f32_e32 v215, v135, v226
	v_mul_f32_e32 v216, v136, v226
	v_mul_f32_e32 v217, v137, v226
	v_mul_f32_e32 v218, v138, v226
	v_mul_f32_e32 v219, v139, v226
	v_mul_f32_e32 v220, v140, v226
	v_mul_f32_e32 v221, v141, v226
	v_mul_f32_e32 v222, v142, v226
	v_mul_f32_e32 v223, v143, v226
	v_mul_f32_e32 v208, v208, v56
	v_mul_f32_e32 v209, v209, v57
	v_mul_f32_e32 v210, v210, v58
	v_mul_f32_e32 v211, v211, v59
	v_mul_f32_e32 v212, v212, v60
	v_mul_f32_e32 v213, v213, v61
	v_mul_f32_e32 v214, v214, v62
	v_mul_f32_e32 v215, v215, v63
	v_mul_f32_e32 v216, v216, v64
	v_mul_f32_e32 v217, v217, v65
	v_mul_f32_e32 v218, v218, v66
	v_mul_f32_e32 v219, v219, v67
	v_mul_f32_e32 v220, v220, v68
	v_mul_f32_e32 v221, v221, v69
	v_mul_f32_e32 v222, v222, v70
	v_mul_f32_e32 v223, v223, v71
	v_cvt_pk_bf16_f32 v144, v208, v209
	v_cvt_pk_bf16_f32 v145, v210, v211
	v_cvt_pk_bf16_f32 v146, v212, v213
	v_cvt_pk_bf16_f32 v147, v214, v215
	v_cvt_pk_bf16_f32 v148, v216, v217
	v_cvt_pk_bf16_f32 v149, v218, v219
	v_cvt_pk_bf16_f32 v150, v220, v221
	v_cvt_pk_bf16_f32 v151, v222, v223
	global_store_dwordx4 v2, v[144:147], s[14:15]
	global_store_dwordx4 v2, v[148:151], s[14:15] offset:1024
	s_add_u32 s14, s14, 0x800
	s_addc_u32 s15, s15, 0
	global_load_dwordx4 v[128:131], v1, s[6:7] offset:0
	global_load_dwordx4 v[132:135], v1, s[6:7] offset:16
	global_load_dwordx4 v[136:139], v1, s[6:7] offset:2048
	global_load_dwordx4 v[140:143], v1, s[6:7] offset:2064
	global_load_dwordx4 v[144:147], v2, s[10:11]
	global_load_dwordx4 v[148:151], v2, s[10:11] offset:1024
	s_add_u32 s6, s6, 0x1000
	s_addc_u32 s7, s7, 0
	s_add_u32 s10, s10, 0x800
	s_addc_u32 s11, s11, 0
	s_waitcnt vmcnt(16)
; DI unsigned pk_bf16(float a, float b) { f32x2_t v = {a, b}; bf16x2_t r = __builtin_convertvector(v, bf16x2_t); return __builtin_bit_cast(unsigned, r); }
; DI void row_phase(const bf16_t* msrc, const float* xsrc, float* xdst, const float* g_post, const float* g_next, bf16_t* hdst, const int gw) {
;     ...
;                 for (int j = 0; j < 4; ++j) { const u32x2 mw = *(const u32x2*)(msrc + (size_t)(rowb + r) * DM + lane * 4 + 256 * j);
;                     mv[r][j] = (f32x4){__uint_as_float(mw[0] << 16), __uint_as_float(mw[0] & 0xffff0000u), __uint_as_float(mw[1] << 16), __uint_as_float(mw[1] & 0xffff0000u)}; }
;             float ss[RB];
; #pragma unroll
;             for (int r = 0; r < RB; ++r) { ss[r] = 0.f;
; #pragma unroll
;                 for (int j = 0; j < 4; ++j) ss[r] += mv[r][j][0] * mv[r][j][0] + mv[r][j][1] * mv[r][j][1] + mv[r][j][2] * mv[r][j][2] + mv[r][j][3] * mv[r][j][3]; }
; #pragma unroll
;             for (int o = 32; o >= 1; o >>= 1)
; #pragma unroll
;                 for (int r = 0; r < RB; ++r) ss[r] += shx(ss[r], o);
; #pragma unroll
;             for (int j = 0; j < 4; ++j) { const f32x4 g = *(const f32x4*)(g_post + lane * 4 + 256 * j);
; #pragma unroll
;                 for (int r = 0; r < RB; ++r) { const float r1 = rsqrtf(ss[r] * (1.f / DM) + EPS); xv[r][j] = xv[r][j] + mv[r][j] * r1 * g; *(f32x4*)(xdst + (size_t)(rowb + r) * DM + lane * 4 + 256 * j) = xv[r][j]; } }
;         }
;         if (hdst) {
;             float ss[RB];
; #pragma unroll
;             for (int r = 0; r < RB; ++r) { ss[r] = 0.f;
; #pragma unroll
;                 for (int j = 0; j < 4; ++j) ss[r] += xv[r][j][0] * xv[r][j][0] + xv[r][j][1] * xv[r][j][1] + xv[r][j][2] * xv[r][j][2] + xv[r][j][3] * xv[r][j][3]; }
; #pragma unroll
;             for (int o = 32; o >= 1; o >>= 1)
; #pragma unroll
;                 for (int r = 0; r < RB; ++r) ss[r] += shx(ss[r], o);
; #pragma unroll
;             for (int j = 0; j < 4; ++j) { const f32x4 g = *(const f32x4*)(g_next + lane * 4 + 256 * j);
; #pragma unroll
;                 for (int r = 0; r < RB; ++r) { const float r2 = rsqrtf(ss[r] * (1.f / DM) + EPS); const f32x4 hv = xv[r][j] * r2 * g;
;                     u32x2 o; o[0] = pk_bf16(hv[0], hv[1]); o[1] = pk_bf16(hv[2], hv[3]); *(u32x2*)(hdst + (size_t)(rowb + r) * DM + lane * 4 + 256 * j) = o; } }
	v_lshlrev_b32_e32 v208, 16, v176
	v_and_b32_e32 v209, 0xffff0000, v176
	v_lshlrev_b32_e32 v210, 16, v177
	v_and_b32_e32 v211, 0xffff0000, v177
	v_lshlrev_b32_e32 v212, 16, v178
	v_and_b32_e32 v213, 0xffff0000, v178
	v_lshlrev_b32_e32 v214, 16, v179
	v_and_b32_e32 v215, 0xffff0000, v179
	v_lshlrev_b32_e32 v216, 16, v180
	v_and_b32_e32 v217, 0xffff0000, v180
	v_lshlrev_b32_e32 v218, 16, v181
	v_and_b32_e32 v219, 0xffff0000, v181
	v_lshlrev_b32_e32 v220, 16, v182
	v_and_b32_e32 v221, 0xffff0000, v182
	v_lshlrev_b32_e32 v222, 16, v183
	v_and_b32_e32 v223, 0xffff0000, v183
	v_mul_f32_e32 v224, v208, v208
	v_fmac_f32_e32 v224, v209, v209
	v_fmac_f32_e32 v224, v210, v210
	v_fmac_f32_e32 v224, v211, v211
	v_fmac_f32_e32 v224, v212, v212
	v_fmac_f32_e32 v224, v213, v213
	v_fmac_f32_e32 v224, v214, v214
	v_fmac_f32_e32 v224, v215, v215
	v_fmac_f32_e32 v224, v216, v216
	v_fmac_f32_e32 v224, v217, v217
	v_fmac_f32_e32 v224, v218, v218
	v_fmac_f32_e32 v224, v219, v219
	v_fmac_f32_e32 v224, v220, v220
	v_fmac_f32_e32 v224, v221, v221
	v_fmac_f32_e32 v224, v222, v222
	v_fmac_f32_e32 v224, v223, v223
	s_nop 1
	v_add_f32_dpp v224, v224, v224 quad_perm:[1,0,3,2] row_mask:0xf bank_mask:0xf
	s_nop 1
	v_add_f32_dpp v224, v224, v224 quad_perm:[2,3,0,1] row_mask:0xf bank_mask:0xf
	s_nop 1
	v_add_f32_dpp v224, v224, v224 row_ror:4 row_mask:0xf bank_mask:0xf
	s_nop 1
	v_add_f32_dpp v224, v224, v224 row_ror:8 row_mask:0xf bank_mask:0xf
	s_nop 1
	v_readlane_b32 s20, v224, 0
	v_readlane_b32 s21, v224, 16
	v_readlane_b32 s22, v224, 32
	v_readlane_b32 s23, v224, 48
	s_nop 1
	v_mov_b32_e32 v225, s20
	v_add_f32_e32 v225, s21, v225
	v_add_f32_e32 v225, s22, v225
	v_add_f32_e32 v225, s23, v225
	v_mov_b32_e32 v226, 0x358637bd
	v_fmac_f32_e32 v226, 0x3a800000, v225
	v_rsq_f32_e32 v226, v226
	s_nop 0
	v_mul_f32_e32 v208, v208, v226
	v_mul_f32_e32 v209, v209, v226
	v_mul_f32_e32 v210, v210, v226
	v_mul_f32_e32 v211, v211, v226
	v_mul_f32_e32 v212, v212, v226
	v_mul_f32_e32 v213, v213, v226
	v_mul_f32_e32 v214, v214, v226
	v_mul_f32_e32 v215, v215, v226
	v_mul_f32_e32 v216, v216, v226
	v_mul_f32_e32 v217, v217, v226
	v_mul_f32_e32 v218, v218, v226
	v_mul_f32_e32 v219, v219, v226
	v_mul_f32_e32 v220, v220, v226
	v_mul_f32_e32 v221, v221, v226
	v_mul_f32_e32 v222, v222, v226
	v_mul_f32_e32 v223, v223, v226
	v_fmac_f32_e32 v160, v208, v40
	v_fmac_f32_e32 v161, v209, v41
	v_fmac_f32_e32 v162, v210, v42
	v_fmac_f32_e32 v163, v211, v43
	v_fmac_f32_e32 v164, v212, v44
	v_fmac_f32_e32 v165, v213, v45
	v_fmac_f32_e32 v166, v214, v46
	v_fmac_f32_e32 v167, v215, v47
	v_fmac_f32_e32 v168, v216, v48
	v_fmac_f32_e32 v169, v217, v49
	v_fmac_f32_e32 v170, v218, v50
	v_fmac_f32_e32 v171, v219, v51
	v_fmac_f32_e32 v172, v220, v52
	v_fmac_f32_e32 v173, v221, v53
	v_fmac_f32_e32 v174, v222, v54
	v_fmac_f32_e32 v175, v223, v55
	v_mul_f32_e32 v224, v160, v160
	v_fmac_f32_e32 v224, v161, v161
	v_fmac_f32_e32 v224, v162, v162
	v_fmac_f32_e32 v224, v163, v163
	v_fmac_f32_e32 v224, v164, v164
	v_fmac_f32_e32 v224, v165, v165
	v_fmac_f32_e32 v224, v166, v166
	v_fmac_f32_e32 v224, v167, v167
	v_fmac_f32_e32 v224, v168, v168
	v_fmac_f32_e32 v224, v169, v169
	v_fmac_f32_e32 v224, v170, v170
	v_fmac_f32_e32 v224, v171, v171
	v_fmac_f32_e32 v224, v172, v172
	v_fmac_f32_e32 v224, v173, v173
	v_fmac_f32_e32 v224, v174, v174
	v_fmac_f32_e32 v224, v175, v175
	s_nop 1
	v_add_f32_dpp v224, v224, v224 quad_perm:[1,0,3,2] row_mask:0xf bank_mask:0xf
	s_nop 1
	v_add_f32_dpp v224, v224, v224 quad_perm:[2,3,0,1] row_mask:0xf bank_mask:0xf
	s_nop 1
	v_add_f32_dpp v224, v224, v224 row_ror:4 row_mask:0xf bank_mask:0xf
	s_nop 1
	v_add_f32_dpp v224, v224, v224 row_ror:8 row_mask:0xf bank_mask:0xf
	s_nop 1
	v_readlane_b32 s20, v224, 0
	v_readlane_b32 s21, v224, 16
	v_readlane_b32 s22, v224, 32
	v_readlane_b32 s23, v224, 48
	s_nop 1
	v_mov_b32_e32 v225, s20
	v_add_f32_e32 v225, s21, v225
	v_add_f32_e32 v225, s22, v225
	v_add_f32_e32 v225, s23, v225
	v_mov_b32_e32 v226, 0x358637bd
	v_fmac_f32_e32 v226, 0x3a800000, v225
	v_rsq_f32_e32 v226, v226
	s_nop 0
	v_mul_f32_e32 v208, v160, v226
	v_mul_f32_e32 v209, v161, v226
	v_mul_f32_e32 v210, v162, v226
	v_mul_f32_e32 v211, v163, v226
	v_mul_f32_e32 v212, v164, v226
	v_mul_f32_e32 v213, v165, v226
	v_mul_f32_e32 v214, v166, v226
	v_mul_f32_e32 v215, v167, v226
	v_mul_f32_e32 v216, v168, v226
	v_mul_f32_e32 v217, v169, v226
	v_mul_f32_e32 v218, v170, v226
	v_mul_f32_e32 v219, v171, v226
	v_mul_f32_e32 v220, v172, v226
	v_mul_f32_e32 v221, v173, v226
	v_mul_f32_e32 v222, v174, v226
	v_mul_f32_e32 v223, v175, v226
	v_mul_f32_e32 v208, v208, v56
	v_mul_f32_e32 v209, v209, v57
	v_mul_f32_e32 v210, v210, v58
	v_mul_f32_e32 v211, v211, v59
	v_mul_f32_e32 v212, v212, v60
	v_mul_f32_e32 v213, v213, v61
	v_mul_f32_e32 v214, v214, v62
	v_mul_f32_e32 v215, v215, v63
	v_mul_f32_e32 v216, v216, v64
	v_mul_f32_e32 v217, v217, v65
	v_mul_f32_e32 v218, v218, v66
	v_mul_f32_e32 v219, v219, v67
	v_mul_f32_e32 v220, v220, v68
	v_mul_f32_e32 v221, v221, v69
	v_mul_f32_e32 v222, v222, v70
	v_mul_f32_e32 v223, v223, v71
	v_cvt_pk_bf16_f32 v176, v208, v209
	v_cvt_pk_bf16_f32 v177, v210, v211
	v_cvt_pk_bf16_f32 v178, v212, v213
	v_cvt_pk_bf16_f32 v179, v214, v215
	v_cvt_pk_bf16_f32 v180, v216, v217
	v_cvt_pk_bf16_f32 v181, v218, v219
	v_cvt_pk_bf16_f32 v182, v220, v221
	v_cvt_pk_bf16_f32 v183, v222, v223
	global_store_dwordx4 v2, v[176:179], s[14:15]
	global_store_dwordx4 v2, v[180:183], s[14:15] offset:1024
	s_add_u32 s14, s14, 0x800
	s_addc_u32 s15, s15, 0
	s_waitcnt vmcnt(10)
; DI unsigned pk_bf16(float a, float b) { f32x2_t v = {a, b}; bf16x2_t r = __builtin_convertvector(v, bf16x2_t); return __builtin_bit_cast(unsigned, r); }
; DI void row_phase(const bf16_t* msrc, const float* xsrc, float* xdst, const float* g_post, const float* g_next, bf16_t* hdst, const int gw) {
;     ...
;                 for (int j = 0; j < 4; ++j) { const u32x2 mw = *(const u32x2*)(msrc + (size_t)(rowb + r) * DM + lane * 4 + 256 * j);
;                     mv[r][j] = (f32x4){__uint_as_float(mw[0] << 16), __uint_as_float(mw[0] & 0xffff0000u), __uint_as_float(mw[1] << 16), __uint_as_float(mw[1] & 0xffff0000u)}; }
;             float ss[RB];
; #pragma unroll
;             for (int r = 0; r < RB; ++r) { ss[r] = 0.f;
; #pragma unroll
;                 for (int j = 0; j < 4; ++j) ss[r] += mv[r][j][0] * mv[r][j][0] + mv[r][j][1] * mv[r][j][1] + mv[r][j][2] * mv[r][j][2] + mv[r][j][3] * mv[r][j][3]; }
; #pragma unroll
;             for (int o = 32; o >= 1; o >>= 1)
; #pragma unroll
;                 for (int r = 0; r < RB; ++r) ss[r] += shx(ss[r], o);
; #pragma unroll
;             for (int j = 0; j < 4; ++j) { const f32x4 g = *(const f32x4*)(g_post + lane * 4 + 256 * j);
; #pragma unroll
;                 for (int r = 0; r < RB; ++r) { const float r1 = rsqrtf(ss[r] * (1.f / DM) + EPS); xv[r][j] = xv[r][j] + mv[r][j] * r1 * g; *(f32x4*)(xdst + (size_t)(rowb + r) * DM + lane * 4 + 256 * j) = xv[r][j]; } }
;         }
;         if (hdst) {
;             float ss[RB];
; #pragma unroll
;             for (int r = 0; r < RB; ++r) { ss[r] = 0.f;
; #pragma unroll
;                 for (int j = 0; j < 4; ++j) ss[r] += xv[r][j][0] * xv[r][j][0] + xv[r][j][1] * xv[r][j][1] + xv[r][j][2] * xv[r][j][2] + xv[r][j][3] * xv[r][j][3]; }
; #pragma unroll
;             for (int o = 32; o >= 1; o >>= 1)
; #pragma unroll
;                 for (int r = 0; r < RB; ++r) ss[r] += shx(ss[r], o);
; #pragma unroll
;             for (int j = 0; j < 4; ++j) { const f32x4 g = *(const f32x4*)(g_next + lane * 4 + 256 * j);
; #pragma unroll
;                 for (int r = 0; r < RB; ++r) { const float r2 = rsqrtf(ss[r] * (1.f / DM) + EPS); const f32x4 hv = xv[r][j] * r2 * g;
;                     u32x2 o; o[0] = pk_bf16(hv[0], hv[1]); o[1] = pk_bf16(hv[2], hv[3]); *(u32x2*)(hdst + (size_t)(rowb + r) * DM + lane * 4 + 256 * j) = o; } }
	v_lshlrev_b32_e32 v208, 16, v112
	v_and_b32_e32 v209, 0xffff0000, v112
	v_lshlrev_b32_e32 v210, 16, v113
	v_and_b32_e32 v211, 0xffff0000, v113
	v_lshlrev_b32_e32 v212, 16, v114
	v_and_b32_e32 v213, 0xffff0000, v114
	v_lshlrev_b32_e32 v214, 16, v115
	v_and_b32_e32 v215, 0xffff0000, v115
	v_lshlrev_b32_e32 v216, 16, v116
	v_and_b32_e32 v217, 0xffff0000, v116
	v_lshlrev_b32_e32 v218, 16, v117
	v_and_b32_e32 v219, 0xffff0000, v117
	v_lshlrev_b32_e32 v220, 16, v118
	v_and_b32_e32 v221, 0xffff0000, v118
	v_lshlrev_b32_e32 v222, 16, v119
	v_and_b32_e32 v223, 0xffff0000, v119
	v_mul_f32_e32 v224, v208, v208
	v_fmac_f32_e32 v224, v209, v209
	v_fmac_f32_e32 v224, v210, v210
	v_fmac_f32_e32 v224, v211, v211
	v_fmac_f32_e32 v224, v212, v212
	v_fmac_f32_e32 v224, v213, v213
	v_fmac_f32_e32 v224, v214, v214
	v_fmac_f32_e32 v224, v215, v215
	v_fmac_f32_e32 v224, v216, v216
	v_fmac_f32_e32 v224, v217, v217
	v_fmac_f32_e32 v224, v218, v218
	v_fmac_f32_e32 v224, v219, v219
	v_fmac_f32_e32 v224, v220, v220
	v_fmac_f32_e32 v224, v221, v221
	v_fmac_f32_e32 v224, v222, v222
	v_fmac_f32_e32 v224, v223, v223
	s_nop 1
	v_add_f32_dpp v224, v224, v224 quad_perm:[1,0,3,2] row_mask:0xf bank_mask:0xf
	s_nop 1
	v_add_f32_dpp v224, v224, v224 quad_perm:[2,3,0,1] row_mask:0xf bank_mask:0xf
	s_nop 1
	v_add_f32_dpp v224, v224, v224 row_ror:4 row_mask:0xf bank_mask:0xf
	s_nop 1
	v_add_f32_dpp v224, v224, v224 row_ror:8 row_mask:0xf bank_mask:0xf
	s_nop 1
	v_readlane_b32 s20, v224, 0
	v_readlane_b32 s21, v224, 16
	v_readlane_b32 s22, v224, 32
	v_readlane_b32 s23, v224, 48
	s_nop 1
	v_mov_b32_e32 v225, s20
	v_add_f32_e32 v225, s21, v225
	v_add_f32_e32 v225, s22, v225
	v_add_f32_e32 v225, s23, v225
	v_mov_b32_e32 v226, 0x358637bd
	v_fmac_f32_e32 v226, 0x3a800000, v225
	v_rsq_f32_e32 v226, v226
	s_nop 0
	v_mul_f32_e32 v208, v208, v226
	v_mul_f32_e32 v209, v209, v226
	v_mul_f32_e32 v210, v210, v226
	v_mul_f32_e32 v211, v211, v226
	v_mul_f32_e32 v212, v212, v226
	v_mul_f32_e32 v213, v213, v226
	v_mul_f32_e32 v214, v214, v226
	v_mul_f32_e32 v215, v215, v226
	v_mul_f32_e32 v216, v216, v226
	v_mul_f32_e32 v217, v217, v226
	v_mul_f32_e32 v218, v218, v226
	v_mul_f32_e32 v219, v219, v226
	v_mul_f32_e32 v220, v220, v226
	v_mul_f32_e32 v221, v221, v226
	v_mul_f32_e32 v222, v222, v226
	v_mul_f32_e32 v223, v223, v226
	v_fmac_f32_e32 v96, v208, v40
	v_fmac_f32_e32 v97, v209, v41
	v_fmac_f32_e32 v98, v210, v42
	v_fmac_f32_e32 v99, v211, v43
	v_fmac_f32_e32 v100, v212, v44
	v_fmac_f32_e32 v101, v213, v45
	v_fmac_f32_e32 v102, v214, v46
	v_fmac_f32_e32 v103, v215, v47
	v_fmac_f32_e32 v104, v216, v48
	v_fmac_f32_e32 v105, v217, v49
	v_fmac_f32_e32 v106, v218, v50
	v_fmac_f32_e32 v107, v219, v51
	v_fmac_f32_e32 v108, v220, v52
	v_fmac_f32_e32 v109, v221, v53
	v_fmac_f32_e32 v110, v222, v54
	v_fmac_f32_e32 v111, v223, v55
	v_mul_f32_e32 v224, v96, v96
	v_fmac_f32_e32 v224, v97, v97
	v_fmac_f32_e32 v224, v98, v98
	v_fmac_f32_e32 v224, v99, v99
	v_fmac_f32_e32 v224, v100, v100
	v_fmac_f32_e32 v224, v101, v101
	v_fmac_f32_e32 v224, v102, v102
	v_fmac_f32_e32 v224, v103, v103
	v_fmac_f32_e32 v224, v104, v104
	v_fmac_f32_e32 v224, v105, v105
	v_fmac_f32_e32 v224, v106, v106
	v_fmac_f32_e32 v224, v107, v107
	v_fmac_f32_e32 v224, v108, v108
	v_fmac_f32_e32 v224, v109, v109
	v_fmac_f32_e32 v224, v110, v110
	v_fmac_f32_e32 v224, v111, v111
	s_nop 1
	v_add_f32_dpp v224, v224, v224 quad_perm:[1,0,3,2] row_mask:0xf bank_mask:0xf
	s_nop 1
	v_add_f32_dpp v224, v224, v224 quad_perm:[2,3,0,1] row_mask:0xf bank_mask:0xf
	s_nop 1
	v_add_f32_dpp v224, v224, v224 row_ror:4 row_mask:0xf bank_mask:0xf
	s_nop 1
	v_add_f32_dpp v224, v224, v224 row_ror:8 row_mask:0xf bank_mask:0xf
	s_nop 1
	v_readlane_b32 s20, v224, 0
	v_readlane_b32 s21, v224, 16
	v_readlane_b32 s22, v224, 32
	v_readlane_b32 s23, v224, 48
	s_nop 1
	v_mov_b32_e32 v225, s20
	v_add_f32_e32 v225, s21, v225
	v_add_f32_e32 v225, s22, v225
	v_add_f32_e32 v225, s23, v225
	v_mov_b32_e32 v226, 0x358637bd
	v_fmac_f32_e32 v226, 0x3a800000, v225
	v_rsq_f32_e32 v226, v226
	s_nop 0
	v_mul_f32_e32 v208, v96, v226
	v_mul_f32_e32 v209, v97, v226
	v_mul_f32_e32 v210, v98, v226
	v_mul_f32_e32 v211, v99, v226
	v_mul_f32_e32 v212, v100, v226
	v_mul_f32_e32 v213, v101, v226
	v_mul_f32_e32 v214, v102, v226
	v_mul_f32_e32 v215, v103, v226
	v_mul_f32_e32 v216, v104, v226
	v_mul_f32_e32 v217, v105, v226
	v_mul_f32_e32 v218, v106, v226
	v_mul_f32_e32 v219, v107, v226
	v_mul_f32_e32 v220, v108, v226
	v_mul_f32_e32 v221, v109, v226
	v_mul_f32_e32 v222, v110, v226
	v_mul_f32_e32 v223, v111, v226
	v_mul_f32_e32 v208, v208, v56
	v_mul_f32_e32 v209, v209, v57
	v_mul_f32_e32 v210, v210, v58
	v_mul_f32_e32 v211, v211, v59
	v_mul_f32_e32 v212, v212, v60
	v_mul_f32_e32 v213, v213, v61
	v_mul_f32_e32 v214, v214, v62
	v_mul_f32_e32 v215, v215, v63
	v_mul_f32_e32 v216, v216, v64
	v_mul_f32_e32 v217, v217, v65
	v_mul_f32_e32 v218, v218, v66
	v_mul_f32_e32 v219, v219, v67
	v_mul_f32_e32 v220, v220, v68
	v_mul_f32_e32 v221, v221, v69
	v_mul_f32_e32 v222, v222, v70
	v_mul_f32_e32 v223, v223, v71
	v_cvt_pk_bf16_f32 v112, v208, v209
	v_cvt_pk_bf16_f32 v113, v210, v211
	v_cvt_pk_bf16_f32 v114, v212, v213
	v_cvt_pk_bf16_f32 v115, v214, v215
	v_cvt_pk_bf16_f32 v116, v216, v217
	v_cvt_pk_bf16_f32 v117, v218, v219
	v_cvt_pk_bf16_f32 v118, v220, v221
	v_cvt_pk_bf16_f32 v119, v222, v223
	global_store_dwordx4 v2, v[112:115], s[14:15]
	global_store_dwordx4 v2, v[116:119], s[14:15] offset:1024
	s_add_u32 s14, s14, 0x800
	s_addc_u32 s15, s15, 0
	s_waitcnt vmcnt(4)
; DI unsigned pk_bf16(float a, float b) { f32x2_t v = {a, b}; bf16x2_t r = __builtin_convertvector(v, bf16x2_t); return __builtin_bit_cast(unsigned, r); }
; DI void row_phase(const bf16_t* msrc, const float* xsrc, float* xdst, const float* g_post, const float* g_next, bf16_t* hdst, const int gw) {
;     ...
;                 for (int j = 0; j < 4; ++j) { const u32x2 mw = *(const u32x2*)(msrc + (size_t)(rowb + r) * DM + lane * 4 + 256 * j);
;                     mv[r][j] = (f32x4){__uint_as_float(mw[0] << 16), __uint_as_float(mw[0] & 0xffff0000u), __uint_as_float(mw[1] << 16), __uint_as_float(mw[1] & 0xffff0000u)}; }
;             float ss[RB];
; #pragma unroll
;             for (int r = 0; r < RB; ++r) { ss[r] = 0.f;
; #pragma unroll
;                 for (int j = 0; j < 4; ++j) ss[r] += mv[r][j][0] * mv[r][j][0] + mv[r][j][1] * mv[r][j][1] + mv[r][j][2] * mv[r][j][2] + mv[r][j][3] * mv[r][j][3]; }
; #pragma unroll
;             for (int o = 32; o >= 1; o >>= 1)
; #pragma unroll
;                 for (int r = 0; r < RB; ++r) ss[r] += shx(ss[r], o);
; #pragma unroll
;             for (int j = 0; j < 4; ++j) { const f32x4 g = *(const f32x4*)(g_post + lane * 4 + 256 * j);
; #pragma unroll
;                 for (int r = 0; r < RB; ++r) { const float r1 = rsqrtf(ss[r] * (1.f / DM) + EPS); xv[r][j] = xv[r][j] + mv[r][j] * r1 * g; *(f32x4*)(xdst + (size_t)(rowb + r) * DM + lane * 4 + 256 * j) = xv[r][j]; } }
;         }
;         if (hdst) {
;             float ss[RB];
; #pragma unroll
;             for (int r = 0; r < RB; ++r) { ss[r] = 0.f;
; #pragma unroll
;                 for (int j = 0; j < 4; ++j) ss[r] += xv[r][j][0] * xv[r][j][0] + xv[r][j][1] * xv[r][j][1] + xv[r][j][2] * xv[r][j][2] + xv[r][j][3] * xv[r][j][3]; }
; #pragma unroll
;             for (int o = 32; o >= 1; o >>= 1)
; #pragma unroll
;                 for (int r = 0; r < RB; ++r) ss[r] += shx(ss[r], o);
; #pragma unroll
;             for (int j = 0; j < 4; ++j) { const f32x4 g = *(const f32x4*)(g_next + lane * 4 + 256 * j);
; #pragma unroll
;                 for (int r = 0; r < RB; ++r) { const float r2 = rsqrtf(ss[r] * (1.f / DM) + EPS); const f32x4 hv = xv[r][j] * r2 * g;
;                     u32x2 o; o[0] = pk_bf16(hv[0], hv[1]); o[1] = pk_bf16(hv[2], hv[3]); *(u32x2*)(hdst + (size_t)(rowb + r) * DM + lane * 4 + 256 * j) = o; } }
	v_lshlrev_b32_e32 v208, 16, v144
	v_and_b32_e32 v209, 0xffff0000, v144
	v_lshlrev_b32_e32 v210, 16, v145
	v_and_b32_e32 v211, 0xffff0000, v145
	v_lshlrev_b32_e32 v212, 16, v146
	v_and_b32_e32 v213, 0xffff0000, v146
	v_lshlrev_b32_e32 v214, 16, v147
	v_and_b32_e32 v215, 0xffff0000, v147
	v_lshlrev_b32_e32 v216, 16, v148
	v_and_b32_e32 v217, 0xffff0000, v148
	v_lshlrev_b32_e32 v218, 16, v149
	v_and_b32_e32 v219, 0xffff0000, v149
	v_lshlrev_b32_e32 v220, 16, v150
	v_and_b32_e32 v221, 0xffff0000, v150
	v_lshlrev_b32_e32 v222, 16, v151
	v_and_b32_e32 v223, 0xffff0000, v151
	v_mul_f32_e32 v224, v208, v208
	v_fmac_f32_e32 v224, v209, v209
	v_fmac_f32_e32 v224, v210, v210
	v_fmac_f32_e32 v224, v211, v211
	v_fmac_f32_e32 v224, v212, v212
	v_fmac_f32_e32 v224, v213, v213
	v_fmac_f32_e32 v224, v214, v214
	v_fmac_f32_e32 v224, v215, v215
	v_fmac_f32_e32 v224, v216, v216
	v_fmac_f32_e32 v224, v217, v217
	v_fmac_f32_e32 v224, v218, v218
	v_fmac_f32_e32 v224, v219, v219
	v_fmac_f32_e32 v224, v220, v220
	v_fmac_f32_e32 v224, v221, v221
	v_fmac_f32_e32 v224, v222, v222
	v_fmac_f32_e32 v224, v223, v223
	s_nop 1
	v_add_f32_dpp v224, v224, v224 quad_perm:[1,0,3,2] row_mask:0xf bank_mask:0xf
	s_nop 1
	v_add_f32_dpp v224, v224, v224 quad_perm:[2,3,0,1] row_mask:0xf bank_mask:0xf
	s_nop 1
	v_add_f32_dpp v224, v224, v224 row_ror:4 row_mask:0xf bank_mask:0xf
	s_nop 1
	v_add_f32_dpp v224, v224, v224 row_ror:8 row_mask:0xf bank_mask:0xf
	s_nop 1
	v_readlane_b32 s20, v224, 0
	v_readlane_b32 s21, v224, 16
	v_readlane_b32 s22, v224, 32
	v_readlane_b32 s23, v224, 48
	s_nop 1
	v_mov_b32_e32 v225, s20
	v_add_f32_e32 v225, s21, v225
	v_add_f32_e32 v225, s22, v225
	v_add_f32_e32 v225, s23, v225
	v_mov_b32_e32 v226, 0x358637bd
	v_fmac_f32_e32 v226, 0x3a800000, v225
	v_rsq_f32_e32 v226, v226
	s_nop 0
	v_mul_f32_e32 v208, v208, v226
	v_mul_f32_e32 v209, v209, v226
	v_mul_f32_e32 v210, v210, v226
	v_mul_f32_e32 v211, v211, v226
	v_mul_f32_e32 v212, v212, v226
	v_mul_f32_e32 v213, v213, v226
	v_mul_f32_e32 v214, v214, v226
	v_mul_f32_e32 v215, v215, v226
	v_mul_f32_e32 v216, v216, v226
	v_mul_f32_e32 v217, v217, v226
	v_mul_f32_e32 v218, v218, v226
	v_mul_f32_e32 v219, v219, v226
	v_mul_f32_e32 v220, v220, v226
	v_mul_f32_e32 v221, v221, v226
	v_mul_f32_e32 v222, v222, v226
	v_mul_f32_e32 v223, v223, v226
	v_fmac_f32_e32 v128, v208, v40
	v_fmac_f32_e32 v129, v209, v41
	v_fmac_f32_e32 v130, v210, v42
	v_fmac_f32_e32 v131, v211, v43
	v_fmac_f32_e32 v132, v212, v44
	v_fmac_f32_e32 v133, v213, v45
	v_fmac_f32_e32 v134, v214, v46
	v_fmac_f32_e32 v135, v215, v47
	v_fmac_f32_e32 v136, v216, v48
	v_fmac_f32_e32 v137, v217, v49
	v_fmac_f32_e32 v138, v218, v50
	v_fmac_f32_e32 v139, v219, v51
	v_fmac_f32_e32 v140, v220, v52
	v_fmac_f32_e32 v141, v221, v53
	v_fmac_f32_e32 v142, v222, v54
	v_fmac_f32_e32 v143, v223, v55
	v_mul_f32_e32 v224, v128, v128
	v_fmac_f32_e32 v224, v129, v129
	v_fmac_f32_e32 v224, v130, v130
	v_fmac_f32_e32 v224, v131, v131
	v_fmac_f32_e32 v224, v132, v132
	v_fmac_f32_e32 v224, v133, v133
	v_fmac_f32_e32 v224, v134, v134
	v_fmac_f32_e32 v224, v135, v135
	v_fmac_f32_e32 v224, v136, v136
	v_fmac_f32_e32 v224, v137, v137
	v_fmac_f32_e32 v224, v138, v138
	v_fmac_f32_e32 v224, v139, v139
	v_fmac_f32_e32 v224, v140, v140
	v_fmac_f32_e32 v224, v141, v141
	v_fmac_f32_e32 v224, v142, v142
	v_fmac_f32_e32 v224, v143, v143
	s_nop 1
	v_add_f32_dpp v224, v224, v224 quad_perm:[1,0,3,2] row_mask:0xf bank_mask:0xf
	s_nop 1
	v_add_f32_dpp v224, v224, v224 quad_perm:[2,3,0,1] row_mask:0xf bank_mask:0xf
	s_nop 1
	v_add_f32_dpp v224, v224, v224 row_ror:4 row_mask:0xf bank_mask:0xf
	s_nop 1
	v_add_f32_dpp v224, v224, v224 row_ror:8 row_mask:0xf bank_mask:0xf
	s_nop 1
	v_readlane_b32 s20, v224, 0
	v_readlane_b32 s21, v224, 16
	v_readlane_b32 s22, v224, 32
	v_readlane_b32 s23, v224, 48
	s_nop 1
	v_mov_b32_e32 v225, s20
	v_add_f32_e32 v225, s21, v225
	v_add_f32_e32 v225, s22, v225
	v_add_f32_e32 v225, s23, v225
	v_mov_b32_e32 v226, 0x358637bd
	v_fmac_f32_e32 v226, 0x3a800000, v225
	v_rsq_f32_e32 v226, v226
	s_nop 0
	v_mul_f32_e32 v208, v128, v226
	v_mul_f32_e32 v209, v129, v226
	v_mul_f32_e32 v210, v130, v226
	v_mul_f32_e32 v211, v131, v226
	v_mul_f32_e32 v212, v132, v226
	v_mul_f32_e32 v213, v133, v226
	v_mul_f32_e32 v214, v134, v226
	v_mul_f32_e32 v215, v135, v226
	v_mul_f32_e32 v216, v136, v226
	v_mul_f32_e32 v217, v137, v226
	v_mul_f32_e32 v218, v138, v226
	v_mul_f32_e32 v219, v139, v226
	v_mul_f32_e32 v220, v140, v226
	v_mul_f32_e32 v221, v141, v226
	v_mul_f32_e32 v222, v142, v226
	v_mul_f32_e32 v223, v143, v226
	v_mul_f32_e32 v208, v208, v56
	v_mul_f32_e32 v209, v209, v57
	v_mul_f32_e32 v210, v210, v58
	v_mul_f32_e32 v211, v211, v59
	v_mul_f32_e32 v212, v212, v60
	v_mul_f32_e32 v213, v213, v61
	v_mul_f32_e32 v214, v214, v62
	v_mul_f32_e32 v215, v215, v63
	v_mul_f32_e32 v216, v216, v64
	v_mul_f32_e32 v217, v217, v65
	v_mul_f32_e32 v218, v218, v66
	v_mul_f32_e32 v219, v219, v67
	v_mul_f32_e32 v220, v220, v68
	v_mul_f32_e32 v221, v221, v69
	v_mul_f32_e32 v222, v222, v70
	v_mul_f32_e32 v223, v223, v71
	v_cvt_pk_bf16_f32 v144, v208, v209
	v_cvt_pk_bf16_f32 v145, v210, v211
	v_cvt_pk_bf16_f32 v146, v212, v213
	v_cvt_pk_bf16_f32 v147, v214, v215
	v_cvt_pk_bf16_f32 v148, v216, v217
	v_cvt_pk_bf16_f32 v149, v218, v219
	v_cvt_pk_bf16_f32 v150, v220, v221
	v_cvt_pk_bf16_f32 v151, v222, v223
	global_store_dwordx4 v2, v[144:147], s[14:15]
	global_store_dwordx4 v2, v[148:151], s[14:15] offset:1024
	s_add_u32 s14, s14, 0x800
	s_addc_u32 s15, s15, 0
	v_readlane_b32 s4, v3, 0
	v_readlane_b32 s5, v3, 1
	v_readlane_b32 s6, v3, 2
	v_readlane_b32 s7, v3, 3
	v_readlane_b32 s8, v3, 4
	v_readlane_b32 s9, v3, 5
	v_readlane_b32 s10, v3, 6
	v_readlane_b32 s11, v3, 7
	v_readlane_b32 s12, v3, 8
	v_readlane_b32 s13, v3, 9
	v_readlane_b32 s14, v3, 10
	v_readlane_b32 s15, v3, 11
	v_readlane_b32 s16, v3, 12
	v_readlane_b32 s17, v3, 13
	v_readlane_b32 s18, v3, 14
	v_readlane_b32 s19, v3, 15
	v_readlane_b32 s20, v3, 16
	v_readlane_b32 s21, v3, 17
	v_readlane_b32 s22, v3, 18
	v_readlane_b32 s23, v3, 19
	v_readlane_b32 s24, v3, 20
	v_readlane_b32 s25, v3, 21
	s_mov_b32 s6, 0x358637bd
	s_branch .LBB0_79
; DI int obid() { int b = blockIdx.x; asm volatile("" : "+s"(b)); return b; }
; DI int ogrid() { int g = gridDim.x; asm volatile("" : "+s"(g)); return g; }
; DI int otid_w(int gw) { return (gw << 6) | olane(); }
; DI void row_phase(const bf16_t* msrc, const float* xsrc, float* xdst, const float* g_post, const float* g_next, bf16_t* hdst, const int gw) {
;     ...
;     const int tid = otid_w(gw); const int lane = tid & 63, w = tid >> 6;
;     const int wg = obid() * 8 + w, nw = ogrid() * 8;
;     for (int rowb = wg * RB; rowb < M_TOK; rowb += nw * RB) {
;         f32x4 xv[RB][4], mv[RB][4];
; #pragma unroll
;         for (int r = 0; r < RB; ++r)
; #pragma unroll
;             for (int j = 0; j < 4; ++j) xv[r][j] = *(const f32x4*)(xsrc + (size_t)(rowb + r) * DM + lane * 4 + 256 * j);
;         if (msrc) {
; #pragma unroll
;             for (int r = 0; r < RB; ++r)
; #pragma unroll
;                 for (int j = 0; j < 4; ++j) { const u32x2 mw = *(const u32x2*)(msrc + (size_t)(rowb + r) * DM + lane * 4 + 256 * j);
;                     mv[r][j] = (f32x4){__uint_as_float(mw[0] << 16), __uint_as_float(mw[0] & 0xffff0000u), __uint_as_float(mw[1] << 16), __uint_as_float(mw[1] & 0xffff0000u)}; }
;             float ss[RB];
; #pragma unroll
;             for (int r = 0; r < RB; ++r) { ss[r] = 0.f;
; #pragma unroll
;                 for (int j = 0; j < 4; ++j) ss[r] += mv[r][j][0] * mv[r][j][0] + mv[r][j][1] * mv[r][j][1] + mv[r][j][2] * mv[r][j][2] + mv[r][j][3] * mv[r][j][3]; }
.Lrow_r2h:
	v_writelane_b32 v3, s4, 0
	v_writelane_b32 v3, s5, 1
	v_writelane_b32 v3, s6, 2
	v_writelane_b32 v3, s7, 3
	v_writelane_b32 v3, s8, 4
	v_writelane_b32 v3, s9, 5
	v_writelane_b32 v3, s10, 6
	v_writelane_b32 v3, s11, 7
	v_writelane_b32 v3, s12, 8
	v_writelane_b32 v3, s13, 9
	v_writelane_b32 v3, s14, 10
	v_writelane_b32 v3, s15, 11
	v_writelane_b32 v3, s16, 12
	v_writelane_b32 v3, s17, 13
	v_writelane_b32 v3, s18, 14
	v_writelane_b32 v3, s19, 15
	v_writelane_b32 v3, s20, 16
	v_writelane_b32 v3, s21, 17
	v_writelane_b32 v3, s22, 18
	v_writelane_b32 v3, s23, 19
	v_writelane_b32 v3, s24, 20
	v_writelane_b32 v3, s25, 21
	s_waitcnt vmcnt(0) lgkmcnt(0)
	v_mbcnt_lo_u32_b32 v0, -1, 0
	v_mbcnt_hi_u32_b32 v0, -1, v0
	v_lshlrev_b32_e32 v1, 5, v0
	v_lshlrev_b32_e32 v2, 4, v0
	s_lshr_b32 s4, s71, 6
	s_and_b32 s5, s2, 7
	s_lshl_b32 s5, s5, 8
	s_lshr_b32 s24, s2, 3
	s_lshl_b32 s24, s24, 3
	s_add_i32 s5, s5, s24
	s_add_i32 s5, s5, s4
	s_lshl_b32 s24, s5, 15
	s_lshl_b32 s25, s5, 14
	v_readlane_b32 s8, v254, 62
	v_readlane_b32 s9, v254, 63
	v_readlane_b32 s6, v255, 2
	v_readlane_b32 s7, v255, 3
	v_readlane_b32 s4, v255, 6
	v_readlane_b32 s16, v255, 10
	v_readlane_b32 s17, v255, 11
	s_nop 1
	s_cmp_eq_u32 s4, 0
	s_cselect_b32 s6, s6, s8
	s_cselect_b32 s7, s7, s9
	s_add_u32 s6, s6, s24
	s_addc_u32 s7, s7, 0
	s_add_u32 s8, s8, s24
	s_addc_u32 s9, s9, 0
	s_add_u32 s10, s68, 0x10681000
	s_addc_u32 s11, s69, 0
	s_add_u32 s10, s10, s25
	s_addc_u32 s11, s11, 0
	s_add_u32 s12, s10, 0x2000000
	s_addc_u32 s13, s11, 0
	s_add_u32 s14, s82, s25
	s_addc_u32 s15, s83, 0
	s_add_u32 s18, s16, 0x1000
	s_addc_u32 s19, s17, 0
	global_load_dwordx4 v[40:43], v1, s[18:19] offset:0
	global_load_dwordx4 v[44:47], v1, s[18:19] offset:16
	global_load_dwordx4 v[48:51], v1, s[18:19] offset:2048
	global_load_dwordx4 v[52:55], v1, s[18:19] offset:2064
	s_add_u32 s18, s16, 0x3000
	s_addc_u32 s19, s17, 0
	global_load_dwordx4 v[56:59], v1, s[18:19] offset:0
	global_load_dwordx4 v[60:63], v1, s[18:19] offset:16
	global_load_dwordx4 v[64:67], v1, s[18:19] offset:2048
	global_load_dwordx4 v[68:71], v1, s[18:19] offset:2064
	s_add_u32 s18, s16, 0x4000
	s_addc_u32 s19, s17, 0
	global_load_dwordx4 v[72:75], v1, s[18:19] offset:0
	global_load_dwordx4 v[76:79], v1, s[18:19] offset:16
	global_load_dwordx4 v[80:83], v1, s[18:19] offset:2048
	global_load_dwordx4 v[84:87], v1, s[18:19] offset:2064
	global_load_dwordx4 v[96:99], v1, s[6:7] offset:0
	global_load_dwordx4 v[100:103], v1, s[6:7] offset:16
	global_load_dwordx4 v[104:107], v1, s[6:7] offset:2048
	global_load_dwordx4 v[108:111], v1, s[6:7] offset:2064
	global_load_dwordx4 v[112:115], v2, s[10:11]
	global_load_dwordx4 v[116:119], v2, s[10:11] offset:1024
	global_load_dwordx4 v[120:123], v2, s[12:13]
	global_load_dwordx4 v[124:127], v2, s[12:13] offset:1024
	s_add_u32 s6, s6, 0x1000
	s_addc_u32 s7, s7, 0
	s_add_u32 s10, s10, 0x800
	s_addc_u32 s11, s11, 0
	s_add_u32 s12, s12, 0x800
	s_addc_u32 s13, s13, 0
	global_load_dwordx4 v[128:131], v1, s[6:7] offset:0
	global_load_dwordx4 v[132:135], v1, s[6:7] offset:16
	global_load_dwordx4 v[136:139], v1, s[6:7] offset:2048
	global_load_dwordx4 v[140:143], v1, s[6:7] offset:2064
	global_load_dwordx4 v[144:147], v2, s[10:11]
	global_load_dwordx4 v[148:151], v2, s[10:11] offset:1024
	global_load_dwordx4 v[152:155], v2, s[12:13]
	global_load_dwordx4 v[156:159], v2, s[12:13] offset:1024
	s_add_u32 s6, s6, 0x1000
	s_addc_u32 s7, s7, 0
	s_add_u32 s10, s10, 0x800
	s_addc_u32 s11, s11, 0
	s_add_u32 s12, s12, 0x800
	s_addc_u32 s13, s13, 0
	global_load_dwordx4 v[160:163], v1, s[6:7] offset:0
	global_load_dwordx4 v[164:167], v1, s[6:7] offset:16
	global_load_dwordx4 v[168:171], v1, s[6:7] offset:2048
	global_load_dwordx4 v[172:175], v1, s[6:7] offset:2064
	global_load_dwordx4 v[176:179], v2, s[10:11]
	global_load_dwordx4 v[180:183], v2, s[10:11] offset:1024
	global_load_dwordx4 v[184:187], v2, s[12:13]
	global_load_dwordx4 v[188:191], v2, s[12:13] offset:1024
	s_add_u32 s6, s6, 0x1000
	s_addc_u32 s7, s7, 0
	s_add_u32 s10, s10, 0x800
	s_addc_u32 s11, s11, 0
	s_add_u32 s12, s12, 0x800
	s_addc_u32 s13, s13, 0
	s_waitcnt vmcnt(16)
	v_lshlrev_b32_e32 v208, 16, v112
	v_and_b32_e32 v209, 0xffff0000, v112
	v_lshlrev_b32_e32 v210, 16, v113
	v_and_b32_e32 v211, 0xffff0000, v113
	v_lshlrev_b32_e32 v212, 16, v114
	v_and_b32_e32 v213, 0xffff0000, v114
	v_lshlrev_b32_e32 v214, 16, v115
	v_and_b32_e32 v215, 0xffff0000, v115
	v_lshlrev_b32_e32 v216, 16, v116
	v_and_b32_e32 v217, 0xffff0000, v116
	v_lshlrev_b32_e32 v218, 16, v117
	v_and_b32_e32 v219, 0xffff0000, v117
	v_lshlrev_b32_e32 v220, 16, v118
	v_and_b32_e32 v221, 0xffff0000, v118
	v_lshlrev_b32_e32 v222, 16, v119
	v_and_b32_e32 v223, 0xffff0000, v119
	v_mul_f32_e32 v224, v208, v208
	v_fmac_f32_e32 v224, v209, v209
	v_fmac_f32_e32 v224, v210, v210
	v_fmac_f32_e32 v224, v211, v211
	v_fmac_f32_e32 v224, v212, v212
	v_fmac_f32_e32 v224, v213, v213
	v_fmac_f32_e32 v224, v214, v214
	v_fmac_f32_e32 v224, v215, v215
	v_fmac_f32_e32 v224, v216, v216
	v_fmac_f32_e32 v224, v217, v217
	v_fmac_f32_e32 v224, v218, v218
	v_fmac_f32_e32 v224, v219, v219
	v_fmac_f32_e32 v224, v220, v220
	v_fmac_f32_e32 v224, v221, v221
	v_fmac_f32_e32 v224, v222, v222
	v_fmac_f32_e32 v224, v223, v223
	s_nop 1
	v_add_f32_dpp v224, v224, v224 quad_perm:[1,0,3,2] row_mask:0xf bank_mask:0xf
	s_nop 1
	v_add_f32_dpp v224, v224, v224 quad_perm:[2,3,0,1] row_mask:0xf bank_mask:0xf
	s_nop 1
	v_add_f32_dpp v224, v224, v224 row_ror:4 row_mask:0xf bank_mask:0xf
	s_nop 1
	v_add_f32_dpp v224, v224, v224 row_ror:8 row_mask:0xf bank_mask:0xf
	s_nop 1
	v_readlane_b32 s20, v224, 0
	v_readlane_b32 s21, v224, 16
; DI unsigned pk_bf16(float a, float b) { f32x2_t v = {a, b}; bf16x2_t r = __builtin_convertvector(v, bf16x2_t); return __builtin_bit_cast(unsigned, r); }
; DI float shx(float v, int mask) { const int l = olane(); return __builtin_bit_cast(float, __builtin_amdgcn_ds_bpermute(((l ^ mask) & 63) << 2, __builtin_bit_cast(int, v))); }
; DI void row_phase(const bf16_t* msrc, const float* xsrc, float* xdst, const float* g_post, const float* g_next, bf16_t* hdst, const int gw) {
;     ...
;                 for (int j = 0; j < 4; ++j) ss[r] += mv[r][j][0] * mv[r][j][0] + mv[r][j][1] * mv[r][j][1] + mv[r][j][2] * mv[r][j][2] + mv[r][j][3] * mv[r][j][3]; }
; #pragma unroll
;             for (int o = 32; o >= 1; o >>= 1)
; #pragma unroll
;                 for (int r = 0; r < RB; ++r) ss[r] += shx(ss[r], o);
; #pragma unroll
;             for (int j = 0; j < 4; ++j) { const f32x4 g = *(const f32x4*)(g_post + lane * 4 + 256 * j);
; #pragma unroll
;                 for (int r = 0; r < RB; ++r) { const float r1 = rsqrtf(ss[r] * (1.f / DM) + EPS); xv[r][j] = xv[r][j] + mv[r][j] * r1 * g; *(f32x4*)(xdst + (size_t)(rowb + r) * DM + lane * 4 + 256 * j) = xv[r][j]; } }
;         }
;         if (hdst) {
;             float ss[RB];
; #pragma unroll
;             for (int r = 0; r < RB; ++r) { ss[r] = 0.f;
; #pragma unroll
;                 for (int j = 0; j < 4; ++j) ss[r] += xv[r][j][0] * xv[r][j][0] + xv[r][j][1] * xv[r][j][1] + xv[r][j][2] * xv[r][j][2] + xv[r][j][3] * xv[r][j][3]; }
; #pragma unroll
;             for (int o = 32; o >= 1; o >>= 1)
; #pragma unroll
;                 for (int r = 0; r < RB; ++r) ss[r] += shx(ss[r], o);
; #pragma unroll
;             for (int j = 0; j < 4; ++j) { const f32x4 g = *(const f32x4*)(g_next + lane * 4 + 256 * j);
; #pragma unroll
;                 for (int r = 0; r < RB; ++r) { const float r2 = rsqrtf(ss[r] * (1.f / DM) + EPS); const f32x4 hv = xv[r][j] * r2 * g;
;                     u32x2 o; o[0] = pk_bf16(hv[0], hv[1]); o[1] = pk_bf16(hv[2], hv[3]); *(u32x2*)(hdst + (size_t)(rowb + r) * DM + lane * 4 + 256 * j) = o; } }
	v_readlane_b32 s22, v224, 32
	v_readlane_b32 s23, v224, 48
	s_nop 1
	v_mov_b32_e32 v225, s20
	v_add_f32_e32 v225, s21, v225
	v_add_f32_e32 v225, s22, v225
	v_add_f32_e32 v225, s23, v225
	v_mov_b32_e32 v226, 0x358637bd
	v_fmac_f32_e32 v226, 0x3a800000, v225
	v_rsq_f32_e32 v226, v226
	s_nop 0
	v_mul_f32_e32 v208, v208, v226
	v_mul_f32_e32 v209, v209, v226
	v_mul_f32_e32 v210, v210, v226
	v_mul_f32_e32 v211, v211, v226
	v_mul_f32_e32 v212, v212, v226
	v_mul_f32_e32 v213, v213, v226
	v_mul_f32_e32 v214, v214, v226
	v_mul_f32_e32 v215, v215, v226
	v_mul_f32_e32 v216, v216, v226
	v_mul_f32_e32 v217, v217, v226
	v_mul_f32_e32 v218, v218, v226
	v_mul_f32_e32 v219, v219, v226
	v_mul_f32_e32 v220, v220, v226
	v_mul_f32_e32 v221, v221, v226
	v_mul_f32_e32 v222, v222, v226
	v_mul_f32_e32 v223, v223, v226
	v_fmac_f32_e32 v96, v208, v40
	v_fmac_f32_e32 v97, v209, v41
	v_fmac_f32_e32 v98, v210, v42
	v_fmac_f32_e32 v99, v211, v43
	v_fmac_f32_e32 v100, v212, v44
	v_fmac_f32_e32 v101, v213, v45
	v_fmac_f32_e32 v102, v214, v46
	v_fmac_f32_e32 v103, v215, v47
	v_fmac_f32_e32 v104, v216, v48
	v_fmac_f32_e32 v105, v217, v49
	v_fmac_f32_e32 v106, v218, v50
	v_fmac_f32_e32 v107, v219, v51
	v_fmac_f32_e32 v108, v220, v52
	v_fmac_f32_e32 v109, v221, v53
	v_fmac_f32_e32 v110, v222, v54
	v_fmac_f32_e32 v111, v223, v55
	v_lshlrev_b32_e32 v208, 16, v120
	v_and_b32_e32 v209, 0xffff0000, v120
	v_lshlrev_b32_e32 v210, 16, v121
	v_and_b32_e32 v211, 0xffff0000, v121
	v_lshlrev_b32_e32 v212, 16, v122
	v_and_b32_e32 v213, 0xffff0000, v122
	v_lshlrev_b32_e32 v214, 16, v123
	v_and_b32_e32 v215, 0xffff0000, v123
	v_lshlrev_b32_e32 v216, 16, v124
	v_and_b32_e32 v217, 0xffff0000, v124
	v_lshlrev_b32_e32 v218, 16, v125
	v_and_b32_e32 v219, 0xffff0000, v125
	v_lshlrev_b32_e32 v220, 16, v126
	v_and_b32_e32 v221, 0xffff0000, v126
	v_lshlrev_b32_e32 v222, 16, v127
	v_and_b32_e32 v223, 0xffff0000, v127
	v_mul_f32_e32 v224, v208, v208
	v_fmac_f32_e32 v224, v209, v209
	v_fmac_f32_e32 v224, v210, v210
	v_fmac_f32_e32 v224, v211, v211
	v_fmac_f32_e32 v224, v212, v212
	v_fmac_f32_e32 v224, v213, v213
	v_fmac_f32_e32 v224, v214, v214
	v_fmac_f32_e32 v224, v215, v215
	v_fmac_f32_e32 v224, v216, v216
	v_fmac_f32_e32 v224, v217, v217
	v_fmac_f32_e32 v224, v218, v218
	v_fmac_f32_e32 v224, v219, v219
	v_fmac_f32_e32 v224, v220, v220
	v_fmac_f32_e32 v224, v221, v221
	v_fmac_f32_e32 v224, v222, v222
	v_fmac_f32_e32 v224, v223, v223
	s_nop 1
	v_add_f32_dpp v224, v224, v224 quad_perm:[1,0,3,2] row_mask:0xf bank_mask:0xf
	s_nop 1
	v_add_f32_dpp v224, v224, v224 quad_perm:[2,3,0,1] row_mask:0xf bank_mask:0xf
	s_nop 1
	v_add_f32_dpp v224, v224, v224 row_ror:4 row_mask:0xf bank_mask:0xf
	s_nop 1
	v_add_f32_dpp v224, v224, v224 row_ror:8 row_mask:0xf bank_mask:0xf
	s_nop 1
	v_readlane_b32 s20, v224, 0
	v_readlane_b32 s21, v224, 16
	v_readlane_b32 s22, v224, 32
	v_readlane_b32 s23, v224, 48
	s_nop 1
	v_mov_b32_e32 v225, s20
	v_add_f32_e32 v225, s21, v225
	v_add_f32_e32 v225, s22, v225
	v_add_f32_e32 v225, s23, v225
	v_mov_b32_e32 v226, 0x358637bd
	v_fmac_f32_e32 v226, 0x3a800000, v225
	v_rsq_f32_e32 v226, v226
	s_nop 0
	v_mul_f32_e32 v208, v208, v226
	v_mul_f32_e32 v209, v209, v226
	v_mul_f32_e32 v210, v210, v226
	v_mul_f32_e32 v211, v211, v226
	v_mul_f32_e32 v212, v212, v226
	v_mul_f32_e32 v213, v213, v226
	v_mul_f32_e32 v214, v214, v226
	v_mul_f32_e32 v215, v215, v226
	v_mul_f32_e32 v216, v216, v226
	v_mul_f32_e32 v217, v217, v226
	v_mul_f32_e32 v218, v218, v226
	v_mul_f32_e32 v219, v219, v226
	v_mul_f32_e32 v220, v220, v226
	v_mul_f32_e32 v221, v221, v226
	v_mul_f32_e32 v222, v222, v226
	v_mul_f32_e32 v223, v223, v226
	v_fmac_f32_e32 v96, v208, v56
	v_fmac_f32_e32 v97, v209, v57
	v_fmac_f32_e32 v98, v210, v58
	v_fmac_f32_e32 v99, v211, v59
	v_fmac_f32_e32 v100, v212, v60
	v_fmac_f32_e32 v101, v213, v61
	v_fmac_f32_e32 v102, v214, v62
	v_fmac_f32_e32 v103, v215, v63
	v_fmac_f32_e32 v104, v216, v64
	v_fmac_f32_e32 v105, v217, v65
	v_fmac_f32_e32 v106, v218, v66
	v_fmac_f32_e32 v107, v219, v67
	v_fmac_f32_e32 v108, v220, v68
	v_fmac_f32_e32 v109, v221, v69
	v_fmac_f32_e32 v110, v222, v70
	v_fmac_f32_e32 v111, v223, v71
	global_store_dwordx4 v1, v[96:99], s[8:9] offset:0
	global_store_dwordx4 v1, v[100:103], s[8:9] offset:16
	global_store_dwordx4 v1, v[104:107], s[8:9] offset:2048
	global_store_dwordx4 v1, v[108:111], s[8:9] offset:2064
	s_add_u32 s8, s8, 0x1000
	s_addc_u32 s9, s9, 0
	v_mul_f32_e32 v224, v96, v96
	v_fmac_f32_e32 v224, v97, v97
	v_fmac_f32_e32 v224, v98, v98
	v_fmac_f32_e32 v224, v99, v99
	v_fmac_f32_e32 v224, v100, v100
	v_fmac_f32_e32 v224, v101, v101
	v_fmac_f32_e32 v224, v102, v102
	v_fmac_f32_e32 v224, v103, v103
	v_fmac_f32_e32 v224, v104, v104
	v_fmac_f32_e32 v224, v105, v105
	v_fmac_f32_e32 v224, v106, v106
	v_fmac_f32_e32 v224, v107, v107
	v_fmac_f32_e32 v224, v108, v108
	v_fmac_f32_e32 v224, v109, v109
	v_fmac_f32_e32 v224, v110, v110
	v_fmac_f32_e32 v224, v111, v111
	s_nop 1
	v_add_f32_dpp v224, v224, v224 quad_perm:[1,0,3,2] row_mask:0xf bank_mask:0xf
	s_nop 1
	v_add_f32_dpp v224, v224, v224 quad_perm:[2,3,0,1] row_mask:0xf bank_mask:0xf
	s_nop 1
	v_add_f32_dpp v224, v224, v224 row_ror:4 row_mask:0xf bank_mask:0xf
	s_nop 1
	v_add_f32_dpp v224, v224, v224 row_ror:8 row_mask:0xf bank_mask:0xf
	s_nop 1
	v_readlane_b32 s20, v224, 0
	v_readlane_b32 s21, v224, 16
	v_readlane_b32 s22, v224, 32
	v_readlane_b32 s23, v224, 48
	s_nop 1
	v_mov_b32_e32 v225, s20
	v_add_f32_e32 v225, s21, v225
	v_add_f32_e32 v225, s22, v225
	v_add_f32_e32 v225, s23, v225
	v_mov_b32_e32 v226, 0x358637bd
	v_fmac_f32_e32 v226, 0x3a800000, v225
	v_rsq_f32_e32 v226, v226
	s_nop 0
	v_mul_f32_e32 v208, v96, v226
; DI unsigned pk_bf16(float a, float b) { f32x2_t v = {a, b}; bf16x2_t r = __builtin_convertvector(v, bf16x2_t); return __builtin_bit_cast(unsigned, r); }
; DI float shx(float v, int mask) { const int l = olane(); return __builtin_bit_cast(float, __builtin_amdgcn_ds_bpermute(((l ^ mask) & 63) << 2, __builtin_bit_cast(int, v))); }
; DI void row_phase(const bf16_t* msrc, const float* xsrc, float* xdst, const float* g_post, const float* g_next, bf16_t* hdst, const int gw) {
;     ...
;                 for (int r = 0; r < RB; ++r) { const float r1 = rsqrtf(ss[r] * (1.f / DM) + EPS); xv[r][j] = xv[r][j] + mv[r][j] * r1 * g; *(f32x4*)(xdst + (size_t)(rowb + r) * DM + lane * 4 + 256 * j) = xv[r][j]; } }
;         }
;         if (hdst) {
;             float ss[RB];
; #pragma unroll
;             for (int r = 0; r < RB; ++r) { ss[r] = 0.f;
; #pragma unroll
;                 for (int j = 0; j < 4; ++j) ss[r] += xv[r][j][0] * xv[r][j][0] + xv[r][j][1] * xv[r][j][1] + xv[r][j][2] * xv[r][j][2] + xv[r][j][3] * xv[r][j][3]; }
; #pragma unroll
;             for (int o = 32; o >= 1; o >>= 1)
; #pragma unroll
;                 for (int r = 0; r < RB; ++r) ss[r] += shx(ss[r], o);
; #pragma unroll
;             for (int j = 0; j < 4; ++j) { const f32x4 g = *(const f32x4*)(g_next + lane * 4 + 256 * j);
; #pragma unroll
;                 for (int r = 0; r < RB; ++r) { const float r2 = rsqrtf(ss[r] * (1.f / DM) + EPS); const f32x4 hv = xv[r][j] * r2 * g;
;                     u32x2 o; o[0] = pk_bf16(hv[0], hv[1]); o[1] = pk_bf16(hv[2], hv[3]); *(u32x2*)(hdst + (size_t)(rowb + r) * DM + lane * 4 + 256 * j) = o; } }
	v_mul_f32_e32 v209, v97, v226
	v_mul_f32_e32 v210, v98, v226
	v_mul_f32_e32 v211, v99, v226
	v_mul_f32_e32 v212, v100, v226
	v_mul_f32_e32 v213, v101, v226
	v_mul_f32_e32 v214, v102, v226
	v_mul_f32_e32 v215, v103, v226
	v_mul_f32_e32 v216, v104, v226
	v_mul_f32_e32 v217, v105, v226
	v_mul_f32_e32 v218, v106, v226
	v_mul_f32_e32 v219, v107, v226
	v_mul_f32_e32 v220, v108, v226
	v_mul_f32_e32 v221, v109, v226
	v_mul_f32_e32 v222, v110, v226
	v_mul_f32_e32 v223, v111, v226
	v_mul_f32_e32 v208, v208, v72
	v_mul_f32_e32 v209, v209, v73
	v_mul_f32_e32 v210, v210, v74
	v_mul_f32_e32 v211, v211, v75
	v_mul_f32_e32 v212, v212, v76
	v_mul_f32_e32 v213, v213, v77
	v_mul_f32_e32 v214, v214, v78
	v_mul_f32_e32 v215, v215, v79
	v_mul_f32_e32 v216, v216, v80
	v_mul_f32_e32 v217, v217, v81
	v_mul_f32_e32 v218, v218, v82
	v_mul_f32_e32 v219, v219, v83
	v_mul_f32_e32 v220, v220, v84
	v_mul_f32_e32 v221, v221, v85
	v_mul_f32_e32 v222, v222, v86
	v_mul_f32_e32 v223, v223, v87
	v_cvt_pk_bf16_f32 v112, v208, v209
	v_cvt_pk_bf16_f32 v113, v210, v211
	v_cvt_pk_bf16_f32 v114, v212, v213
	v_cvt_pk_bf16_f32 v115, v214, v215
	v_cvt_pk_bf16_f32 v116, v216, v217
	v_cvt_pk_bf16_f32 v117, v218, v219
	v_cvt_pk_bf16_f32 v118, v220, v221
	v_cvt_pk_bf16_f32 v119, v222, v223
	global_store_dwordx4 v2, v[112:115], s[14:15]
	global_store_dwordx4 v2, v[116:119], s[14:15] offset:1024
	s_add_u32 s14, s14, 0x800
	s_addc_u32 s15, s15, 0
	global_load_dwordx4 v[96:99], v1, s[6:7] offset:0
	global_load_dwordx4 v[100:103], v1, s[6:7] offset:16
	global_load_dwordx4 v[104:107], v1, s[6:7] offset:2048
	global_load_dwordx4 v[108:111], v1, s[6:7] offset:2064
	global_load_dwordx4 v[112:115], v2, s[10:11]
	global_load_dwordx4 v[116:119], v2, s[10:11] offset:1024
	global_load_dwordx4 v[120:123], v2, s[12:13]
	global_load_dwordx4 v[124:127], v2, s[12:13] offset:1024
	s_add_u32 s6, s6, 0x1000
	s_addc_u32 s7, s7, 0
	s_add_u32 s10, s10, 0x800
	s_addc_u32 s11, s11, 0
	s_add_u32 s12, s12, 0x800
	s_addc_u32 s13, s13, 0
	s_waitcnt vmcnt(22)
	v_lshlrev_b32_e32 v208, 16, v144
	v_and_b32_e32 v209, 0xffff0000, v144
	v_lshlrev_b32_e32 v210, 16, v145
	v_and_b32_e32 v211, 0xffff0000, v145
	v_lshlrev_b32_e32 v212, 16, v146
	v_and_b32_e32 v213, 0xffff0000, v146
	v_lshlrev_b32_e32 v214, 16, v147
	v_and_b32_e32 v215, 0xffff0000, v147
	v_lshlrev_b32_e32 v216, 16, v148
	v_and_b32_e32 v217, 0xffff0000, v148
	v_lshlrev_b32_e32 v218, 16, v149
	v_and_b32_e32 v219, 0xffff0000, v149
	v_lshlrev_b32_e32 v220, 16, v150
	v_and_b32_e32 v221, 0xffff0000, v150
	v_lshlrev_b32_e32 v222, 16, v151
	v_and_b32_e32 v223, 0xffff0000, v151
	v_mul_f32_e32 v224, v208, v208
	v_fmac_f32_e32 v224, v209, v209
	v_fmac_f32_e32 v224, v210, v210
	v_fmac_f32_e32 v224, v211, v211
	v_fmac_f32_e32 v224, v212, v212
	v_fmac_f32_e32 v224, v213, v213
	v_fmac_f32_e32 v224, v214, v214
	v_fmac_f32_e32 v224, v215, v215
	v_fmac_f32_e32 v224, v216, v216
	v_fmac_f32_e32 v224, v217, v217
	v_fmac_f32_e32 v224, v218, v218
	v_fmac_f32_e32 v224, v219, v219
	v_fmac_f32_e32 v224, v220, v220
	v_fmac_f32_e32 v224, v221, v221
	v_fmac_f32_e32 v224, v222, v222
	v_fmac_f32_e32 v224, v223, v223
	s_nop 1
	v_add_f32_dpp v224, v224, v224 quad_perm:[1,0,3,2] row_mask:0xf bank_mask:0xf
	s_nop 1
	v_add_f32_dpp v224, v224, v224 quad_perm:[2,3,0,1] row_mask:0xf bank_mask:0xf
	s_nop 1
	v_add_f32_dpp v224, v224, v224 row_ror:4 row_mask:0xf bank_mask:0xf
	s_nop 1
	v_add_f32_dpp v224, v224, v224 row_ror:8 row_mask:0xf bank_mask:0xf
	s_nop 1
	v_readlane_b32 s20, v224, 0
	v_readlane_b32 s21, v224, 16
	v_readlane_b32 s22, v224, 32
	v_readlane_b32 s23, v224, 48
	s_nop 1
	v_mov_b32_e32 v225, s20
	v_add_f32_e32 v225, s21, v225
	v_add_f32_e32 v225, s22, v225
	v_add_f32_e32 v225, s23, v225
	v_mov_b32_e32 v226, 0x358637bd
	v_fmac_f32_e32 v226, 0x3a800000, v225
	v_rsq_f32_e32 v226, v226
	s_nop 0
	v_mul_f32_e32 v208, v208, v226
	v_mul_f32_e32 v209, v209, v226
	v_mul_f32_e32 v210, v210, v226
	v_mul_f32_e32 v211, v211, v226
	v_mul_f32_e32 v212, v212, v226
	v_mul_f32_e32 v213, v213, v226
	v_mul_f32_e32 v214, v214, v226
	v_mul_f32_e32 v215, v215, v226
	v_mul_f32_e32 v216, v216, v226
	v_mul_f32_e32 v217, v217, v226
	v_mul_f32_e32 v218, v218, v226
	v_mul_f32_e32 v219, v219, v226
	v_mul_f32_e32 v220, v220, v226
	v_mul_f32_e32 v221, v221, v226
	v_mul_f32_e32 v222, v222, v226
	v_mul_f32_e32 v223, v223, v226
	v_fmac_f32_e32 v128, v208, v40
	v_fmac_f32_e32 v129, v209, v41
	v_fmac_f32_e32 v130, v210, v42
	v_fmac_f32_e32 v131, v211, v43
	v_fmac_f32_e32 v132, v212, v44
	v_fmac_f32_e32 v133, v213, v45
	v_fmac_f32_e32 v134, v214, v46
	v_fmac_f32_e32 v135, v215, v47
	v_fmac_f32_e32 v136, v216, v48
	v_fmac_f32_e32 v137, v217, v49
	v_fmac_f32_e32 v138, v218, v50
	v_fmac_f32_e32 v139, v219, v51
	v_fmac_f32_e32 v140, v220, v52
	v_fmac_f32_e32 v141, v221, v53
	v_fmac_f32_e32 v142, v222, v54
	v_fmac_f32_e32 v143, v223, v55
	v_lshlrev_b32_e32 v208, 16, v152
	v_and_b32_e32 v209, 0xffff0000, v152
	v_lshlrev_b32_e32 v210, 16, v153
	v_and_b32_e32 v211, 0xffff0000, v153
	v_lshlrev_b32_e32 v212, 16, v154
	v_and_b32_e32 v213, 0xffff0000, v154
	v_lshlrev_b32_e32 v214, 16, v155
	v_and_b32_e32 v215, 0xffff0000, v155
	v_lshlrev_b32_e32 v216, 16, v156
	v_and_b32_e32 v217, 0xffff0000, v156
	v_lshlrev_b32_e32 v218, 16, v157
	v_and_b32_e32 v219, 0xffff0000, v157
	v_lshlrev_b32_e32 v220, 16, v158
	v_and_b32_e32 v221, 0xffff0000, v158
	v_lshlrev_b32_e32 v222, 16, v159
	v_and_b32_e32 v223, 0xffff0000, v159
	v_mul_f32_e32 v224, v208, v208
	v_fmac_f32_e32 v224, v209, v209
	v_fmac_f32_e32 v224, v210, v210
	v_fmac_f32_e32 v224, v211, v211
	v_fmac_f32_e32 v224, v212, v212
	v_fmac_f32_e32 v224, v213, v213
	v_fmac_f32_e32 v224, v214, v214
; DI unsigned pk_bf16(float a, float b) { f32x2_t v = {a, b}; bf16x2_t r = __builtin_convertvector(v, bf16x2_t); return __builtin_bit_cast(unsigned, r); }
; DI float shx(float v, int mask) { const int l = olane(); return __builtin_bit_cast(float, __builtin_amdgcn_ds_bpermute(((l ^ mask) & 63) << 2, __builtin_bit_cast(int, v))); }
; DI void row_phase(const bf16_t* msrc, const float* xsrc, float* xdst, const float* g_post, const float* g_next, bf16_t* hdst, const int gw) {
;     ...
;                 for (int j = 0; j < 4; ++j) ss[r] += mv[r][j][0] * mv[r][j][0] + mv[r][j][1] * mv[r][j][1] + mv[r][j][2] * mv[r][j][2] + mv[r][j][3] * mv[r][j][3]; }
; #pragma unroll
;             for (int o = 32; o >= 1; o >>= 1)
; #pragma unroll
;                 for (int r = 0; r < RB; ++r) ss[r] += shx(ss[r], o);
; #pragma unroll
;             for (int j = 0; j < 4; ++j) { const f32x4 g = *(const f32x4*)(g_post + lane * 4 + 256 * j);
; #pragma unroll
;                 for (int r = 0; r < RB; ++r) { const float r1 = rsqrtf(ss[r] * (1.f / DM) + EPS); xv[r][j] = xv[r][j] + mv[r][j] * r1 * g; *(f32x4*)(xdst + (size_t)(rowb + r) * DM + lane * 4 + 256 * j) = xv[r][j]; } }
;         }
;         if (hdst) {
;             float ss[RB];
; #pragma unroll
;             for (int r = 0; r < RB; ++r) { ss[r] = 0.f;
; #pragma unroll
;                 for (int j = 0; j < 4; ++j) ss[r] += xv[r][j][0] * xv[r][j][0] + xv[r][j][1] * xv[r][j][1] + xv[r][j][2] * xv[r][j][2] + xv[r][j][3] * xv[r][j][3]; }
; #pragma unroll
;             for (int o = 32; o >= 1; o >>= 1)
; #pragma unroll
;                 for (int r = 0; r < RB; ++r) ss[r] += shx(ss[r], o);
; #pragma unroll
;             for (int j = 0; j < 4; ++j) { const f32x4 g = *(const f32x4*)(g_next + lane * 4 + 256 * j);
; #pragma unroll
;                 for (int r = 0; r < RB; ++r) { const float r2 = rsqrtf(ss[r] * (1.f / DM) + EPS); const f32x4 hv = xv[r][j] * r2 * g;
;                     u32x2 o; o[0] = pk_bf16(hv[0], hv[1]); o[1] = pk_bf16(hv[2], hv[3]); *(u32x2*)(hdst + (size_t)(rowb + r) * DM + lane * 4 + 256 * j) = o; } }
	v_fmac_f32_e32 v224, v215, v215
	v_fmac_f32_e32 v224, v216, v216
	v_fmac_f32_e32 v224, v217, v217
	v_fmac_f32_e32 v224, v218, v218
	v_fmac_f32_e32 v224, v219, v219
	v_fmac_f32_e32 v224, v220, v220
	v_fmac_f32_e32 v224, v221, v221
	v_fmac_f32_e32 v224, v222, v222
	v_fmac_f32_e32 v224, v223, v223
	s_nop 1
	v_add_f32_dpp v224, v224, v224 quad_perm:[1,0,3,2] row_mask:0xf bank_mask:0xf
	s_nop 1
	v_add_f32_dpp v224, v224, v224 quad_perm:[2,3,0,1] row_mask:0xf bank_mask:0xf
	s_nop 1
	v_add_f32_dpp v224, v224, v224 row_ror:4 row_mask:0xf bank_mask:0xf
	s_nop 1
	v_add_f32_dpp v224, v224, v224 row_ror:8 row_mask:0xf bank_mask:0xf
	s_nop 1
	v_readlane_b32 s20, v224, 0
	v_readlane_b32 s21, v224, 16
	v_readlane_b32 s22, v224, 32
	v_readlane_b32 s23, v224, 48
	s_nop 1
	v_mov_b32_e32 v225, s20
	v_add_f32_e32 v225, s21, v225
	v_add_f32_e32 v225, s22, v225
	v_add_f32_e32 v225, s23, v225
	v_mov_b32_e32 v226, 0x358637bd
	v_fmac_f32_e32 v226, 0x3a800000, v225
	v_rsq_f32_e32 v226, v226
	s_nop 0
	v_mul_f32_e32 v208, v208, v226
	v_mul_f32_e32 v209, v209, v226
	v_mul_f32_e32 v210, v210, v226
	v_mul_f32_e32 v211, v211, v226
	v_mul_f32_e32 v212, v212, v226
	v_mul_f32_e32 v213, v213, v226
	v_mul_f32_e32 v214, v214, v226
	v_mul_f32_e32 v215, v215, v226
	v_mul_f32_e32 v216, v216, v226
	v_mul_f32_e32 v217, v217, v226
	v_mul_f32_e32 v218, v218, v226
	v_mul_f32_e32 v219, v219, v226
	v_mul_f32_e32 v220, v220, v226
	v_mul_f32_e32 v221, v221, v226
	v_mul_f32_e32 v222, v222, v226
	v_mul_f32_e32 v223, v223, v226
	v_fmac_f32_e32 v128, v208, v56
	v_fmac_f32_e32 v129, v209, v57
	v_fmac_f32_e32 v130, v210, v58
	v_fmac_f32_e32 v131, v211, v59
	v_fmac_f32_e32 v132, v212, v60
	v_fmac_f32_e32 v133, v213, v61
	v_fmac_f32_e32 v134, v214, v62
	v_fmac_f32_e32 v135, v215, v63
	v_fmac_f32_e32 v136, v216, v64
	v_fmac_f32_e32 v137, v217, v65
	v_fmac_f32_e32 v138, v218, v66
	v_fmac_f32_e32 v139, v219, v67
	v_fmac_f32_e32 v140, v220, v68
	v_fmac_f32_e32 v141, v221, v69
	v_fmac_f32_e32 v142, v222, v70
	v_fmac_f32_e32 v143, v223, v71
	global_store_dwordx4 v1, v[128:131], s[8:9] offset:0
	global_store_dwordx4 v1, v[132:135], s[8:9] offset:16
	global_store_dwordx4 v1, v[136:139], s[8:9] offset:2048
	global_store_dwordx4 v1, v[140:143], s[8:9] offset:2064
	s_add_u32 s8, s8, 0x1000
	s_addc_u32 s9, s9, 0
	v_mul_f32_e32 v224, v128, v128
	v_fmac_f32_e32 v224, v129, v129
	v_fmac_f32_e32 v224, v130, v130
	v_fmac_f32_e32 v224, v131, v131
	v_fmac_f32_e32 v224, v132, v132
	v_fmac_f32_e32 v224, v133, v133
	v_fmac_f32_e32 v224, v134, v134
	v_fmac_f32_e32 v224, v135, v135
	v_fmac_f32_e32 v224, v136, v136
	v_fmac_f32_e32 v224, v137, v137
	v_fmac_f32_e32 v224, v138, v138
	v_fmac_f32_e32 v224, v139, v139
	v_fmac_f32_e32 v224, v140, v140
	v_fmac_f32_e32 v224, v141, v141
	v_fmac_f32_e32 v224, v142, v142
	v_fmac_f32_e32 v224, v143, v143
	s_nop 1
	v_add_f32_dpp v224, v224, v224 quad_perm:[1,0,3,2] row_mask:0xf bank_mask:0xf
	s_nop 1
	v_add_f32_dpp v224, v224, v224 quad_perm:[2,3,0,1] row_mask:0xf bank_mask:0xf
	s_nop 1
	v_add_f32_dpp v224, v224, v224 row_ror:4 row_mask:0xf bank_mask:0xf
	s_nop 1
	v_add_f32_dpp v224, v224, v224 row_ror:8 row_mask:0xf bank_mask:0xf
	s_nop 1
	v_readlane_b32 s20, v224, 0
	v_readlane_b32 s21, v224, 16
	v_readlane_b32 s22, v224, 32
	v_readlane_b32 s23, v224, 48
	s_nop 1
	v_mov_b32_e32 v225, s20
	v_add_f32_e32 v225, s21, v225
	v_add_f32_e32 v225, s22, v225
	v_add_f32_e32 v225, s23, v225
	v_mov_b32_e32 v226, 0x358637bd
	v_fmac_f32_e32 v226, 0x3a800000, v225
	v_rsq_f32_e32 v226, v226
	s_nop 0
	v_mul_f32_e32 v208, v128, v226
	v_mul_f32_e32 v209, v129, v226
	v_mul_f32_e32 v210, v130, v226
	v_mul_f32_e32 v211, v131, v226
	v_mul_f32_e32 v212, v132, v226
	v_mul_f32_e32 v213, v133, v226
	v_mul_f32_e32 v214, v134, v226
	v_mul_f32_e32 v215, v135, v226
	v_mul_f32_e32 v216, v136, v226
	v_mul_f32_e32 v217, v137, v226
	v_mul_f32_e32 v218, v138, v226
	v_mul_f32_e32 v219, v139, v226
	v_mul_f32_e32 v220, v140, v226
	v_mul_f32_e32 v221, v141, v226
	v_mul_f32_e32 v222, v142, v226
	v_mul_f32_e32 v223, v143, v226
	v_mul_f32_e32 v208, v208, v72
	v_mul_f32_e32 v209, v209, v73
	v_mul_f32_e32 v210, v210, v74
	v_mul_f32_e32 v211, v211, v75
	v_mul_f32_e32 v212, v212, v76
	v_mul_f32_e32 v213, v213, v77
	v_mul_f32_e32 v214, v214, v78
	v_mul_f32_e32 v215, v215, v79
	v_mul_f32_e32 v216, v216, v80
	v_mul_f32_e32 v217, v217, v81
	v_mul_f32_e32 v218, v218, v82
	v_mul_f32_e32 v219, v219, v83
	v_mul_f32_e32 v220, v220, v84
	v_mul_f32_e32 v221, v221, v85
	v_mul_f32_e32 v222, v222, v86
	v_mul_f32_e32 v223, v223, v87
	v_cvt_pk_bf16_f32 v144, v208, v209
	v_cvt_pk_bf16_f32 v145, v210, v211
	v_cvt_pk_bf16_f32 v146, v212, v213
	v_cvt_pk_bf16_f32 v147, v214, v215
	v_cvt_pk_bf16_f32 v148, v216, v217
	v_cvt_pk_bf16_f32 v149, v218, v219
	v_cvt_pk_bf16_f32 v150, v220, v221
	v_cvt_pk_bf16_f32 v151, v222, v223
	global_store_dwordx4 v2, v[144:147], s[14:15]
	global_store_dwordx4 v2, v[148:151], s[14:15] offset:1024
	s_add_u32 s14, s14, 0x800
	s_addc_u32 s15, s15, 0
	global_load_dwordx4 v[128:131], v1, s[6:7] offset:0
	global_load_dwordx4 v[132:135], v1, s[6:7] offset:16
	global_load_dwordx4 v[136:139], v1, s[6:7] offset:2048
	global_load_dwordx4 v[140:143], v1, s[6:7] offset:2064
	global_load_dwordx4 v[144:147], v2, s[10:11]
	global_load_dwordx4 v[148:151], v2, s[10:11] offset:1024
	global_load_dwordx4 v[152:155], v2, s[12:13]
	global_load_dwordx4 v[156:159], v2, s[12:13] offset:1024
	s_add_u32 s6, s6, 0x1000
	s_addc_u32 s7, s7, 0
	s_add_u32 s10, s10, 0x800
	s_addc_u32 s11, s11, 0
	s_add_u32 s12, s12, 0x800
	s_addc_u32 s13, s13, 0
	s_waitcnt vmcnt(28)
; DI float shx(float v, int mask) { const int l = olane(); return __builtin_bit_cast(float, __builtin_amdgcn_ds_bpermute(((l ^ mask) & 63) << 2, __builtin_bit_cast(int, v))); }
; DI void row_phase(const bf16_t* msrc, const float* xsrc, float* xdst, const float* g_post, const float* g_next, bf16_t* hdst, const int gw) {
;     ...
;                 for (int j = 0; j < 4; ++j) { const u32x2 mw = *(const u32x2*)(msrc + (size_t)(rowb + r) * DM + lane * 4 + 256 * j);
;                     mv[r][j] = (f32x4){__uint_as_float(mw[0] << 16), __uint_as_float(mw[0] & 0xffff0000u), __uint_as_float(mw[1] << 16), __uint_as_float(mw[1] & 0xffff0000u)}; }
;             float ss[RB];
; #pragma unroll
;             for (int r = 0; r < RB; ++r) { ss[r] = 0.f;
; #pragma unroll
;                 for (int j = 0; j < 4; ++j) ss[r] += mv[r][j][0] * mv[r][j][0] + mv[r][j][1] * mv[r][j][1] + mv[r][j][2] * mv[r][j][2] + mv[r][j][3] * mv[r][j][3]; }
; #pragma unroll
;             for (int o = 32; o >= 1; o >>= 1)
; #pragma unroll
;                 for (int r = 0; r < RB; ++r) ss[r] += shx(ss[r], o);
; #pragma unroll
;             for (int j = 0; j < 4; ++j) { const f32x4 g = *(const f32x4*)(g_post + lane * 4 + 256 * j);
; #pragma unroll
;                 for (int r = 0; r < RB; ++r) { const float r1 = rsqrtf(ss[r] * (1.f / DM) + EPS); xv[r][j] = xv[r][j] + mv[r][j] * r1 * g; *(f32x4*)(xdst + (size_t)(rowb + r) * DM + lane * 4 + 256 * j) = xv[r][j]; } }
	v_lshlrev_b32_e32 v208, 16, v176
	v_and_b32_e32 v209, 0xffff0000, v176
	v_lshlrev_b32_e32 v210, 16, v177
	v_and_b32_e32 v211, 0xffff0000, v177
	v_lshlrev_b32_e32 v212, 16, v178
	v_and_b32_e32 v213, 0xffff0000, v178
	v_lshlrev_b32_e32 v214, 16, v179
	v_and_b32_e32 v215, 0xffff0000, v179
	v_lshlrev_b32_e32 v216, 16, v180
	v_and_b32_e32 v217, 0xffff0000, v180
	v_lshlrev_b32_e32 v218, 16, v181
	v_and_b32_e32 v219, 0xffff0000, v181
	v_lshlrev_b32_e32 v220, 16, v182
	v_and_b32_e32 v221, 0xffff0000, v182
	v_lshlrev_b32_e32 v222, 16, v183
	v_and_b32_e32 v223, 0xffff0000, v183
	v_mul_f32_e32 v224, v208, v208
	v_fmac_f32_e32 v224, v209, v209
	v_fmac_f32_e32 v224, v210, v210
	v_fmac_f32_e32 v224, v211, v211
	v_fmac_f32_e32 v224, v212, v212
	v_fmac_f32_e32 v224, v213, v213
	v_fmac_f32_e32 v224, v214, v214
	v_fmac_f32_e32 v224, v215, v215
	v_fmac_f32_e32 v224, v216, v216
	v_fmac_f32_e32 v224, v217, v217
	v_fmac_f32_e32 v224, v218, v218
	v_fmac_f32_e32 v224, v219, v219
	v_fmac_f32_e32 v224, v220, v220
	v_fmac_f32_e32 v224, v221, v221
	v_fmac_f32_e32 v224, v222, v222
	v_fmac_f32_e32 v224, v223, v223
	s_nop 1
	v_add_f32_dpp v224, v224, v224 quad_perm:[1,0,3,2] row_mask:0xf bank_mask:0xf
	s_nop 1
	v_add_f32_dpp v224, v224, v224 quad_perm:[2,3,0,1] row_mask:0xf bank_mask:0xf
	s_nop 1
	v_add_f32_dpp v224, v224, v224 row_ror:4 row_mask:0xf bank_mask:0xf
	s_nop 1
	v_add_f32_dpp v224, v224, v224 row_ror:8 row_mask:0xf bank_mask:0xf
	s_nop 1
	v_readlane_b32 s20, v224, 0
	v_readlane_b32 s21, v224, 16
	v_readlane_b32 s22, v224, 32
	v_readlane_b32 s23, v224, 48
	s_nop 1
	v_mov_b32_e32 v225, s20
	v_add_f32_e32 v225, s21, v225
	v_add_f32_e32 v225, s22, v225
	v_add_f32_e32 v225, s23, v225
	v_mov_b32_e32 v226, 0x358637bd
	v_fmac_f32_e32 v226, 0x3a800000, v225
	v_rsq_f32_e32 v226, v226
	s_nop 0
	v_mul_f32_e32 v208, v208, v226
	v_mul_f32_e32 v209, v209, v226
	v_mul_f32_e32 v210, v210, v226
	v_mul_f32_e32 v211, v211, v226
	v_mul_f32_e32 v212, v212, v226
	v_mul_f32_e32 v213, v213, v226
	v_mul_f32_e32 v214, v214, v226
	v_mul_f32_e32 v215, v215, v226
	v_mul_f32_e32 v216, v216, v226
	v_mul_f32_e32 v217, v217, v226
	v_mul_f32_e32 v218, v218, v226
	v_mul_f32_e32 v219, v219, v226
	v_mul_f32_e32 v220, v220, v226
	v_mul_f32_e32 v221, v221, v226
	v_mul_f32_e32 v222, v222, v226
	v_mul_f32_e32 v223, v223, v226
	v_fmac_f32_e32 v160, v208, v40
	v_fmac_f32_e32 v161, v209, v41
	v_fmac_f32_e32 v162, v210, v42
	v_fmac_f32_e32 v163, v211, v43
	v_fmac_f32_e32 v164, v212, v44
	v_fmac_f32_e32 v165, v213, v45
	v_fmac_f32_e32 v166, v214, v46
	v_fmac_f32_e32 v167, v215, v47
	v_fmac_f32_e32 v168, v216, v48
	v_fmac_f32_e32 v169, v217, v49
	v_fmac_f32_e32 v170, v218, v50
	v_fmac_f32_e32 v171, v219, v51
	v_fmac_f32_e32 v172, v220, v52
	v_fmac_f32_e32 v173, v221, v53
	v_fmac_f32_e32 v174, v222, v54
	v_fmac_f32_e32 v175, v223, v55
	v_lshlrev_b32_e32 v208, 16, v184
	v_and_b32_e32 v209, 0xffff0000, v184
	v_lshlrev_b32_e32 v210, 16, v185
	v_and_b32_e32 v211, 0xffff0000, v185
	v_lshlrev_b32_e32 v212, 16, v186
	v_and_b32_e32 v213, 0xffff0000, v186
	v_lshlrev_b32_e32 v214, 16, v187
	v_and_b32_e32 v215, 0xffff0000, v187
	v_lshlrev_b32_e32 v216, 16, v188
	v_and_b32_e32 v217, 0xffff0000, v188
	v_lshlrev_b32_e32 v218, 16, v189
	v_and_b32_e32 v219, 0xffff0000, v189
	v_lshlrev_b32_e32 v220, 16, v190
	v_and_b32_e32 v221, 0xffff0000, v190
	v_lshlrev_b32_e32 v222, 16, v191
	v_and_b32_e32 v223, 0xffff0000, v191
	v_mul_f32_e32 v224, v208, v208
	v_fmac_f32_e32 v224, v209, v209
	v_fmac_f32_e32 v224, v210, v210
	v_fmac_f32_e32 v224, v211, v211
	v_fmac_f32_e32 v224, v212, v212
	v_fmac_f32_e32 v224, v213, v213
	v_fmac_f32_e32 v224, v214, v214
	v_fmac_f32_e32 v224, v215, v215
	v_fmac_f32_e32 v224, v216, v216
	v_fmac_f32_e32 v224, v217, v217
	v_fmac_f32_e32 v224, v218, v218
	v_fmac_f32_e32 v224, v219, v219
	v_fmac_f32_e32 v224, v220, v220
	v_fmac_f32_e32 v224, v221, v221
	v_fmac_f32_e32 v224, v222, v222
	v_fmac_f32_e32 v224, v223, v223
	s_nop 1
	v_add_f32_dpp v224, v224, v224 quad_perm:[1,0,3,2] row_mask:0xf bank_mask:0xf
	s_nop 1
	v_add_f32_dpp v224, v224, v224 quad_perm:[2,3,0,1] row_mask:0xf bank_mask:0xf
	s_nop 1
	v_add_f32_dpp v224, v224, v224 row_ror:4 row_mask:0xf bank_mask:0xf
	s_nop 1
	v_add_f32_dpp v224, v224, v224 row_ror:8 row_mask:0xf bank_mask:0xf
	s_nop 1
	v_readlane_b32 s20, v224, 0
	v_readlane_b32 s21, v224, 16
	v_readlane_b32 s22, v224, 32
	v_readlane_b32 s23, v224, 48
	s_nop 1
	v_mov_b32_e32 v225, s20
	v_add_f32_e32 v225, s21, v225
	v_add_f32_e32 v225, s22, v225
	v_add_f32_e32 v225, s23, v225
	v_mov_b32_e32 v226, 0x358637bd
	v_fmac_f32_e32 v226, 0x3a800000, v225
	v_rsq_f32_e32 v226, v226
	s_nop 0
	v_mul_f32_e32 v208, v208, v226
	v_mul_f32_e32 v209, v209, v226
	v_mul_f32_e32 v210, v210, v226
	v_mul_f32_e32 v211, v211, v226
	v_mul_f32_e32 v212, v212, v226
	v_mul_f32_e32 v213, v213, v226
	v_mul_f32_e32 v214, v214, v226
	v_mul_f32_e32 v215, v215, v226
	v_mul_f32_e32 v216, v216, v226
	v_mul_f32_e32 v217, v217, v226
	v_mul_f32_e32 v218, v218, v226
	v_mul_f32_e32 v219, v219, v226
	v_mul_f32_e32 v220, v220, v226
	v_mul_f32_e32 v221, v221, v226
	v_mul_f32_e32 v222, v222, v226
	v_mul_f32_e32 v223, v223, v226
	v_fmac_f32_e32 v160, v208, v56
	v_fmac_f32_e32 v161, v209, v57
	v_fmac_f32_e32 v162, v210, v58
	v_fmac_f32_e32 v163, v211, v59
	v_fmac_f32_e32 v164, v212, v60
	v_fmac_f32_e32 v165, v213, v61
	v_fmac_f32_e32 v166, v214, v62
	v_fmac_f32_e32 v167, v215, v63
	v_fmac_f32_e32 v168, v216, v64
	v_fmac_f32_e32 v169, v217, v65
	v_fmac_f32_e32 v170, v218, v66
	v_fmac_f32_e32 v171, v219, v67
	v_fmac_f32_e32 v172, v220, v68
	v_fmac_f32_e32 v173, v221, v69
	v_fmac_f32_e32 v174, v222, v70
	v_fmac_f32_e32 v175, v223, v71
; DI unsigned pk_bf16(float a, float b) { f32x2_t v = {a, b}; bf16x2_t r = __builtin_convertvector(v, bf16x2_t); return __builtin_bit_cast(unsigned, r); }
; DI float shx(float v, int mask) { const int l = olane(); return __builtin_bit_cast(float, __builtin_amdgcn_ds_bpermute(((l ^ mask) & 63) << 2, __builtin_bit_cast(int, v))); }
; DI void row_phase(const bf16_t* msrc, const float* xsrc, float* xdst, const float* g_post, const float* g_next, bf16_t* hdst, const int gw) {
;     ...
;             for (int j = 0; j < 4; ++j) { const f32x4 g = *(const f32x4*)(g_post + lane * 4 + 256 * j);
; #pragma unroll
;                 for (int r = 0; r < RB; ++r) { const float r1 = rsqrtf(ss[r] * (1.f / DM) + EPS); xv[r][j] = xv[r][j] + mv[r][j] * r1 * g; *(f32x4*)(xdst + (size_t)(rowb + r) * DM + lane * 4 + 256 * j) = xv[r][j]; } }
;         }
;         if (hdst) {
;             float ss[RB];
; #pragma unroll
;             for (int r = 0; r < RB; ++r) { ss[r] = 0.f;
; #pragma unroll
;                 for (int j = 0; j < 4; ++j) ss[r] += xv[r][j][0] * xv[r][j][0] + xv[r][j][1] * xv[r][j][1] + xv[r][j][2] * xv[r][j][2] + xv[r][j][3] * xv[r][j][3]; }
; #pragma unroll
;             for (int o = 32; o >= 1; o >>= 1)
; #pragma unroll
;                 for (int r = 0; r < RB; ++r) ss[r] += shx(ss[r], o);
; #pragma unroll
;             for (int j = 0; j < 4; ++j) { const f32x4 g = *(const f32x4*)(g_next + lane * 4 + 256 * j);
; #pragma unroll
;                 for (int r = 0; r < RB; ++r) { const float r2 = rsqrtf(ss[r] * (1.f / DM) + EPS); const f32x4 hv = xv[r][j] * r2 * g;
;                     u32x2 o; o[0] = pk_bf16(hv[0], hv[1]); o[1] = pk_bf16(hv[2], hv[3]); *(u32x2*)(hdst + (size_t)(rowb + r) * DM + lane * 4 + 256 * j) = o; } }
	global_store_dwordx4 v1, v[160:163], s[8:9] offset:0
	global_store_dwordx4 v1, v[164:167], s[8:9] offset:16
	global_store_dwordx4 v1, v[168:171], s[8:9] offset:2048
	global_store_dwordx4 v1, v[172:175], s[8:9] offset:2064
	s_add_u32 s8, s8, 0x1000
	s_addc_u32 s9, s9, 0
	v_mul_f32_e32 v224, v160, v160
	v_fmac_f32_e32 v224, v161, v161
	v_fmac_f32_e32 v224, v162, v162
	v_fmac_f32_e32 v224, v163, v163
	v_fmac_f32_e32 v224, v164, v164
	v_fmac_f32_e32 v224, v165, v165
	v_fmac_f32_e32 v224, v166, v166
	v_fmac_f32_e32 v224, v167, v167
	v_fmac_f32_e32 v224, v168, v168
	v_fmac_f32_e32 v224, v169, v169
	v_fmac_f32_e32 v224, v170, v170
	v_fmac_f32_e32 v224, v171, v171
	v_fmac_f32_e32 v224, v172, v172
	v_fmac_f32_e32 v224, v173, v173
	v_fmac_f32_e32 v224, v174, v174
	v_fmac_f32_e32 v224, v175, v175
	s_nop 1
	v_add_f32_dpp v224, v224, v224 quad_perm:[1,0,3,2] row_mask:0xf bank_mask:0xf
	s_nop 1
	v_add_f32_dpp v224, v224, v224 quad_perm:[2,3,0,1] row_mask:0xf bank_mask:0xf
	s_nop 1
	v_add_f32_dpp v224, v224, v224 row_ror:4 row_mask:0xf bank_mask:0xf
	s_nop 1
	v_add_f32_dpp v224, v224, v224 row_ror:8 row_mask:0xf bank_mask:0xf
	s_nop 1
	v_readlane_b32 s20, v224, 0
	v_readlane_b32 s21, v224, 16
	v_readlane_b32 s22, v224, 32
	v_readlane_b32 s23, v224, 48
	s_nop 1
	v_mov_b32_e32 v225, s20
	v_add_f32_e32 v225, s21, v225
	v_add_f32_e32 v225, s22, v225
	v_add_f32_e32 v225, s23, v225
	v_mov_b32_e32 v226, 0x358637bd
	v_fmac_f32_e32 v226, 0x3a800000, v225
	v_rsq_f32_e32 v226, v226
	s_nop 0
	v_mul_f32_e32 v208, v160, v226
	v_mul_f32_e32 v209, v161, v226
	v_mul_f32_e32 v210, v162, v226
	v_mul_f32_e32 v211, v163, v226
	v_mul_f32_e32 v212, v164, v226
	v_mul_f32_e32 v213, v165, v226
	v_mul_f32_e32 v214, v166, v226
	v_mul_f32_e32 v215, v167, v226
	v_mul_f32_e32 v216, v168, v226
	v_mul_f32_e32 v217, v169, v226
	v_mul_f32_e32 v218, v170, v226
	v_mul_f32_e32 v219, v171, v226
	v_mul_f32_e32 v220, v172, v226
	v_mul_f32_e32 v221, v173, v226
	v_mul_f32_e32 v222, v174, v226
	v_mul_f32_e32 v223, v175, v226
	v_mul_f32_e32 v208, v208, v72
	v_mul_f32_e32 v209, v209, v73
	v_mul_f32_e32 v210, v210, v74
	v_mul_f32_e32 v211, v211, v75
	v_mul_f32_e32 v212, v212, v76
	v_mul_f32_e32 v213, v213, v77
	v_mul_f32_e32 v214, v214, v78
	v_mul_f32_e32 v215, v215, v79
	v_mul_f32_e32 v216, v216, v80
	v_mul_f32_e32 v217, v217, v81
	v_mul_f32_e32 v218, v218, v82
	v_mul_f32_e32 v219, v219, v83
	v_mul_f32_e32 v220, v220, v84
	v_mul_f32_e32 v221, v221, v85
	v_mul_f32_e32 v222, v222, v86
	v_mul_f32_e32 v223, v223, v87
	v_cvt_pk_bf16_f32 v176, v208, v209
	v_cvt_pk_bf16_f32 v177, v210, v211
	v_cvt_pk_bf16_f32 v178, v212, v213
	v_cvt_pk_bf16_f32 v179, v214, v215
	v_cvt_pk_bf16_f32 v180, v216, v217
	v_cvt_pk_bf16_f32 v181, v218, v219
	v_cvt_pk_bf16_f32 v182, v220, v221
	v_cvt_pk_bf16_f32 v183, v222, v223
	global_store_dwordx4 v2, v[176:179], s[14:15]
	global_store_dwordx4 v2, v[180:183], s[14:15] offset:1024
	s_add_u32 s14, s14, 0x800
	s_addc_u32 s15, s15, 0
	global_load_dwordx4 v[160:163], v1, s[6:7] offset:0
	global_load_dwordx4 v[164:167], v1, s[6:7] offset:16
	global_load_dwordx4 v[168:171], v1, s[6:7] offset:2048
	global_load_dwordx4 v[172:175], v1, s[6:7] offset:2064
	global_load_dwordx4 v[176:179], v2, s[10:11]
	global_load_dwordx4 v[180:183], v2, s[10:11] offset:1024
	global_load_dwordx4 v[184:187], v2, s[12:13]
	global_load_dwordx4 v[188:191], v2, s[12:13] offset:1024
	s_add_u32 s6, s6, 0x1000
	s_addc_u32 s7, s7, 0
	s_add_u32 s10, s10, 0x800
	s_addc_u32 s11, s11, 0
	s_add_u32 s12, s12, 0x800
	s_addc_u32 s13, s13, 0
	s_waitcnt vmcnt(28)
	v_lshlrev_b32_e32 v208, 16, v112
	v_and_b32_e32 v209, 0xffff0000, v112
	v_lshlrev_b32_e32 v210, 16, v113
	v_and_b32_e32 v211, 0xffff0000, v113
	v_lshlrev_b32_e32 v212, 16, v114
	v_and_b32_e32 v213, 0xffff0000, v114
	v_lshlrev_b32_e32 v214, 16, v115
	v_and_b32_e32 v215, 0xffff0000, v115
	v_lshlrev_b32_e32 v216, 16, v116
	v_and_b32_e32 v217, 0xffff0000, v116
	v_lshlrev_b32_e32 v218, 16, v117
	v_and_b32_e32 v219, 0xffff0000, v117
	v_lshlrev_b32_e32 v220, 16, v118
	v_and_b32_e32 v221, 0xffff0000, v118
	v_lshlrev_b32_e32 v222, 16, v119
	v_and_b32_e32 v223, 0xffff0000, v119
	v_mul_f32_e32 v224, v208, v208
	v_fmac_f32_e32 v224, v209, v209
	v_fmac_f32_e32 v224, v210, v210
	v_fmac_f32_e32 v224, v211, v211
	v_fmac_f32_e32 v224, v212, v212
	v_fmac_f32_e32 v224, v213, v213
	v_fmac_f32_e32 v224, v214, v214
	v_fmac_f32_e32 v224, v215, v215
	v_fmac_f32_e32 v224, v216, v216
	v_fmac_f32_e32 v224, v217, v217
	v_fmac_f32_e32 v224, v218, v218
	v_fmac_f32_e32 v224, v219, v219
	v_fmac_f32_e32 v224, v220, v220
	v_fmac_f32_e32 v224, v221, v221
	v_fmac_f32_e32 v224, v222, v222
	v_fmac_f32_e32 v224, v223, v223
	s_nop 1
	v_add_f32_dpp v224, v224, v224 quad_perm:[1,0,3,2] row_mask:0xf bank_mask:0xf
	s_nop 1
	v_add_f32_dpp v224, v224, v224 quad_perm:[2,3,0,1] row_mask:0xf bank_mask:0xf
	s_nop 1
	v_add_f32_dpp v224, v224, v224 row_ror:4 row_mask:0xf bank_mask:0xf
	s_nop 1
	v_add_f32_dpp v224, v224, v224 row_ror:8 row_mask:0xf bank_mask:0xf
	s_nop 1
	v_readlane_b32 s20, v224, 0
	v_readlane_b32 s21, v224, 16
	v_readlane_b32 s22, v224, 32
	v_readlane_b32 s23, v224, 48
	s_nop 1
	v_mov_b32_e32 v225, s20
	v_add_f32_e32 v225, s21, v225
	v_add_f32_e32 v225, s22, v225
	v_add_f32_e32 v225, s23, v225
	v_mov_b32_e32 v226, 0x358637bd
	v_fmac_f32_e32 v226, 0x3a800000, v225
	v_rsq_f32_e32 v226, v226
	s_nop 0
	v_mul_f32_e32 v208, v208, v226
	v_mul_f32_e32 v209, v209, v226
	v_mul_f32_e32 v210, v210, v226
	v_mul_f32_e32 v211, v211, v226
	v_mul_f32_e32 v212, v212, v226
	v_mul_f32_e32 v213, v213, v226
	v_mul_f32_e32 v214, v214, v226
	v_mul_f32_e32 v215, v215, v226
	v_mul_f32_e32 v216, v216, v226
; DI float shx(float v, int mask) { const int l = olane(); return __builtin_bit_cast(float, __builtin_amdgcn_ds_bpermute(((l ^ mask) & 63) << 2, __builtin_bit_cast(int, v))); }
; DI void row_phase(const bf16_t* msrc, const float* xsrc, float* xdst, const float* g_post, const float* g_next, bf16_t* hdst, const int gw) {
;     ...
;                 for (int j = 0; j < 4; ++j) ss[r] += mv[r][j][0] * mv[r][j][0] + mv[r][j][1] * mv[r][j][1] + mv[r][j][2] * mv[r][j][2] + mv[r][j][3] * mv[r][j][3]; }
; #pragma unroll
;             for (int o = 32; o >= 1; o >>= 1)
; #pragma unroll
;                 for (int r = 0; r < RB; ++r) ss[r] += shx(ss[r], o);
; #pragma unroll
;             for (int j = 0; j < 4; ++j) { const f32x4 g = *(const f32x4*)(g_post + lane * 4 + 256 * j);
; #pragma unroll
;                 for (int r = 0; r < RB; ++r) { const float r1 = rsqrtf(ss[r] * (1.f / DM) + EPS); xv[r][j] = xv[r][j] + mv[r][j] * r1 * g; *(f32x4*)(xdst + (size_t)(rowb + r) * DM + lane * 4 + 256 * j) = xv[r][j]; } }
;         }
;         if (hdst) {
;             float ss[RB];
; #pragma unroll
;             for (int r = 0; r < RB; ++r) { ss[r] = 0.f;
; #pragma unroll
;                 for (int j = 0; j < 4; ++j) ss[r] += xv[r][j][0] * xv[r][j][0] + xv[r][j][1] * xv[r][j][1] + xv[r][j][2] * xv[r][j][2] + xv[r][j][3] * xv[r][j][3]; }
; #pragma unroll
;             for (int o = 32; o >= 1; o >>= 1)
; #pragma unroll
;                 for (int r = 0; r < RB; ++r) ss[r] += shx(ss[r], o);
; #pragma unroll
;             for (int j = 0; j < 4; ++j) { const f32x4 g = *(const f32x4*)(g_next + lane * 4 + 256 * j);
; #pragma unroll
	v_mul_f32_e32 v217, v217, v226
	v_mul_f32_e32 v218, v218, v226
	v_mul_f32_e32 v219, v219, v226
	v_mul_f32_e32 v220, v220, v226
	v_mul_f32_e32 v221, v221, v226
	v_mul_f32_e32 v222, v222, v226
	v_mul_f32_e32 v223, v223, v226
	v_fmac_f32_e32 v96, v208, v40
	v_fmac_f32_e32 v97, v209, v41
	v_fmac_f32_e32 v98, v210, v42
	v_fmac_f32_e32 v99, v211, v43
	v_fmac_f32_e32 v100, v212, v44
	v_fmac_f32_e32 v101, v213, v45
	v_fmac_f32_e32 v102, v214, v46
	v_fmac_f32_e32 v103, v215, v47
	v_fmac_f32_e32 v104, v216, v48
	v_fmac_f32_e32 v105, v217, v49
	v_fmac_f32_e32 v106, v218, v50
	v_fmac_f32_e32 v107, v219, v51
	v_fmac_f32_e32 v108, v220, v52
	v_fmac_f32_e32 v109, v221, v53
	v_fmac_f32_e32 v110, v222, v54
	v_fmac_f32_e32 v111, v223, v55
	v_lshlrev_b32_e32 v208, 16, v120
	v_and_b32_e32 v209, 0xffff0000, v120
	v_lshlrev_b32_e32 v210, 16, v121
	v_and_b32_e32 v211, 0xffff0000, v121
	v_lshlrev_b32_e32 v212, 16, v122
	v_and_b32_e32 v213, 0xffff0000, v122
	v_lshlrev_b32_e32 v214, 16, v123
	v_and_b32_e32 v215, 0xffff0000, v123
	v_lshlrev_b32_e32 v216, 16, v124
	v_and_b32_e32 v217, 0xffff0000, v124
	v_lshlrev_b32_e32 v218, 16, v125
	v_and_b32_e32 v219, 0xffff0000, v125
	v_lshlrev_b32_e32 v220, 16, v126
	v_and_b32_e32 v221, 0xffff0000, v126
	v_lshlrev_b32_e32 v222, 16, v127
	v_and_b32_e32 v223, 0xffff0000, v127
	v_mul_f32_e32 v224, v208, v208
	v_fmac_f32_e32 v224, v209, v209
	v_fmac_f32_e32 v224, v210, v210
	v_fmac_f32_e32 v224, v211, v211
	v_fmac_f32_e32 v224, v212, v212
	v_fmac_f32_e32 v224, v213, v213
	v_fmac_f32_e32 v224, v214, v214
	v_fmac_f32_e32 v224, v215, v215
	v_fmac_f32_e32 v224, v216, v216
	v_fmac_f32_e32 v224, v217, v217
	v_fmac_f32_e32 v224, v218, v218
	v_fmac_f32_e32 v224, v219, v219
	v_fmac_f32_e32 v224, v220, v220
	v_fmac_f32_e32 v224, v221, v221
	v_fmac_f32_e32 v224, v222, v222
	v_fmac_f32_e32 v224, v223, v223
	s_nop 1
	v_add_f32_dpp v224, v224, v224 quad_perm:[1,0,3,2] row_mask:0xf bank_mask:0xf
	s_nop 1
	v_add_f32_dpp v224, v224, v224 quad_perm:[2,3,0,1] row_mask:0xf bank_mask:0xf
	s_nop 1
	v_add_f32_dpp v224, v224, v224 row_ror:4 row_mask:0xf bank_mask:0xf
	s_nop 1
	v_add_f32_dpp v224, v224, v224 row_ror:8 row_mask:0xf bank_mask:0xf
	s_nop 1
	v_readlane_b32 s20, v224, 0
	v_readlane_b32 s21, v224, 16
	v_readlane_b32 s22, v224, 32
	v_readlane_b32 s23, v224, 48
	s_nop 1
	v_mov_b32_e32 v225, s20
	v_add_f32_e32 v225, s21, v225
	v_add_f32_e32 v225, s22, v225
	v_add_f32_e32 v225, s23, v225
	v_mov_b32_e32 v226, 0x358637bd
	v_fmac_f32_e32 v226, 0x3a800000, v225
	v_rsq_f32_e32 v226, v226
	s_nop 0
	v_mul_f32_e32 v208, v208, v226
	v_mul_f32_e32 v209, v209, v226
	v_mul_f32_e32 v210, v210, v226
	v_mul_f32_e32 v211, v211, v226
	v_mul_f32_e32 v212, v212, v226
	v_mul_f32_e32 v213, v213, v226
	v_mul_f32_e32 v214, v214, v226
	v_mul_f32_e32 v215, v215, v226
	v_mul_f32_e32 v216, v216, v226
	v_mul_f32_e32 v217, v217, v226
	v_mul_f32_e32 v218, v218, v226
	v_mul_f32_e32 v219, v219, v226
	v_mul_f32_e32 v220, v220, v226
	v_mul_f32_e32 v221, v221, v226
	v_mul_f32_e32 v222, v222, v226
	v_mul_f32_e32 v223, v223, v226
	v_fmac_f32_e32 v96, v208, v56
	v_fmac_f32_e32 v97, v209, v57
	v_fmac_f32_e32 v98, v210, v58
	v_fmac_f32_e32 v99, v211, v59
	v_fmac_f32_e32 v100, v212, v60
	v_fmac_f32_e32 v101, v213, v61
	v_fmac_f32_e32 v102, v214, v62
	v_fmac_f32_e32 v103, v215, v63
	v_fmac_f32_e32 v104, v216, v64
	v_fmac_f32_e32 v105, v217, v65
	v_fmac_f32_e32 v106, v218, v66
	v_fmac_f32_e32 v107, v219, v67
	v_fmac_f32_e32 v108, v220, v68
	v_fmac_f32_e32 v109, v221, v69
	v_fmac_f32_e32 v110, v222, v70
	v_fmac_f32_e32 v111, v223, v71
	global_store_dwordx4 v1, v[96:99], s[8:9] offset:0
	global_store_dwordx4 v1, v[100:103], s[8:9] offset:16
	global_store_dwordx4 v1, v[104:107], s[8:9] offset:2048
	global_store_dwordx4 v1, v[108:111], s[8:9] offset:2064
	s_add_u32 s8, s8, 0x1000
	s_addc_u32 s9, s9, 0
	v_mul_f32_e32 v224, v96, v96
	v_fmac_f32_e32 v224, v97, v97
	v_fmac_f32_e32 v224, v98, v98
	v_fmac_f32_e32 v224, v99, v99
	v_fmac_f32_e32 v224, v100, v100
	v_fmac_f32_e32 v224, v101, v101
	v_fmac_f32_e32 v224, v102, v102
	v_fmac_f32_e32 v224, v103, v103
	v_fmac_f32_e32 v224, v104, v104
	v_fmac_f32_e32 v224, v105, v105
	v_fmac_f32_e32 v224, v106, v106
	v_fmac_f32_e32 v224, v107, v107
	v_fmac_f32_e32 v224, v108, v108
	v_fmac_f32_e32 v224, v109, v109
	v_fmac_f32_e32 v224, v110, v110
	v_fmac_f32_e32 v224, v111, v111
	s_nop 1
	v_add_f32_dpp v224, v224, v224 quad_perm:[1,0,3,2] row_mask:0xf bank_mask:0xf
	s_nop 1
	v_add_f32_dpp v224, v224, v224 quad_perm:[2,3,0,1] row_mask:0xf bank_mask:0xf
	s_nop 1
	v_add_f32_dpp v224, v224, v224 row_ror:4 row_mask:0xf bank_mask:0xf
	s_nop 1
	v_add_f32_dpp v224, v224, v224 row_ror:8 row_mask:0xf bank_mask:0xf
	s_nop 1
	v_readlane_b32 s20, v224, 0
	v_readlane_b32 s21, v224, 16
	v_readlane_b32 s22, v224, 32
	v_readlane_b32 s23, v224, 48
	s_nop 1
	v_mov_b32_e32 v225, s20
	v_add_f32_e32 v225, s21, v225
	v_add_f32_e32 v225, s22, v225
	v_add_f32_e32 v225, s23, v225
	v_mov_b32_e32 v226, 0x358637bd
	v_fmac_f32_e32 v226, 0x3a800000, v225
	v_rsq_f32_e32 v226, v226
	s_nop 0
	v_mul_f32_e32 v208, v96, v226
	v_mul_f32_e32 v209, v97, v226
	v_mul_f32_e32 v210, v98, v226
	v_mul_f32_e32 v211, v99, v226
	v_mul_f32_e32 v212, v100, v226
	v_mul_f32_e32 v213, v101, v226
	v_mul_f32_e32 v214, v102, v226
	v_mul_f32_e32 v215, v103, v226
	v_mul_f32_e32 v216, v104, v226
	v_mul_f32_e32 v217, v105, v226
	v_mul_f32_e32 v218, v106, v226
	v_mul_f32_e32 v219, v107, v226
	v_mul_f32_e32 v220, v108, v226
	v_mul_f32_e32 v221, v109, v226
	v_mul_f32_e32 v222, v110, v226
	v_mul_f32_e32 v223, v111, v226
	v_mul_f32_e32 v208, v208, v72
	v_mul_f32_e32 v209, v209, v73
	v_mul_f32_e32 v210, v210, v74
; DI unsigned pk_bf16(float a, float b) { f32x2_t v = {a, b}; bf16x2_t r = __builtin_convertvector(v, bf16x2_t); return __builtin_bit_cast(unsigned, r); }
; DI float shx(float v, int mask) { const int l = olane(); return __builtin_bit_cast(float, __builtin_amdgcn_ds_bpermute(((l ^ mask) & 63) << 2, __builtin_bit_cast(int, v))); }
; DI void row_phase(const bf16_t* msrc, const float* xsrc, float* xdst, const float* g_post, const float* g_next, bf16_t* hdst, const int gw) {
;     ...
;             for (int j = 0; j < 4; ++j) { const f32x4 g = *(const f32x4*)(g_post + lane * 4 + 256 * j);
; #pragma unroll
;                 for (int r = 0; r < RB; ++r) { const float r1 = rsqrtf(ss[r] * (1.f / DM) + EPS); xv[r][j] = xv[r][j] + mv[r][j] * r1 * g; *(f32x4*)(xdst + (size_t)(rowb + r) * DM + lane * 4 + 256 * j) = xv[r][j]; } }
;         }
;         if (hdst) {
;             float ss[RB];
; #pragma unroll
;             for (int r = 0; r < RB; ++r) { ss[r] = 0.f;
; #pragma unroll
;                 for (int j = 0; j < 4; ++j) ss[r] += xv[r][j][0] * xv[r][j][0] + xv[r][j][1] * xv[r][j][1] + xv[r][j][2] * xv[r][j][2] + xv[r][j][3] * xv[r][j][3]; }
; #pragma unroll
;             for (int o = 32; o >= 1; o >>= 1)
; #pragma unroll
;                 for (int r = 0; r < RB; ++r) ss[r] += shx(ss[r], o);
; #pragma unroll
;             for (int j = 0; j < 4; ++j) { const f32x4 g = *(const f32x4*)(g_next + lane * 4 + 256 * j);
; #pragma unroll
;                 for (int r = 0; r < RB; ++r) { const float r2 = rsqrtf(ss[r] * (1.f / DM) + EPS); const f32x4 hv = xv[r][j] * r2 * g;
;                     u32x2 o; o[0] = pk_bf16(hv[0], hv[1]); o[1] = pk_bf16(hv[2], hv[3]); *(u32x2*)(hdst + (size_t)(rowb + r) * DM + lane * 4 + 256 * j) = o; } }
	v_mul_f32_e32 v211, v211, v75
	v_mul_f32_e32 v212, v212, v76
	v_mul_f32_e32 v213, v213, v77
	v_mul_f32_e32 v214, v214, v78
	v_mul_f32_e32 v215, v215, v79
	v_mul_f32_e32 v216, v216, v80
	v_mul_f32_e32 v217, v217, v81
	v_mul_f32_e32 v218, v218, v82
	v_mul_f32_e32 v219, v219, v83
	v_mul_f32_e32 v220, v220, v84
	v_mul_f32_e32 v221, v221, v85
	v_mul_f32_e32 v222, v222, v86
	v_mul_f32_e32 v223, v223, v87
	v_cvt_pk_bf16_f32 v112, v208, v209
	v_cvt_pk_bf16_f32 v113, v210, v211
	v_cvt_pk_bf16_f32 v114, v212, v213
	v_cvt_pk_bf16_f32 v115, v214, v215
	v_cvt_pk_bf16_f32 v116, v216, v217
	v_cvt_pk_bf16_f32 v117, v218, v219
	v_cvt_pk_bf16_f32 v118, v220, v221
	v_cvt_pk_bf16_f32 v119, v222, v223
	global_store_dwordx4 v2, v[112:115], s[14:15]
	global_store_dwordx4 v2, v[116:119], s[14:15] offset:1024
	s_add_u32 s14, s14, 0x800
	s_addc_u32 s15, s15, 0
	global_load_dwordx4 v[96:99], v1, s[6:7] offset:0
	global_load_dwordx4 v[100:103], v1, s[6:7] offset:16
	global_load_dwordx4 v[104:107], v1, s[6:7] offset:2048
	global_load_dwordx4 v[108:111], v1, s[6:7] offset:2064
	global_load_dwordx4 v[112:115], v2, s[10:11]
	global_load_dwordx4 v[116:119], v2, s[10:11] offset:1024
	global_load_dwordx4 v[120:123], v2, s[12:13]
	global_load_dwordx4 v[124:127], v2, s[12:13] offset:1024
	s_add_u32 s6, s6, 0x1000
	s_addc_u32 s7, s7, 0
	s_add_u32 s10, s10, 0x800
	s_addc_u32 s11, s11, 0
	s_add_u32 s12, s12, 0x800
	s_addc_u32 s13, s13, 0
	s_waitcnt vmcnt(28)
	v_lshlrev_b32_e32 v208, 16, v144
	v_and_b32_e32 v209, 0xffff0000, v144
	v_lshlrev_b32_e32 v210, 16, v145
	v_and_b32_e32 v211, 0xffff0000, v145
	v_lshlrev_b32_e32 v212, 16, v146
	v_and_b32_e32 v213, 0xffff0000, v146
	v_lshlrev_b32_e32 v214, 16, v147
	v_and_b32_e32 v215, 0xffff0000, v147
	v_lshlrev_b32_e32 v216, 16, v148
	v_and_b32_e32 v217, 0xffff0000, v148
	v_lshlrev_b32_e32 v218, 16, v149
	v_and_b32_e32 v219, 0xffff0000, v149
	v_lshlrev_b32_e32 v220, 16, v150
	v_and_b32_e32 v221, 0xffff0000, v150
	v_lshlrev_b32_e32 v222, 16, v151
	v_and_b32_e32 v223, 0xffff0000, v151
	v_mul_f32_e32 v224, v208, v208
	v_fmac_f32_e32 v224, v209, v209
	v_fmac_f32_e32 v224, v210, v210
	v_fmac_f32_e32 v224, v211, v211
	v_fmac_f32_e32 v224, v212, v212
	v_fmac_f32_e32 v224, v213, v213
	v_fmac_f32_e32 v224, v214, v214
	v_fmac_f32_e32 v224, v215, v215
	v_fmac_f32_e32 v224, v216, v216
	v_fmac_f32_e32 v224, v217, v217
	v_fmac_f32_e32 v224, v218, v218
	v_fmac_f32_e32 v224, v219, v219
	v_fmac_f32_e32 v224, v220, v220
	v_fmac_f32_e32 v224, v221, v221
	v_fmac_f32_e32 v224, v222, v222
	v_fmac_f32_e32 v224, v223, v223
	s_nop 1
	v_add_f32_dpp v224, v224, v224 quad_perm:[1,0,3,2] row_mask:0xf bank_mask:0xf
	s_nop 1
	v_add_f32_dpp v224, v224, v224 quad_perm:[2,3,0,1] row_mask:0xf bank_mask:0xf
	s_nop 1
	v_add_f32_dpp v224, v224, v224 row_ror:4 row_mask:0xf bank_mask:0xf
	s_nop 1
	v_add_f32_dpp v224, v224, v224 row_ror:8 row_mask:0xf bank_mask:0xf
	s_nop 1
	v_readlane_b32 s20, v224, 0
	v_readlane_b32 s21, v224, 16
	v_readlane_b32 s22, v224, 32
	v_readlane_b32 s23, v224, 48
	s_nop 1
	v_mov_b32_e32 v225, s20
	v_add_f32_e32 v225, s21, v225
	v_add_f32_e32 v225, s22, v225
	v_add_f32_e32 v225, s23, v225
	v_mov_b32_e32 v226, 0x358637bd
	v_fmac_f32_e32 v226, 0x3a800000, v225
	v_rsq_f32_e32 v226, v226
	s_nop 0
	v_mul_f32_e32 v208, v208, v226
	v_mul_f32_e32 v209, v209, v226
	v_mul_f32_e32 v210, v210, v226
	v_mul_f32_e32 v211, v211, v226
	v_mul_f32_e32 v212, v212, v226
	v_mul_f32_e32 v213, v213, v226
	v_mul_f32_e32 v214, v214, v226
	v_mul_f32_e32 v215, v215, v226
	v_mul_f32_e32 v216, v216, v226
	v_mul_f32_e32 v217, v217, v226
	v_mul_f32_e32 v218, v218, v226
	v_mul_f32_e32 v219, v219, v226
	v_mul_f32_e32 v220, v220, v226
	v_mul_f32_e32 v221, v221, v226
	v_mul_f32_e32 v222, v222, v226
	v_mul_f32_e32 v223, v223, v226
	v_fmac_f32_e32 v128, v208, v40
	v_fmac_f32_e32 v129, v209, v41
	v_fmac_f32_e32 v130, v210, v42
	v_fmac_f32_e32 v131, v211, v43
	v_fmac_f32_e32 v132, v212, v44
	v_fmac_f32_e32 v133, v213, v45
	v_fmac_f32_e32 v134, v214, v46
	v_fmac_f32_e32 v135, v215, v47
	v_fmac_f32_e32 v136, v216, v48
	v_fmac_f32_e32 v137, v217, v49
	v_fmac_f32_e32 v138, v218, v50
	v_fmac_f32_e32 v139, v219, v51
	v_fmac_f32_e32 v140, v220, v52
	v_fmac_f32_e32 v141, v221, v53
	v_fmac_f32_e32 v142, v222, v54
	v_fmac_f32_e32 v143, v223, v55
	v_lshlrev_b32_e32 v208, 16, v152
	v_and_b32_e32 v209, 0xffff0000, v152
	v_lshlrev_b32_e32 v210, 16, v153
	v_and_b32_e32 v211, 0xffff0000, v153
	v_lshlrev_b32_e32 v212, 16, v154
	v_and_b32_e32 v213, 0xffff0000, v154
	v_lshlrev_b32_e32 v214, 16, v155
	v_and_b32_e32 v215, 0xffff0000, v155
	v_lshlrev_b32_e32 v216, 16, v156
	v_and_b32_e32 v217, 0xffff0000, v156
	v_lshlrev_b32_e32 v218, 16, v157
	v_and_b32_e32 v219, 0xffff0000, v157
	v_lshlrev_b32_e32 v220, 16, v158
	v_and_b32_e32 v221, 0xffff0000, v158
	v_lshlrev_b32_e32 v222, 16, v159
	v_and_b32_e32 v223, 0xffff0000, v159
	v_mul_f32_e32 v224, v208, v208
	v_fmac_f32_e32 v224, v209, v209
	v_fmac_f32_e32 v224, v210, v210
	v_fmac_f32_e32 v224, v211, v211
	v_fmac_f32_e32 v224, v212, v212
	v_fmac_f32_e32 v224, v213, v213
	v_fmac_f32_e32 v224, v214, v214
	v_fmac_f32_e32 v224, v215, v215
	v_fmac_f32_e32 v224, v216, v216
	v_fmac_f32_e32 v224, v217, v217
	v_fmac_f32_e32 v224, v218, v218
	v_fmac_f32_e32 v224, v219, v219
	v_fmac_f32_e32 v224, v220, v220
	v_fmac_f32_e32 v224, v221, v221
	v_fmac_f32_e32 v224, v222, v222
	v_fmac_f32_e32 v224, v223, v223
	s_nop 1
	v_add_f32_dpp v224, v224, v224 quad_perm:[1,0,3,2] row_mask:0xf bank_mask:0xf
	s_nop 1
	v_add_f32_dpp v224, v224, v224 quad_perm:[2,3,0,1] row_mask:0xf bank_mask:0xf
	s_nop 1
	v_add_f32_dpp v224, v224, v224 row_ror:4 row_mask:0xf bank_mask:0xf
	s_nop 1
; DI unsigned pk_bf16(float a, float b) { f32x2_t v = {a, b}; bf16x2_t r = __builtin_convertvector(v, bf16x2_t); return __builtin_bit_cast(unsigned, r); }
; DI float shx(float v, int mask) { const int l = olane(); return __builtin_bit_cast(float, __builtin_amdgcn_ds_bpermute(((l ^ mask) & 63) << 2, __builtin_bit_cast(int, v))); }
; DI void row_phase(const bf16_t* msrc, const float* xsrc, float* xdst, const float* g_post, const float* g_next, bf16_t* hdst, const int gw) {
;     ...
;                 for (int j = 0; j < 4; ++j) ss[r] += mv[r][j][0] * mv[r][j][0] + mv[r][j][1] * mv[r][j][1] + mv[r][j][2] * mv[r][j][2] + mv[r][j][3] * mv[r][j][3]; }
; #pragma unroll
;             for (int o = 32; o >= 1; o >>= 1)
; #pragma unroll
;                 for (int r = 0; r < RB; ++r) ss[r] += shx(ss[r], o);
; #pragma unroll
;             for (int j = 0; j < 4; ++j) { const f32x4 g = *(const f32x4*)(g_post + lane * 4 + 256 * j);
; #pragma unroll
;                 for (int r = 0; r < RB; ++r) { const float r1 = rsqrtf(ss[r] * (1.f / DM) + EPS); xv[r][j] = xv[r][j] + mv[r][j] * r1 * g; *(f32x4*)(xdst + (size_t)(rowb + r) * DM + lane * 4 + 256 * j) = xv[r][j]; } }
;         }
;         if (hdst) {
;             float ss[RB];
; #pragma unroll
;             for (int r = 0; r < RB; ++r) { ss[r] = 0.f;
; #pragma unroll
;                 for (int j = 0; j < 4; ++j) ss[r] += xv[r][j][0] * xv[r][j][0] + xv[r][j][1] * xv[r][j][1] + xv[r][j][2] * xv[r][j][2] + xv[r][j][3] * xv[r][j][3]; }
; #pragma unroll
;             for (int o = 32; o >= 1; o >>= 1)
; #pragma unroll
;                 for (int r = 0; r < RB; ++r) ss[r] += shx(ss[r], o);
; #pragma unroll
;             for (int j = 0; j < 4; ++j) { const f32x4 g = *(const f32x4*)(g_next + lane * 4 + 256 * j);
; #pragma unroll
;                 for (int r = 0; r < RB; ++r) { const float r2 = rsqrtf(ss[r] * (1.f / DM) + EPS); const f32x4 hv = xv[r][j] * r2 * g;
;                     u32x2 o; o[0] = pk_bf16(hv[0], hv[1]); o[1] = pk_bf16(hv[2], hv[3]); *(u32x2*)(hdst + (size_t)(rowb + r) * DM + lane * 4 + 256 * j) = o; } }
	v_add_f32_dpp v224, v224, v224 row_ror:8 row_mask:0xf bank_mask:0xf
	s_nop 1
	v_readlane_b32 s20, v224, 0
	v_readlane_b32 s21, v224, 16
	v_readlane_b32 s22, v224, 32
	v_readlane_b32 s23, v224, 48
	s_nop 1
	v_mov_b32_e32 v225, s20
	v_add_f32_e32 v225, s21, v225
	v_add_f32_e32 v225, s22, v225
	v_add_f32_e32 v225, s23, v225
	v_mov_b32_e32 v226, 0x358637bd
	v_fmac_f32_e32 v226, 0x3a800000, v225
	v_rsq_f32_e32 v226, v226
	s_nop 0
	v_mul_f32_e32 v208, v208, v226
	v_mul_f32_e32 v209, v209, v226
	v_mul_f32_e32 v210, v210, v226
	v_mul_f32_e32 v211, v211, v226
	v_mul_f32_e32 v212, v212, v226
	v_mul_f32_e32 v213, v213, v226
	v_mul_f32_e32 v214, v214, v226
	v_mul_f32_e32 v215, v215, v226
	v_mul_f32_e32 v216, v216, v226
	v_mul_f32_e32 v217, v217, v226
	v_mul_f32_e32 v218, v218, v226
	v_mul_f32_e32 v219, v219, v226
	v_mul_f32_e32 v220, v220, v226
	v_mul_f32_e32 v221, v221, v226
	v_mul_f32_e32 v222, v222, v226
	v_mul_f32_e32 v223, v223, v226
	v_fmac_f32_e32 v128, v208, v56
	v_fmac_f32_e32 v129, v209, v57
	v_fmac_f32_e32 v130, v210, v58
	v_fmac_f32_e32 v131, v211, v59
	v_fmac_f32_e32 v132, v212, v60
	v_fmac_f32_e32 v133, v213, v61
	v_fmac_f32_e32 v134, v214, v62
	v_fmac_f32_e32 v135, v215, v63
	v_fmac_f32_e32 v136, v216, v64
	v_fmac_f32_e32 v137, v217, v65
	v_fmac_f32_e32 v138, v218, v66
	v_fmac_f32_e32 v139, v219, v67
	v_fmac_f32_e32 v140, v220, v68
	v_fmac_f32_e32 v141, v221, v69
	v_fmac_f32_e32 v142, v222, v70
	v_fmac_f32_e32 v143, v223, v71
	global_store_dwordx4 v1, v[128:131], s[8:9] offset:0
	global_store_dwordx4 v1, v[132:135], s[8:9] offset:16
	global_store_dwordx4 v1, v[136:139], s[8:9] offset:2048
	global_store_dwordx4 v1, v[140:143], s[8:9] offset:2064
	s_add_u32 s8, s8, 0x1000
	s_addc_u32 s9, s9, 0
	v_mul_f32_e32 v224, v128, v128
	v_fmac_f32_e32 v224, v129, v129
	v_fmac_f32_e32 v224, v130, v130
	v_fmac_f32_e32 v224, v131, v131
	v_fmac_f32_e32 v224, v132, v132
	v_fmac_f32_e32 v224, v133, v133
	v_fmac_f32_e32 v224, v134, v134
	v_fmac_f32_e32 v224, v135, v135
	v_fmac_f32_e32 v224, v136, v136
	v_fmac_f32_e32 v224, v137, v137
	v_fmac_f32_e32 v224, v138, v138
	v_fmac_f32_e32 v224, v139, v139
	v_fmac_f32_e32 v224, v140, v140
	v_fmac_f32_e32 v224, v141, v141
	v_fmac_f32_e32 v224, v142, v142
	v_fmac_f32_e32 v224, v143, v143
	s_nop 1
	v_add_f32_dpp v224, v224, v224 quad_perm:[1,0,3,2] row_mask:0xf bank_mask:0xf
	s_nop 1
	v_add_f32_dpp v224, v224, v224 quad_perm:[2,3,0,1] row_mask:0xf bank_mask:0xf
	s_nop 1
	v_add_f32_dpp v224, v224, v224 row_ror:4 row_mask:0xf bank_mask:0xf
	s_nop 1
	v_add_f32_dpp v224, v224, v224 row_ror:8 row_mask:0xf bank_mask:0xf
	s_nop 1
	v_readlane_b32 s20, v224, 0
	v_readlane_b32 s21, v224, 16
	v_readlane_b32 s22, v224, 32
	v_readlane_b32 s23, v224, 48
	s_nop 1
	v_mov_b32_e32 v225, s20
	v_add_f32_e32 v225, s21, v225
	v_add_f32_e32 v225, s22, v225
	v_add_f32_e32 v225, s23, v225
	v_mov_b32_e32 v226, 0x358637bd
	v_fmac_f32_e32 v226, 0x3a800000, v225
	v_rsq_f32_e32 v226, v226
	s_nop 0
	v_mul_f32_e32 v208, v128, v226
	v_mul_f32_e32 v209, v129, v226
	v_mul_f32_e32 v210, v130, v226
	v_mul_f32_e32 v211, v131, v226
	v_mul_f32_e32 v212, v132, v226
	v_mul_f32_e32 v213, v133, v226
	v_mul_f32_e32 v214, v134, v226
	v_mul_f32_e32 v215, v135, v226
	v_mul_f32_e32 v216, v136, v226
	v_mul_f32_e32 v217, v137, v226
	v_mul_f32_e32 v218, v138, v226
	v_mul_f32_e32 v219, v139, v226
	v_mul_f32_e32 v220, v140, v226
	v_mul_f32_e32 v221, v141, v226
	v_mul_f32_e32 v222, v142, v226
	v_mul_f32_e32 v223, v143, v226
	v_mul_f32_e32 v208, v208, v72
	v_mul_f32_e32 v209, v209, v73
	v_mul_f32_e32 v210, v210, v74
	v_mul_f32_e32 v211, v211, v75
	v_mul_f32_e32 v212, v212, v76
	v_mul_f32_e32 v213, v213, v77
	v_mul_f32_e32 v214, v214, v78
	v_mul_f32_e32 v215, v215, v79
	v_mul_f32_e32 v216, v216, v80
	v_mul_f32_e32 v217, v217, v81
	v_mul_f32_e32 v218, v218, v82
	v_mul_f32_e32 v219, v219, v83
	v_mul_f32_e32 v220, v220, v84
	v_mul_f32_e32 v221, v221, v85
	v_mul_f32_e32 v222, v222, v86
	v_mul_f32_e32 v223, v223, v87
	v_cvt_pk_bf16_f32 v144, v208, v209
	v_cvt_pk_bf16_f32 v145, v210, v211
	v_cvt_pk_bf16_f32 v146, v212, v213
	v_cvt_pk_bf16_f32 v147, v214, v215
	v_cvt_pk_bf16_f32 v148, v216, v217
	v_cvt_pk_bf16_f32 v149, v218, v219
	v_cvt_pk_bf16_f32 v150, v220, v221
	v_cvt_pk_bf16_f32 v151, v222, v223
	global_store_dwordx4 v2, v[144:147], s[14:15]
	global_store_dwordx4 v2, v[148:151], s[14:15] offset:1024
	s_add_u32 s14, s14, 0x800
	s_addc_u32 s15, s15, 0
	global_load_dwordx4 v[128:131], v1, s[6:7] offset:0
	global_load_dwordx4 v[132:135], v1, s[6:7] offset:16
	global_load_dwordx4 v[136:139], v1, s[6:7] offset:2048
	global_load_dwordx4 v[140:143], v1, s[6:7] offset:2064
	global_load_dwordx4 v[144:147], v2, s[10:11]
	global_load_dwordx4 v[148:151], v2, s[10:11] offset:1024
	global_load_dwordx4 v[152:155], v2, s[12:13]
	global_load_dwordx4 v[156:159], v2, s[12:13] offset:1024
	s_add_u32 s6, s6, 0x1000
	s_addc_u32 s7, s7, 0
	s_add_u32 s10, s10, 0x800
	s_addc_u32 s11, s11, 0
	s_add_u32 s12, s12, 0x800
	s_addc_u32 s13, s13, 0
	s_waitcnt vmcnt(28)
; DI float shx(float v, int mask) { const int l = olane(); return __builtin_bit_cast(float, __builtin_amdgcn_ds_bpermute(((l ^ mask) & 63) << 2, __builtin_bit_cast(int, v))); }
; DI void row_phase(const bf16_t* msrc, const float* xsrc, float* xdst, const float* g_post, const float* g_next, bf16_t* hdst, const int gw) {
;     ...
;                 for (int j = 0; j < 4; ++j) { const u32x2 mw = *(const u32x2*)(msrc + (size_t)(rowb + r) * DM + lane * 4 + 256 * j);
;                     mv[r][j] = (f32x4){__uint_as_float(mw[0] << 16), __uint_as_float(mw[0] & 0xffff0000u), __uint_as_float(mw[1] << 16), __uint_as_float(mw[1] & 0xffff0000u)}; }
;             float ss[RB];
; #pragma unroll
;             for (int r = 0; r < RB; ++r) { ss[r] = 0.f;
; #pragma unroll
;                 for (int j = 0; j < 4; ++j) ss[r] += mv[r][j][0] * mv[r][j][0] + mv[r][j][1] * mv[r][j][1] + mv[r][j][2] * mv[r][j][2] + mv[r][j][3] * mv[r][j][3]; }
; #pragma unroll
;             for (int o = 32; o >= 1; o >>= 1)
; #pragma unroll
;                 for (int r = 0; r < RB; ++r) ss[r] += shx(ss[r], o);
; #pragma unroll
;             for (int j = 0; j < 4; ++j) { const f32x4 g = *(const f32x4*)(g_post + lane * 4 + 256 * j);
; #pragma unroll
;                 for (int r = 0; r < RB; ++r) { const float r1 = rsqrtf(ss[r] * (1.f / DM) + EPS); xv[r][j] = xv[r][j] + mv[r][j] * r1 * g; *(f32x4*)(xdst + (size_t)(rowb + r) * DM + lane * 4 + 256 * j) = xv[r][j]; } }
	v_lshlrev_b32_e32 v208, 16, v176
	v_and_b32_e32 v209, 0xffff0000, v176
	v_lshlrev_b32_e32 v210, 16, v177
	v_and_b32_e32 v211, 0xffff0000, v177
	v_lshlrev_b32_e32 v212, 16, v178
	v_and_b32_e32 v213, 0xffff0000, v178
	v_lshlrev_b32_e32 v214, 16, v179
	v_and_b32_e32 v215, 0xffff0000, v179
	v_lshlrev_b32_e32 v216, 16, v180
	v_and_b32_e32 v217, 0xffff0000, v180
	v_lshlrev_b32_e32 v218, 16, v181
	v_and_b32_e32 v219, 0xffff0000, v181
	v_lshlrev_b32_e32 v220, 16, v182
	v_and_b32_e32 v221, 0xffff0000, v182
	v_lshlrev_b32_e32 v222, 16, v183
	v_and_b32_e32 v223, 0xffff0000, v183
	v_mul_f32_e32 v224, v208, v208
	v_fmac_f32_e32 v224, v209, v209
	v_fmac_f32_e32 v224, v210, v210
	v_fmac_f32_e32 v224, v211, v211
	v_fmac_f32_e32 v224, v212, v212
	v_fmac_f32_e32 v224, v213, v213
	v_fmac_f32_e32 v224, v214, v214
	v_fmac_f32_e32 v224, v215, v215
	v_fmac_f32_e32 v224, v216, v216
	v_fmac_f32_e32 v224, v217, v217
	v_fmac_f32_e32 v224, v218, v218
	v_fmac_f32_e32 v224, v219, v219
	v_fmac_f32_e32 v224, v220, v220
	v_fmac_f32_e32 v224, v221, v221
	v_fmac_f32_e32 v224, v222, v222
	v_fmac_f32_e32 v224, v223, v223
	s_nop 1
	v_add_f32_dpp v224, v224, v224 quad_perm:[1,0,3,2] row_mask:0xf bank_mask:0xf
	s_nop 1
	v_add_f32_dpp v224, v224, v224 quad_perm:[2,3,0,1] row_mask:0xf bank_mask:0xf
	s_nop 1
	v_add_f32_dpp v224, v224, v224 row_ror:4 row_mask:0xf bank_mask:0xf
	s_nop 1
	v_add_f32_dpp v224, v224, v224 row_ror:8 row_mask:0xf bank_mask:0xf
	s_nop 1
	v_readlane_b32 s20, v224, 0
	v_readlane_b32 s21, v224, 16
	v_readlane_b32 s22, v224, 32
	v_readlane_b32 s23, v224, 48
	s_nop 1
	v_mov_b32_e32 v225, s20
	v_add_f32_e32 v225, s21, v225
	v_add_f32_e32 v225, s22, v225
	v_add_f32_e32 v225, s23, v225
	v_mov_b32_e32 v226, 0x358637bd
	v_fmac_f32_e32 v226, 0x3a800000, v225
	v_rsq_f32_e32 v226, v226
	s_nop 0
	v_mul_f32_e32 v208, v208, v226
	v_mul_f32_e32 v209, v209, v226
	v_mul_f32_e32 v210, v210, v226
	v_mul_f32_e32 v211, v211, v226
	v_mul_f32_e32 v212, v212, v226
	v_mul_f32_e32 v213, v213, v226
	v_mul_f32_e32 v214, v214, v226
	v_mul_f32_e32 v215, v215, v226
	v_mul_f32_e32 v216, v216, v226
	v_mul_f32_e32 v217, v217, v226
	v_mul_f32_e32 v218, v218, v226
	v_mul_f32_e32 v219, v219, v226
	v_mul_f32_e32 v220, v220, v226
	v_mul_f32_e32 v221, v221, v226
	v_mul_f32_e32 v222, v222, v226
	v_mul_f32_e32 v223, v223, v226
	v_fmac_f32_e32 v160, v208, v40
	v_fmac_f32_e32 v161, v209, v41
	v_fmac_f32_e32 v162, v210, v42
	v_fmac_f32_e32 v163, v211, v43
	v_fmac_f32_e32 v164, v212, v44
	v_fmac_f32_e32 v165, v213, v45
	v_fmac_f32_e32 v166, v214, v46
	v_fmac_f32_e32 v167, v215, v47
	v_fmac_f32_e32 v168, v216, v48
	v_fmac_f32_e32 v169, v217, v49
	v_fmac_f32_e32 v170, v218, v50
	v_fmac_f32_e32 v171, v219, v51
	v_fmac_f32_e32 v172, v220, v52
	v_fmac_f32_e32 v173, v221, v53
	v_fmac_f32_e32 v174, v222, v54
	v_fmac_f32_e32 v175, v223, v55
	v_lshlrev_b32_e32 v208, 16, v184
	v_and_b32_e32 v209, 0xffff0000, v184
	v_lshlrev_b32_e32 v210, 16, v185
	v_and_b32_e32 v211, 0xffff0000, v185
	v_lshlrev_b32_e32 v212, 16, v186
	v_and_b32_e32 v213, 0xffff0000, v186
	v_lshlrev_b32_e32 v214, 16, v187
	v_and_b32_e32 v215, 0xffff0000, v187
	v_lshlrev_b32_e32 v216, 16, v188
	v_and_b32_e32 v217, 0xffff0000, v188
	v_lshlrev_b32_e32 v218, 16, v189
	v_and_b32_e32 v219, 0xffff0000, v189
	v_lshlrev_b32_e32 v220, 16, v190
	v_and_b32_e32 v221, 0xffff0000, v190
	v_lshlrev_b32_e32 v222, 16, v191
	v_and_b32_e32 v223, 0xffff0000, v191
	v_mul_f32_e32 v224, v208, v208
	v_fmac_f32_e32 v224, v209, v209
	v_fmac_f32_e32 v224, v210, v210
	v_fmac_f32_e32 v224, v211, v211
	v_fmac_f32_e32 v224, v212, v212
	v_fmac_f32_e32 v224, v213, v213
	v_fmac_f32_e32 v224, v214, v214
	v_fmac_f32_e32 v224, v215, v215
	v_fmac_f32_e32 v224, v216, v216
	v_fmac_f32_e32 v224, v217, v217
	v_fmac_f32_e32 v224, v218, v218
	v_fmac_f32_e32 v224, v219, v219
	v_fmac_f32_e32 v224, v220, v220
	v_fmac_f32_e32 v224, v221, v221
	v_fmac_f32_e32 v224, v222, v222
	v_fmac_f32_e32 v224, v223, v223
	s_nop 1
	v_add_f32_dpp v224, v224, v224 quad_perm:[1,0,3,2] row_mask:0xf bank_mask:0xf
	s_nop 1
	v_add_f32_dpp v224, v224, v224 quad_perm:[2,3,0,1] row_mask:0xf bank_mask:0xf
	s_nop 1
	v_add_f32_dpp v224, v224, v224 row_ror:4 row_mask:0xf bank_mask:0xf
	s_nop 1
	v_add_f32_dpp v224, v224, v224 row_ror:8 row_mask:0xf bank_mask:0xf
	s_nop 1
	v_readlane_b32 s20, v224, 0
	v_readlane_b32 s21, v224, 16
	v_readlane_b32 s22, v224, 32
	v_readlane_b32 s23, v224, 48
	s_nop 1
	v_mov_b32_e32 v225, s20
	v_add_f32_e32 v225, s21, v225
	v_add_f32_e32 v225, s22, v225
	v_add_f32_e32 v225, s23, v225
	v_mov_b32_e32 v226, 0x358637bd
	v_fmac_f32_e32 v226, 0x3a800000, v225
	v_rsq_f32_e32 v226, v226
	s_nop 0
	v_mul_f32_e32 v208, v208, v226
	v_mul_f32_e32 v209, v209, v226
	v_mul_f32_e32 v210, v210, v226
	v_mul_f32_e32 v211, v211, v226
	v_mul_f32_e32 v212, v212, v226
	v_mul_f32_e32 v213, v213, v226
	v_mul_f32_e32 v214, v214, v226
	v_mul_f32_e32 v215, v215, v226
	v_mul_f32_e32 v216, v216, v226
	v_mul_f32_e32 v217, v217, v226
	v_mul_f32_e32 v218, v218, v226
	v_mul_f32_e32 v219, v219, v226
	v_mul_f32_e32 v220, v220, v226
	v_mul_f32_e32 v221, v221, v226
	v_mul_f32_e32 v222, v222, v226
	v_mul_f32_e32 v223, v223, v226
	v_fmac_f32_e32 v160, v208, v56
	v_fmac_f32_e32 v161, v209, v57
	v_fmac_f32_e32 v162, v210, v58
	v_fmac_f32_e32 v163, v211, v59
	v_fmac_f32_e32 v164, v212, v60
	v_fmac_f32_e32 v165, v213, v61
	v_fmac_f32_e32 v166, v214, v62
	v_fmac_f32_e32 v167, v215, v63
	v_fmac_f32_e32 v168, v216, v64
	v_fmac_f32_e32 v169, v217, v65
	v_fmac_f32_e32 v170, v218, v66
	v_fmac_f32_e32 v171, v219, v67
	v_fmac_f32_e32 v172, v220, v68
	v_fmac_f32_e32 v173, v221, v69
	v_fmac_f32_e32 v174, v222, v70
	v_fmac_f32_e32 v175, v223, v71
; DI unsigned pk_bf16(float a, float b) { f32x2_t v = {a, b}; bf16x2_t r = __builtin_convertvector(v, bf16x2_t); return __builtin_bit_cast(unsigned, r); }
; DI float shx(float v, int mask) { const int l = olane(); return __builtin_bit_cast(float, __builtin_amdgcn_ds_bpermute(((l ^ mask) & 63) << 2, __builtin_bit_cast(int, v))); }
; DI void row_phase(const bf16_t* msrc, const float* xsrc, float* xdst, const float* g_post, const float* g_next, bf16_t* hdst, const int gw) {
;     ...
;             for (int j = 0; j < 4; ++j) { const f32x4 g = *(const f32x4*)(g_post + lane * 4 + 256 * j);
; #pragma unroll
;                 for (int r = 0; r < RB; ++r) { const float r1 = rsqrtf(ss[r] * (1.f / DM) + EPS); xv[r][j] = xv[r][j] + mv[r][j] * r1 * g; *(f32x4*)(xdst + (size_t)(rowb + r) * DM + lane * 4 + 256 * j) = xv[r][j]; } }
;         }
;         if (hdst) {
;             float ss[RB];
; #pragma unroll
;             for (int r = 0; r < RB; ++r) { ss[r] = 0.f;
; #pragma unroll
;                 for (int j = 0; j < 4; ++j) ss[r] += xv[r][j][0] * xv[r][j][0] + xv[r][j][1] * xv[r][j][1] + xv[r][j][2] * xv[r][j][2] + xv[r][j][3] * xv[r][j][3]; }
; #pragma unroll
;             for (int o = 32; o >= 1; o >>= 1)
; #pragma unroll
;                 for (int r = 0; r < RB; ++r) ss[r] += shx(ss[r], o);
; #pragma unroll
;             for (int j = 0; j < 4; ++j) { const f32x4 g = *(const f32x4*)(g_next + lane * 4 + 256 * j);
; #pragma unroll
;                 for (int r = 0; r < RB; ++r) { const float r2 = rsqrtf(ss[r] * (1.f / DM) + EPS); const f32x4 hv = xv[r][j] * r2 * g;
;                     u32x2 o; o[0] = pk_bf16(hv[0], hv[1]); o[1] = pk_bf16(hv[2], hv[3]); *(u32x2*)(hdst + (size_t)(rowb + r) * DM + lane * 4 + 256 * j) = o; } }
	global_store_dwordx4 v1, v[160:163], s[8:9] offset:0
	global_store_dwordx4 v1, v[164:167], s[8:9] offset:16
	global_store_dwordx4 v1, v[168:171], s[8:9] offset:2048
	global_store_dwordx4 v1, v[172:175], s[8:9] offset:2064
	s_add_u32 s8, s8, 0x1000
	s_addc_u32 s9, s9, 0
	v_mul_f32_e32 v224, v160, v160
	v_fmac_f32_e32 v224, v161, v161
	v_fmac_f32_e32 v224, v162, v162
	v_fmac_f32_e32 v224, v163, v163
	v_fmac_f32_e32 v224, v164, v164
	v_fmac_f32_e32 v224, v165, v165
	v_fmac_f32_e32 v224, v166, v166
	v_fmac_f32_e32 v224, v167, v167
	v_fmac_f32_e32 v224, v168, v168
	v_fmac_f32_e32 v224, v169, v169
	v_fmac_f32_e32 v224, v170, v170
	v_fmac_f32_e32 v224, v171, v171
	v_fmac_f32_e32 v224, v172, v172
	v_fmac_f32_e32 v224, v173, v173
	v_fmac_f32_e32 v224, v174, v174
	v_fmac_f32_e32 v224, v175, v175
	s_nop 1
	v_add_f32_dpp v224, v224, v224 quad_perm:[1,0,3,2] row_mask:0xf bank_mask:0xf
	s_nop 1
	v_add_f32_dpp v224, v224, v224 quad_perm:[2,3,0,1] row_mask:0xf bank_mask:0xf
	s_nop 1
	v_add_f32_dpp v224, v224, v224 row_ror:4 row_mask:0xf bank_mask:0xf
	s_nop 1
	v_add_f32_dpp v224, v224, v224 row_ror:8 row_mask:0xf bank_mask:0xf
	s_nop 1
	v_readlane_b32 s20, v224, 0
	v_readlane_b32 s21, v224, 16
	v_readlane_b32 s22, v224, 32
	v_readlane_b32 s23, v224, 48
	s_nop 1
	v_mov_b32_e32 v225, s20
	v_add_f32_e32 v225, s21, v225
	v_add_f32_e32 v225, s22, v225
	v_add_f32_e32 v225, s23, v225
	v_mov_b32_e32 v226, 0x358637bd
	v_fmac_f32_e32 v226, 0x3a800000, v225
	v_rsq_f32_e32 v226, v226
	s_nop 0
	v_mul_f32_e32 v208, v160, v226
	v_mul_f32_e32 v209, v161, v226
	v_mul_f32_e32 v210, v162, v226
	v_mul_f32_e32 v211, v163, v226
	v_mul_f32_e32 v212, v164, v226
	v_mul_f32_e32 v213, v165, v226
	v_mul_f32_e32 v214, v166, v226
	v_mul_f32_e32 v215, v167, v226
	v_mul_f32_e32 v216, v168, v226
	v_mul_f32_e32 v217, v169, v226
	v_mul_f32_e32 v218, v170, v226
	v_mul_f32_e32 v219, v171, v226
	v_mul_f32_e32 v220, v172, v226
	v_mul_f32_e32 v221, v173, v226
	v_mul_f32_e32 v222, v174, v226
	v_mul_f32_e32 v223, v175, v226
	v_mul_f32_e32 v208, v208, v72
	v_mul_f32_e32 v209, v209, v73
	v_mul_f32_e32 v210, v210, v74
	v_mul_f32_e32 v211, v211, v75
	v_mul_f32_e32 v212, v212, v76
	v_mul_f32_e32 v213, v213, v77
	v_mul_f32_e32 v214, v214, v78
	v_mul_f32_e32 v215, v215, v79
	v_mul_f32_e32 v216, v216, v80
	v_mul_f32_e32 v217, v217, v81
	v_mul_f32_e32 v218, v218, v82
	v_mul_f32_e32 v219, v219, v83
	v_mul_f32_e32 v220, v220, v84
	v_mul_f32_e32 v221, v221, v85
	v_mul_f32_e32 v222, v222, v86
	v_mul_f32_e32 v223, v223, v87
	v_cvt_pk_bf16_f32 v176, v208, v209
	v_cvt_pk_bf16_f32 v177, v210, v211
	v_cvt_pk_bf16_f32 v178, v212, v213
	v_cvt_pk_bf16_f32 v179, v214, v215
	v_cvt_pk_bf16_f32 v180, v216, v217
	v_cvt_pk_bf16_f32 v181, v218, v219
	v_cvt_pk_bf16_f32 v182, v220, v221
	v_cvt_pk_bf16_f32 v183, v222, v223
	global_store_dwordx4 v2, v[176:179], s[14:15]
	global_store_dwordx4 v2, v[180:183], s[14:15] offset:1024
	s_add_u32 s14, s14, 0x800
	s_addc_u32 s15, s15, 0
	s_waitcnt vmcnt(20)
	v_lshlrev_b32_e32 v208, 16, v112
	v_and_b32_e32 v209, 0xffff0000, v112
	v_lshlrev_b32_e32 v210, 16, v113
	v_and_b32_e32 v211, 0xffff0000, v113
	v_lshlrev_b32_e32 v212, 16, v114
	v_and_b32_e32 v213, 0xffff0000, v114
	v_lshlrev_b32_e32 v214, 16, v115
	v_and_b32_e32 v215, 0xffff0000, v115
	v_lshlrev_b32_e32 v216, 16, v116
	v_and_b32_e32 v217, 0xffff0000, v116
	v_lshlrev_b32_e32 v218, 16, v117
	v_and_b32_e32 v219, 0xffff0000, v117
	v_lshlrev_b32_e32 v220, 16, v118
	v_and_b32_e32 v221, 0xffff0000, v118
	v_lshlrev_b32_e32 v222, 16, v119
	v_and_b32_e32 v223, 0xffff0000, v119
	v_mul_f32_e32 v224, v208, v208
	v_fmac_f32_e32 v224, v209, v209
	v_fmac_f32_e32 v224, v210, v210
	v_fmac_f32_e32 v224, v211, v211
	v_fmac_f32_e32 v224, v212, v212
	v_fmac_f32_e32 v224, v213, v213
	v_fmac_f32_e32 v224, v214, v214
	v_fmac_f32_e32 v224, v215, v215
	v_fmac_f32_e32 v224, v216, v216
	v_fmac_f32_e32 v224, v217, v217
	v_fmac_f32_e32 v224, v218, v218
	v_fmac_f32_e32 v224, v219, v219
	v_fmac_f32_e32 v224, v220, v220
	v_fmac_f32_e32 v224, v221, v221
	v_fmac_f32_e32 v224, v222, v222
	v_fmac_f32_e32 v224, v223, v223
	s_nop 1
	v_add_f32_dpp v224, v224, v224 quad_perm:[1,0,3,2] row_mask:0xf bank_mask:0xf
	s_nop 1
	v_add_f32_dpp v224, v224, v224 quad_perm:[2,3,0,1] row_mask:0xf bank_mask:0xf
	s_nop 1
	v_add_f32_dpp v224, v224, v224 row_ror:4 row_mask:0xf bank_mask:0xf
	s_nop 1
	v_add_f32_dpp v224, v224, v224 row_ror:8 row_mask:0xf bank_mask:0xf
	s_nop 1
	v_readlane_b32 s20, v224, 0
	v_readlane_b32 s21, v224, 16
	v_readlane_b32 s22, v224, 32
	v_readlane_b32 s23, v224, 48
	s_nop 1
	v_mov_b32_e32 v225, s20
	v_add_f32_e32 v225, s21, v225
	v_add_f32_e32 v225, s22, v225
	v_add_f32_e32 v225, s23, v225
	v_mov_b32_e32 v226, 0x358637bd
	v_fmac_f32_e32 v226, 0x3a800000, v225
	v_rsq_f32_e32 v226, v226
	s_nop 0
	v_mul_f32_e32 v208, v208, v226
	v_mul_f32_e32 v209, v209, v226
	v_mul_f32_e32 v210, v210, v226
	v_mul_f32_e32 v211, v211, v226
	v_mul_f32_e32 v212, v212, v226
	v_mul_f32_e32 v213, v213, v226
	v_mul_f32_e32 v214, v214, v226
	v_mul_f32_e32 v215, v215, v226
	v_mul_f32_e32 v216, v216, v226
	v_mul_f32_e32 v217, v217, v226
	v_mul_f32_e32 v218, v218, v226
	v_mul_f32_e32 v219, v219, v226
	v_mul_f32_e32 v220, v220, v226
	v_mul_f32_e32 v221, v221, v226
	v_mul_f32_e32 v222, v222, v226
	v_mul_f32_e32 v223, v223, v226
	v_fmac_f32_e32 v96, v208, v40
	v_fmac_f32_e32 v97, v209, v41
	v_fmac_f32_e32 v98, v210, v42
	v_fmac_f32_e32 v99, v211, v43
	v_fmac_f32_e32 v100, v212, v44
	v_fmac_f32_e32 v101, v213, v45
	v_fmac_f32_e32 v102, v214, v46
	v_fmac_f32_e32 v103, v215, v47
	v_fmac_f32_e32 v104, v216, v48
	v_fmac_f32_e32 v105, v217, v49
	v_fmac_f32_e32 v106, v218, v50
	v_fmac_f32_e32 v107, v219, v51
; DI unsigned pk_bf16(float a, float b) { f32x2_t v = {a, b}; bf16x2_t r = __builtin_convertvector(v, bf16x2_t); return __builtin_bit_cast(unsigned, r); }
; DI float shx(float v, int mask) { const int l = olane(); return __builtin_bit_cast(float, __builtin_amdgcn_ds_bpermute(((l ^ mask) & 63) << 2, __builtin_bit_cast(int, v))); }
; DI void row_phase(const bf16_t* msrc, const float* xsrc, float* xdst, const float* g_post, const float* g_next, bf16_t* hdst, const int gw) {
;     ...
;                 for (int j = 0; j < 4; ++j) ss[r] += mv[r][j][0] * mv[r][j][0] + mv[r][j][1] * mv[r][j][1] + mv[r][j][2] * mv[r][j][2] + mv[r][j][3] * mv[r][j][3]; }
; #pragma unroll
;             for (int o = 32; o >= 1; o >>= 1)
; #pragma unroll
;                 for (int r = 0; r < RB; ++r) ss[r] += shx(ss[r], o);
; #pragma unroll
;             for (int j = 0; j < 4; ++j) { const f32x4 g = *(const f32x4*)(g_post + lane * 4 + 256 * j);
; #pragma unroll
;                 for (int r = 0; r < RB; ++r) { const float r1 = rsqrtf(ss[r] * (1.f / DM) + EPS); xv[r][j] = xv[r][j] + mv[r][j] * r1 * g; *(f32x4*)(xdst + (size_t)(rowb + r) * DM + lane * 4 + 256 * j) = xv[r][j]; } }
;         }
;         if (hdst) {
;             float ss[RB];
; #pragma unroll
;             for (int r = 0; r < RB; ++r) { ss[r] = 0.f;
; #pragma unroll
;                 for (int j = 0; j < 4; ++j) ss[r] += xv[r][j][0] * xv[r][j][0] + xv[r][j][1] * xv[r][j][1] + xv[r][j][2] * xv[r][j][2] + xv[r][j][3] * xv[r][j][3]; }
; #pragma unroll
;             for (int o = 32; o >= 1; o >>= 1)
; #pragma unroll
;                 for (int r = 0; r < RB; ++r) ss[r] += shx(ss[r], o);
; #pragma unroll
;             for (int j = 0; j < 4; ++j) { const f32x4 g = *(const f32x4*)(g_next + lane * 4 + 256 * j);
; #pragma unroll
;                 for (int r = 0; r < RB; ++r) { const float r2 = rsqrtf(ss[r] * (1.f / DM) + EPS); const f32x4 hv = xv[r][j] * r2 * g;
;                     u32x2 o; o[0] = pk_bf16(hv[0], hv[1]); o[1] = pk_bf16(hv[2], hv[3]); *(u32x2*)(hdst + (size_t)(rowb + r) * DM + lane * 4 + 256 * j) = o; } }
	v_fmac_f32_e32 v108, v220, v52
	v_fmac_f32_e32 v109, v221, v53
	v_fmac_f32_e32 v110, v222, v54
	v_fmac_f32_e32 v111, v223, v55
	v_lshlrev_b32_e32 v208, 16, v120
	v_and_b32_e32 v209, 0xffff0000, v120
	v_lshlrev_b32_e32 v210, 16, v121
	v_and_b32_e32 v211, 0xffff0000, v121
	v_lshlrev_b32_e32 v212, 16, v122
	v_and_b32_e32 v213, 0xffff0000, v122
	v_lshlrev_b32_e32 v214, 16, v123
	v_and_b32_e32 v215, 0xffff0000, v123
	v_lshlrev_b32_e32 v216, 16, v124
	v_and_b32_e32 v217, 0xffff0000, v124
	v_lshlrev_b32_e32 v218, 16, v125
	v_and_b32_e32 v219, 0xffff0000, v125
	v_lshlrev_b32_e32 v220, 16, v126
	v_and_b32_e32 v221, 0xffff0000, v126
	v_lshlrev_b32_e32 v222, 16, v127
	v_and_b32_e32 v223, 0xffff0000, v127
	v_mul_f32_e32 v224, v208, v208
	v_fmac_f32_e32 v224, v209, v209
	v_fmac_f32_e32 v224, v210, v210
	v_fmac_f32_e32 v224, v211, v211
	v_fmac_f32_e32 v224, v212, v212
	v_fmac_f32_e32 v224, v213, v213
	v_fmac_f32_e32 v224, v214, v214
	v_fmac_f32_e32 v224, v215, v215
	v_fmac_f32_e32 v224, v216, v216
	v_fmac_f32_e32 v224, v217, v217
	v_fmac_f32_e32 v224, v218, v218
	v_fmac_f32_e32 v224, v219, v219
	v_fmac_f32_e32 v224, v220, v220
	v_fmac_f32_e32 v224, v221, v221
	v_fmac_f32_e32 v224, v222, v222
	v_fmac_f32_e32 v224, v223, v223
	s_nop 1
	v_add_f32_dpp v224, v224, v224 quad_perm:[1,0,3,2] row_mask:0xf bank_mask:0xf
	s_nop 1
	v_add_f32_dpp v224, v224, v224 quad_perm:[2,3,0,1] row_mask:0xf bank_mask:0xf
	s_nop 1
	v_add_f32_dpp v224, v224, v224 row_ror:4 row_mask:0xf bank_mask:0xf
	s_nop 1
	v_add_f32_dpp v224, v224, v224 row_ror:8 row_mask:0xf bank_mask:0xf
	s_nop 1
	v_readlane_b32 s20, v224, 0
	v_readlane_b32 s21, v224, 16
	v_readlane_b32 s22, v224, 32
	v_readlane_b32 s23, v224, 48
	s_nop 1
	v_mov_b32_e32 v225, s20
	v_add_f32_e32 v225, s21, v225
	v_add_f32_e32 v225, s22, v225
	v_add_f32_e32 v225, s23, v225
	v_mov_b32_e32 v226, 0x358637bd
	v_fmac_f32_e32 v226, 0x3a800000, v225
	v_rsq_f32_e32 v226, v226
	s_nop 0
	v_mul_f32_e32 v208, v208, v226
	v_mul_f32_e32 v209, v209, v226
	v_mul_f32_e32 v210, v210, v226
	v_mul_f32_e32 v211, v211, v226
	v_mul_f32_e32 v212, v212, v226
	v_mul_f32_e32 v213, v213, v226
	v_mul_f32_e32 v214, v214, v226
	v_mul_f32_e32 v215, v215, v226
	v_mul_f32_e32 v216, v216, v226
	v_mul_f32_e32 v217, v217, v226
	v_mul_f32_e32 v218, v218, v226
	v_mul_f32_e32 v219, v219, v226
	v_mul_f32_e32 v220, v220, v226
	v_mul_f32_e32 v221, v221, v226
	v_mul_f32_e32 v222, v222, v226
	v_mul_f32_e32 v223, v223, v226
	v_fmac_f32_e32 v96, v208, v56
	v_fmac_f32_e32 v97, v209, v57
	v_fmac_f32_e32 v98, v210, v58
	v_fmac_f32_e32 v99, v211, v59
	v_fmac_f32_e32 v100, v212, v60
	v_fmac_f32_e32 v101, v213, v61
	v_fmac_f32_e32 v102, v214, v62
	v_fmac_f32_e32 v103, v215, v63
	v_fmac_f32_e32 v104, v216, v64
	v_fmac_f32_e32 v105, v217, v65
	v_fmac_f32_e32 v106, v218, v66
	v_fmac_f32_e32 v107, v219, v67
	v_fmac_f32_e32 v108, v220, v68
	v_fmac_f32_e32 v109, v221, v69
	v_fmac_f32_e32 v110, v222, v70
	v_fmac_f32_e32 v111, v223, v71
	global_store_dwordx4 v1, v[96:99], s[8:9] offset:0
	global_store_dwordx4 v1, v[100:103], s[8:9] offset:16
	global_store_dwordx4 v1, v[104:107], s[8:9] offset:2048
	global_store_dwordx4 v1, v[108:111], s[8:9] offset:2064
	s_add_u32 s8, s8, 0x1000
	s_addc_u32 s9, s9, 0
	v_mul_f32_e32 v224, v96, v96
	v_fmac_f32_e32 v224, v97, v97
	v_fmac_f32_e32 v224, v98, v98
	v_fmac_f32_e32 v224, v99, v99
	v_fmac_f32_e32 v224, v100, v100
	v_fmac_f32_e32 v224, v101, v101
	v_fmac_f32_e32 v224, v102, v102
	v_fmac_f32_e32 v224, v103, v103
	v_fmac_f32_e32 v224, v104, v104
	v_fmac_f32_e32 v224, v105, v105
	v_fmac_f32_e32 v224, v106, v106
	v_fmac_f32_e32 v224, v107, v107
	v_fmac_f32_e32 v224, v108, v108
	v_fmac_f32_e32 v224, v109, v109
	v_fmac_f32_e32 v224, v110, v110
	v_fmac_f32_e32 v224, v111, v111
	s_nop 1
	v_add_f32_dpp v224, v224, v224 quad_perm:[1,0,3,2] row_mask:0xf bank_mask:0xf
	s_nop 1
	v_add_f32_dpp v224, v224, v224 quad_perm:[2,3,0,1] row_mask:0xf bank_mask:0xf
	s_nop 1
	v_add_f32_dpp v224, v224, v224 row_ror:4 row_mask:0xf bank_mask:0xf
	s_nop 1
	v_add_f32_dpp v224, v224, v224 row_ror:8 row_mask:0xf bank_mask:0xf
	s_nop 1
	v_readlane_b32 s20, v224, 0
	v_readlane_b32 s21, v224, 16
	v_readlane_b32 s22, v224, 32
	v_readlane_b32 s23, v224, 48
	s_nop 1
	v_mov_b32_e32 v225, s20
	v_add_f32_e32 v225, s21, v225
	v_add_f32_e32 v225, s22, v225
	v_add_f32_e32 v225, s23, v225
	v_mov_b32_e32 v226, 0x358637bd
	v_fmac_f32_e32 v226, 0x3a800000, v225
	v_rsq_f32_e32 v226, v226
	s_nop 0
	v_mul_f32_e32 v208, v96, v226
	v_mul_f32_e32 v209, v97, v226
	v_mul_f32_e32 v210, v98, v226
	v_mul_f32_e32 v211, v99, v226
	v_mul_f32_e32 v212, v100, v226
	v_mul_f32_e32 v213, v101, v226
	v_mul_f32_e32 v214, v102, v226
	v_mul_f32_e32 v215, v103, v226
	v_mul_f32_e32 v216, v104, v226
	v_mul_f32_e32 v217, v105, v226
	v_mul_f32_e32 v218, v106, v226
	v_mul_f32_e32 v219, v107, v226
	v_mul_f32_e32 v220, v108, v226
	v_mul_f32_e32 v221, v109, v226
	v_mul_f32_e32 v222, v110, v226
	v_mul_f32_e32 v223, v111, v226
	v_mul_f32_e32 v208, v208, v72
	v_mul_f32_e32 v209, v209, v73
	v_mul_f32_e32 v210, v210, v74
	v_mul_f32_e32 v211, v211, v75
	v_mul_f32_e32 v212, v212, v76
	v_mul_f32_e32 v213, v213, v77
	v_mul_f32_e32 v214, v214, v78
	v_mul_f32_e32 v215, v215, v79
	v_mul_f32_e32 v216, v216, v80
	v_mul_f32_e32 v217, v217, v81
	v_mul_f32_e32 v218, v218, v82
	v_mul_f32_e32 v219, v219, v83
	v_mul_f32_e32 v220, v220, v84
	v_mul_f32_e32 v221, v221, v85
	v_mul_f32_e32 v222, v222, v86
	v_mul_f32_e32 v223, v223, v87
	v_cvt_pk_bf16_f32 v112, v208, v209
	v_cvt_pk_bf16_f32 v113, v210, v211
	v_cvt_pk_bf16_f32 v114, v212, v213
	v_cvt_pk_bf16_f32 v115, v214, v215
	v_cvt_pk_bf16_f32 v116, v216, v217
	v_cvt_pk_bf16_f32 v117, v218, v219
	v_cvt_pk_bf16_f32 v118, v220, v221
	v_cvt_pk_bf16_f32 v119, v222, v223
	global_store_dwordx4 v2, v[112:115], s[14:15]
	global_store_dwordx4 v2, v[116:119], s[14:15] offset:1024
	s_add_u32 s14, s14, 0x800
	s_addc_u32 s15, s15, 0
	s_waitcnt vmcnt(12)
; DI float shx(float v, int mask) { const int l = olane(); return __builtin_bit_cast(float, __builtin_amdgcn_ds_bpermute(((l ^ mask) & 63) << 2, __builtin_bit_cast(int, v))); }
; DI void row_phase(const bf16_t* msrc, const float* xsrc, float* xdst, const float* g_post, const float* g_next, bf16_t* hdst, const int gw) {
;     ...
;                 for (int j = 0; j < 4; ++j) { const u32x2 mw = *(const u32x2*)(msrc + (size_t)(rowb + r) * DM + lane * 4 + 256 * j);
;                     mv[r][j] = (f32x4){__uint_as_float(mw[0] << 16), __uint_as_float(mw[0] & 0xffff0000u), __uint_as_float(mw[1] << 16), __uint_as_float(mw[1] & 0xffff0000u)}; }
;             float ss[RB];
; #pragma unroll
;             for (int r = 0; r < RB; ++r) { ss[r] = 0.f;
; #pragma unroll
;                 for (int j = 0; j < 4; ++j) ss[r] += mv[r][j][0] * mv[r][j][0] + mv[r][j][1] * mv[r][j][1] + mv[r][j][2] * mv[r][j][2] + mv[r][j][3] * mv[r][j][3]; }
; #pragma unroll
;             for (int o = 32; o >= 1; o >>= 1)
; #pragma unroll
;                 for (int r = 0; r < RB; ++r) ss[r] += shx(ss[r], o);
; #pragma unroll
;             for (int j = 0; j < 4; ++j) { const f32x4 g = *(const f32x4*)(g_post + lane * 4 + 256 * j);
; #pragma unroll
;                 for (int r = 0; r < RB; ++r) { const float r1 = rsqrtf(ss[r] * (1.f / DM) + EPS); xv[r][j] = xv[r][j] + mv[r][j] * r1 * g; *(f32x4*)(xdst + (size_t)(rowb + r) * DM + lane * 4 + 256 * j) = xv[r][j]; } }
	v_lshlrev_b32_e32 v208, 16, v144
	v_and_b32_e32 v209, 0xffff0000, v144
	v_lshlrev_b32_e32 v210, 16, v145
	v_and_b32_e32 v211, 0xffff0000, v145
	v_lshlrev_b32_e32 v212, 16, v146
	v_and_b32_e32 v213, 0xffff0000, v146
	v_lshlrev_b32_e32 v214, 16, v147
	v_and_b32_e32 v215, 0xffff0000, v147
	v_lshlrev_b32_e32 v216, 16, v148
	v_and_b32_e32 v217, 0xffff0000, v148
	v_lshlrev_b32_e32 v218, 16, v149
	v_and_b32_e32 v219, 0xffff0000, v149
	v_lshlrev_b32_e32 v220, 16, v150
	v_and_b32_e32 v221, 0xffff0000, v150
	v_lshlrev_b32_e32 v222, 16, v151
	v_and_b32_e32 v223, 0xffff0000, v151
	v_mul_f32_e32 v224, v208, v208
	v_fmac_f32_e32 v224, v209, v209
	v_fmac_f32_e32 v224, v210, v210
	v_fmac_f32_e32 v224, v211, v211
	v_fmac_f32_e32 v224, v212, v212
	v_fmac_f32_e32 v224, v213, v213
	v_fmac_f32_e32 v224, v214, v214
	v_fmac_f32_e32 v224, v215, v215
	v_fmac_f32_e32 v224, v216, v216
	v_fmac_f32_e32 v224, v217, v217
	v_fmac_f32_e32 v224, v218, v218
	v_fmac_f32_e32 v224, v219, v219
	v_fmac_f32_e32 v224, v220, v220
	v_fmac_f32_e32 v224, v221, v221
	v_fmac_f32_e32 v224, v222, v222
	v_fmac_f32_e32 v224, v223, v223
	s_nop 1
	v_add_f32_dpp v224, v224, v224 quad_perm:[1,0,3,2] row_mask:0xf bank_mask:0xf
	s_nop 1
	v_add_f32_dpp v224, v224, v224 quad_perm:[2,3,0,1] row_mask:0xf bank_mask:0xf
	s_nop 1
	v_add_f32_dpp v224, v224, v224 row_ror:4 row_mask:0xf bank_mask:0xf
	s_nop 1
	v_add_f32_dpp v224, v224, v224 row_ror:8 row_mask:0xf bank_mask:0xf
	s_nop 1
	v_readlane_b32 s20, v224, 0
	v_readlane_b32 s21, v224, 16
	v_readlane_b32 s22, v224, 32
	v_readlane_b32 s23, v224, 48
	s_nop 1
	v_mov_b32_e32 v225, s20
	v_add_f32_e32 v225, s21, v225
	v_add_f32_e32 v225, s22, v225
	v_add_f32_e32 v225, s23, v225
	v_mov_b32_e32 v226, 0x358637bd
	v_fmac_f32_e32 v226, 0x3a800000, v225
	v_rsq_f32_e32 v226, v226
	s_nop 0
	v_mul_f32_e32 v208, v208, v226
	v_mul_f32_e32 v209, v209, v226
	v_mul_f32_e32 v210, v210, v226
	v_mul_f32_e32 v211, v211, v226
	v_mul_f32_e32 v212, v212, v226
	v_mul_f32_e32 v213, v213, v226
	v_mul_f32_e32 v214, v214, v226
	v_mul_f32_e32 v215, v215, v226
	v_mul_f32_e32 v216, v216, v226
	v_mul_f32_e32 v217, v217, v226
	v_mul_f32_e32 v218, v218, v226
	v_mul_f32_e32 v219, v219, v226
	v_mul_f32_e32 v220, v220, v226
	v_mul_f32_e32 v221, v221, v226
	v_mul_f32_e32 v222, v222, v226
	v_mul_f32_e32 v223, v223, v226
	v_fmac_f32_e32 v128, v208, v40
	v_fmac_f32_e32 v129, v209, v41
	v_fmac_f32_e32 v130, v210, v42
	v_fmac_f32_e32 v131, v211, v43
	v_fmac_f32_e32 v132, v212, v44
	v_fmac_f32_e32 v133, v213, v45
	v_fmac_f32_e32 v134, v214, v46
	v_fmac_f32_e32 v135, v215, v47
	v_fmac_f32_e32 v136, v216, v48
	v_fmac_f32_e32 v137, v217, v49
	v_fmac_f32_e32 v138, v218, v50
	v_fmac_f32_e32 v139, v219, v51
	v_fmac_f32_e32 v140, v220, v52
	v_fmac_f32_e32 v141, v221, v53
	v_fmac_f32_e32 v142, v222, v54
	v_fmac_f32_e32 v143, v223, v55
	v_lshlrev_b32_e32 v208, 16, v152
	v_and_b32_e32 v209, 0xffff0000, v152
	v_lshlrev_b32_e32 v210, 16, v153
	v_and_b32_e32 v211, 0xffff0000, v153
	v_lshlrev_b32_e32 v212, 16, v154
	v_and_b32_e32 v213, 0xffff0000, v154
	v_lshlrev_b32_e32 v214, 16, v155
	v_and_b32_e32 v215, 0xffff0000, v155
	v_lshlrev_b32_e32 v216, 16, v156
	v_and_b32_e32 v217, 0xffff0000, v156
	v_lshlrev_b32_e32 v218, 16, v157
	v_and_b32_e32 v219, 0xffff0000, v157
	v_lshlrev_b32_e32 v220, 16, v158
	v_and_b32_e32 v221, 0xffff0000, v158
	v_lshlrev_b32_e32 v222, 16, v159
	v_and_b32_e32 v223, 0xffff0000, v159
	v_mul_f32_e32 v224, v208, v208
	v_fmac_f32_e32 v224, v209, v209
	v_fmac_f32_e32 v224, v210, v210
	v_fmac_f32_e32 v224, v211, v211
	v_fmac_f32_e32 v224, v212, v212
	v_fmac_f32_e32 v224, v213, v213
	v_fmac_f32_e32 v224, v214, v214
	v_fmac_f32_e32 v224, v215, v215
	v_fmac_f32_e32 v224, v216, v216
	v_fmac_f32_e32 v224, v217, v217
	v_fmac_f32_e32 v224, v218, v218
	v_fmac_f32_e32 v224, v219, v219
	v_fmac_f32_e32 v224, v220, v220
	v_fmac_f32_e32 v224, v221, v221
	v_fmac_f32_e32 v224, v222, v222
	v_fmac_f32_e32 v224, v223, v223
	s_nop 1
	v_add_f32_dpp v224, v224, v224 quad_perm:[1,0,3,2] row_mask:0xf bank_mask:0xf
	s_nop 1
	v_add_f32_dpp v224, v224, v224 quad_perm:[2,3,0,1] row_mask:0xf bank_mask:0xf
	s_nop 1
	v_add_f32_dpp v224, v224, v224 row_ror:4 row_mask:0xf bank_mask:0xf
	s_nop 1
	v_add_f32_dpp v224, v224, v224 row_ror:8 row_mask:0xf bank_mask:0xf
	s_nop 1
	v_readlane_b32 s20, v224, 0
	v_readlane_b32 s21, v224, 16
	v_readlane_b32 s22, v224, 32
	v_readlane_b32 s23, v224, 48
	s_nop 1
	v_mov_b32_e32 v225, s20
	v_add_f32_e32 v225, s21, v225
	v_add_f32_e32 v225, s22, v225
	v_add_f32_e32 v225, s23, v225
	v_mov_b32_e32 v226, 0x358637bd
	v_fmac_f32_e32 v226, 0x3a800000, v225
	v_rsq_f32_e32 v226, v226
	s_nop 0
	v_mul_f32_e32 v208, v208, v226
	v_mul_f32_e32 v209, v209, v226
	v_mul_f32_e32 v210, v210, v226
	v_mul_f32_e32 v211, v211, v226
	v_mul_f32_e32 v212, v212, v226
	v_mul_f32_e32 v213, v213, v226
	v_mul_f32_e32 v214, v214, v226
	v_mul_f32_e32 v215, v215, v226
	v_mul_f32_e32 v216, v216, v226
	v_mul_f32_e32 v217, v217, v226
	v_mul_f32_e32 v218, v218, v226
	v_mul_f32_e32 v219, v219, v226
	v_mul_f32_e32 v220, v220, v226
	v_mul_f32_e32 v221, v221, v226
	v_mul_f32_e32 v222, v222, v226
	v_mul_f32_e32 v223, v223, v226
	v_fmac_f32_e32 v128, v208, v56
	v_fmac_f32_e32 v129, v209, v57
	v_fmac_f32_e32 v130, v210, v58
	v_fmac_f32_e32 v131, v211, v59
	v_fmac_f32_e32 v132, v212, v60
	v_fmac_f32_e32 v133, v213, v61
	v_fmac_f32_e32 v134, v214, v62
	v_fmac_f32_e32 v135, v215, v63
	v_fmac_f32_e32 v136, v216, v64
	v_fmac_f32_e32 v137, v217, v65
	v_fmac_f32_e32 v138, v218, v66
	v_fmac_f32_e32 v139, v219, v67
	v_fmac_f32_e32 v140, v220, v68
	v_fmac_f32_e32 v141, v221, v69
	v_fmac_f32_e32 v142, v222, v70
	v_fmac_f32_e32 v143, v223, v71
; DI unsigned pk_bf16(float a, float b) { f32x2_t v = {a, b}; bf16x2_t r = __builtin_convertvector(v, bf16x2_t); return __builtin_bit_cast(unsigned, r); }
; DI float shx(float v, int mask) { const int l = olane(); return __builtin_bit_cast(float, __builtin_amdgcn_ds_bpermute(((l ^ mask) & 63) << 2, __builtin_bit_cast(int, v))); }
; DI void row_phase(const bf16_t* msrc, const float* xsrc, float* xdst, const float* g_post, const float* g_next, bf16_t* hdst, const int gw) {
;     ...
;             for (int j = 0; j < 4; ++j) { const f32x4 g = *(const f32x4*)(g_post + lane * 4 + 256 * j);
; #pragma unroll
;                 for (int r = 0; r < RB; ++r) { const float r1 = rsqrtf(ss[r] * (1.f / DM) + EPS); xv[r][j] = xv[r][j] + mv[r][j] * r1 * g; *(f32x4*)(xdst + (size_t)(rowb + r) * DM + lane * 4 + 256 * j) = xv[r][j]; } }
;         }
;         if (hdst) {
;             float ss[RB];
; #pragma unroll
;             for (int r = 0; r < RB; ++r) { ss[r] = 0.f;
; #pragma unroll
;                 for (int j = 0; j < 4; ++j) ss[r] += xv[r][j][0] * xv[r][j][0] + xv[r][j][1] * xv[r][j][1] + xv[r][j][2] * xv[r][j][2] + xv[r][j][3] * xv[r][j][3]; }
; #pragma unroll
;             for (int o = 32; o >= 1; o >>= 1)
; #pragma unroll
;                 for (int r = 0; r < RB; ++r) ss[r] += shx(ss[r], o);
; #pragma unroll
;             for (int j = 0; j < 4; ++j) { const f32x4 g = *(const f32x4*)(g_next + lane * 4 + 256 * j);
; #pragma unroll
;                 for (int r = 0; r < RB; ++r) { const float r2 = rsqrtf(ss[r] * (1.f / DM) + EPS); const f32x4 hv = xv[r][j] * r2 * g;
;                     u32x2 o; o[0] = pk_bf16(hv[0], hv[1]); o[1] = pk_bf16(hv[2], hv[3]); *(u32x2*)(hdst + (size_t)(rowb + r) * DM + lane * 4 + 256 * j) = o; } }
	global_store_dwordx4 v1, v[128:131], s[8:9] offset:0
	global_store_dwordx4 v1, v[132:135], s[8:9] offset:16
	global_store_dwordx4 v1, v[136:139], s[8:9] offset:2048
	global_store_dwordx4 v1, v[140:143], s[8:9] offset:2064
	s_add_u32 s8, s8, 0x1000
	s_addc_u32 s9, s9, 0
	v_mul_f32_e32 v224, v128, v128
	v_fmac_f32_e32 v224, v129, v129
	v_fmac_f32_e32 v224, v130, v130
	v_fmac_f32_e32 v224, v131, v131
	v_fmac_f32_e32 v224, v132, v132
	v_fmac_f32_e32 v224, v133, v133
	v_fmac_f32_e32 v224, v134, v134
	v_fmac_f32_e32 v224, v135, v135
	v_fmac_f32_e32 v224, v136, v136
	v_fmac_f32_e32 v224, v137, v137
	v_fmac_f32_e32 v224, v138, v138
	v_fmac_f32_e32 v224, v139, v139
	v_fmac_f32_e32 v224, v140, v140
	v_fmac_f32_e32 v224, v141, v141
	v_fmac_f32_e32 v224, v142, v142
	v_fmac_f32_e32 v224, v143, v143
	s_nop 1
	v_add_f32_dpp v224, v224, v224 quad_perm:[1,0,3,2] row_mask:0xf bank_mask:0xf
	s_nop 1
	v_add_f32_dpp v224, v224, v224 quad_perm:[2,3,0,1] row_mask:0xf bank_mask:0xf
	s_nop 1
	v_add_f32_dpp v224, v224, v224 row_ror:4 row_mask:0xf bank_mask:0xf
	s_nop 1
	v_add_f32_dpp v224, v224, v224 row_ror:8 row_mask:0xf bank_mask:0xf
	s_nop 1
	v_readlane_b32 s20, v224, 0
	v_readlane_b32 s21, v224, 16
	v_readlane_b32 s22, v224, 32
	v_readlane_b32 s23, v224, 48
	s_nop 1
	v_mov_b32_e32 v225, s20
	v_add_f32_e32 v225, s21, v225
	v_add_f32_e32 v225, s22, v225
	v_add_f32_e32 v225, s23, v225
	v_mov_b32_e32 v226, 0x358637bd
	v_fmac_f32_e32 v226, 0x3a800000, v225
	v_rsq_f32_e32 v226, v226
	s_nop 0
	v_mul_f32_e32 v208, v128, v226
	v_mul_f32_e32 v209, v129, v226
	v_mul_f32_e32 v210, v130, v226
	v_mul_f32_e32 v211, v131, v226
	v_mul_f32_e32 v212, v132, v226
	v_mul_f32_e32 v213, v133, v226
	v_mul_f32_e32 v214, v134, v226
	v_mul_f32_e32 v215, v135, v226
	v_mul_f32_e32 v216, v136, v226
	v_mul_f32_e32 v217, v137, v226
	v_mul_f32_e32 v218, v138, v226
	v_mul_f32_e32 v219, v139, v226
	v_mul_f32_e32 v220, v140, v226
	v_mul_f32_e32 v221, v141, v226
	v_mul_f32_e32 v222, v142, v226
	v_mul_f32_e32 v223, v143, v226
	v_mul_f32_e32 v208, v208, v72
	v_mul_f32_e32 v209, v209, v73
	v_mul_f32_e32 v210, v210, v74
	v_mul_f32_e32 v211, v211, v75
	v_mul_f32_e32 v212, v212, v76
	v_mul_f32_e32 v213, v213, v77
	v_mul_f32_e32 v214, v214, v78
	v_mul_f32_e32 v215, v215, v79
	v_mul_f32_e32 v216, v216, v80
	v_mul_f32_e32 v217, v217, v81
	v_mul_f32_e32 v218, v218, v82
	v_mul_f32_e32 v219, v219, v83
	v_mul_f32_e32 v220, v220, v84
	v_mul_f32_e32 v221, v221, v85
	v_mul_f32_e32 v222, v222, v86
	v_mul_f32_e32 v223, v223, v87
	v_cvt_pk_bf16_f32 v144, v208, v209
	v_cvt_pk_bf16_f32 v145, v210, v211
	v_cvt_pk_bf16_f32 v146, v212, v213
	v_cvt_pk_bf16_f32 v147, v214, v215
	v_cvt_pk_bf16_f32 v148, v216, v217
	v_cvt_pk_bf16_f32 v149, v218, v219
	v_cvt_pk_bf16_f32 v150, v220, v221
	v_cvt_pk_bf16_f32 v151, v222, v223
	global_store_dwordx4 v2, v[144:147], s[14:15]
	global_store_dwordx4 v2, v[148:151], s[14:15] offset:1024
	s_add_u32 s14, s14, 0x800
	s_addc_u32 s15, s15, 0
	v_readlane_b32 s4, v3, 0
	v_readlane_b32 s5, v3, 1
	v_readlane_b32 s6, v3, 2
	v_readlane_b32 s7, v3, 3
	v_readlane_b32 s8, v3, 4
	v_readlane_b32 s9, v3, 5
	v_readlane_b32 s10, v3, 6
	v_readlane_b32 s11, v3, 7
	v_readlane_b32 s12, v3, 8
	v_readlane_b32 s13, v3, 9
	v_readlane_b32 s14, v3, 10
	v_readlane_b32 s15, v3, 11
	v_readlane_b32 s16, v3, 12
	v_readlane_b32 s17, v3, 13
	v_readlane_b32 s18, v3, 14
	v_readlane_b32 s19, v3, 15
	v_readlane_b32 s20, v3, 16
	v_readlane_b32 s21, v3, 17
	v_readlane_b32 s22, v3, 18
	v_readlane_b32 s23, v3, 19
	v_readlane_b32 s24, v3, 20
	v_readlane_b32 s25, v3, 21
	s_mov_b32 s6, 0x358637bd
	s_mov_b64 s[34:35], 0
	s_branch .LBB0_74
.Lrow_r2:
	v_writelane_b32 v3, s4, 0
	v_writelane_b32 v3, s5, 1
	v_writelane_b32 v3, s6, 2
	v_writelane_b32 v3, s7, 3
	v_writelane_b32 v3, s8, 4
	v_writelane_b32 v3, s9, 5
	v_writelane_b32 v3, s10, 6
	v_writelane_b32 v3, s11, 7
	v_writelane_b32 v3, s12, 8
	v_writelane_b32 v3, s13, 9
	v_writelane_b32 v3, s14, 10
	v_writelane_b32 v3, s15, 11
	v_writelane_b32 v3, s16, 12
	v_writelane_b32 v3, s17, 13
	v_writelane_b32 v3, s18, 14
	v_writelane_b32 v3, s19, 15
	v_writelane_b32 v3, s20, 16
	v_writelane_b32 v3, s21, 17
	v_writelane_b32 v3, s22, 18
	v_writelane_b32 v3, s23, 19
	v_writelane_b32 v3, s24, 20
	v_writelane_b32 v3, s25, 21
	s_waitcnt vmcnt(0) lgkmcnt(0)
; DI int obid() { int b = blockIdx.x; asm volatile("" : "+s"(b)); return b; }
; DI int ogrid() { int g = gridDim.x; asm volatile("" : "+s"(g)); return g; }
; DI int otid_w(int gw) { return (gw << 6) | olane(); }
; DI void row_phase(const bf16_t* msrc, const float* xsrc, float* xdst, const float* g_post, const float* g_next, bf16_t* hdst, const int gw) {
;     ...
;     const int tid = otid_w(gw); const int lane = tid & 63, w = tid >> 6;
;     const int wg = obid() * 8 + w, nw = ogrid() * 8;
;     for (int rowb = wg * RB; rowb < M_TOK; rowb += nw * RB) {
;         f32x4 xv[RB][4], mv[RB][4];
; #pragma unroll
;         for (int r = 0; r < RB; ++r)
; #pragma unroll
;             for (int j = 0; j < 4; ++j) xv[r][j] = *(const f32x4*)(xsrc + (size_t)(rowb + r) * DM + lane * 4 + 256 * j);
;         if (msrc) {
; #pragma unroll
;             for (int r = 0; r < RB; ++r)
; #pragma unroll
;                 for (int j = 0; j < 4; ++j) { const u32x2 mw = *(const u32x2*)(msrc + (size_t)(rowb + r) * DM + lane * 4 + 256 * j);
;                     mv[r][j] = (f32x4){__uint_as_float(mw[0] << 16), __uint_as_float(mw[0] & 0xffff0000u), __uint_as_float(mw[1] << 16), __uint_as_float(mw[1] & 0xffff0000u)}; }
;             float ss[RB];
; #pragma unroll
;             for (int r = 0; r < RB; ++r) { ss[r] = 0.f;
; #pragma unroll
;                 for (int j = 0; j < 4; ++j) ss[r] += mv[r][j][0] * mv[r][j][0] + mv[r][j][1] * mv[r][j][1] + mv[r][j][2] * mv[r][j][2] + mv[r][j][3] * mv[r][j][3]; }
	v_mbcnt_lo_u32_b32 v0, -1, 0
	v_mbcnt_hi_u32_b32 v0, -1, v0
	v_lshlrev_b32_e32 v1, 5, v0
	v_lshlrev_b32_e32 v2, 4, v0
	s_lshr_b32 s4, s71, 6
	s_and_b32 s5, s2, 7
	s_lshl_b32 s5, s5, 8
	s_lshr_b32 s24, s2, 3
	s_lshl_b32 s24, s24, 3
	s_add_i32 s5, s5, s24
	s_add_i32 s5, s5, s4
	s_lshl_b32 s24, s5, 15
	s_lshl_b32 s25, s5, 14
	v_readlane_b32 s8, v254, 62
	v_readlane_b32 s9, v254, 63
	v_readlane_b32 s6, v255, 2
	v_readlane_b32 s7, v255, 3
	v_readlane_b32 s4, v255, 6
	v_readlane_b32 s16, v255, 10
	v_readlane_b32 s17, v255, 11
	s_nop 1
	s_cmp_eq_u32 s4, 0
	s_cselect_b32 s6, s6, s8
	s_cselect_b32 s7, s7, s9
	s_add_u32 s6, s6, s24
	s_addc_u32 s7, s7, 0
	s_add_u32 s8, s8, s24
	s_addc_u32 s9, s9, 0
	s_add_u32 s10, s68, 0x10681000
	s_addc_u32 s11, s69, 0
	s_add_u32 s10, s10, s25
	s_addc_u32 s11, s11, 0
	s_add_u32 s12, s10, 0x2000000
	s_addc_u32 s13, s11, 0
	s_add_u32 s14, s82, s25
	s_addc_u32 s15, s83, 0
	s_add_u32 s18, s16, 0x1000
	s_addc_u32 s19, s17, 0
	global_load_dwordx4 v[40:43], v1, s[18:19] offset:0
	global_load_dwordx4 v[44:47], v1, s[18:19] offset:16
	global_load_dwordx4 v[48:51], v1, s[18:19] offset:2048
	global_load_dwordx4 v[52:55], v1, s[18:19] offset:2064
	s_add_u32 s18, s16, 0x3000
	s_addc_u32 s19, s17, 0
	global_load_dwordx4 v[56:59], v1, s[18:19] offset:0
	global_load_dwordx4 v[60:63], v1, s[18:19] offset:16
	global_load_dwordx4 v[64:67], v1, s[18:19] offset:2048
	global_load_dwordx4 v[68:71], v1, s[18:19] offset:2064
	global_load_dwordx4 v[96:99], v1, s[6:7] offset:0
	global_load_dwordx4 v[100:103], v1, s[6:7] offset:16
	global_load_dwordx4 v[104:107], v1, s[6:7] offset:2048
	global_load_dwordx4 v[108:111], v1, s[6:7] offset:2064
	global_load_dwordx4 v[112:115], v2, s[10:11]
	global_load_dwordx4 v[116:119], v2, s[10:11] offset:1024
	global_load_dwordx4 v[120:123], v2, s[12:13]
	global_load_dwordx4 v[124:127], v2, s[12:13] offset:1024
	s_add_u32 s6, s6, 0x1000
	s_addc_u32 s7, s7, 0
	s_add_u32 s10, s10, 0x800
	s_addc_u32 s11, s11, 0
	s_add_u32 s12, s12, 0x800
	s_addc_u32 s13, s13, 0
	global_load_dwordx4 v[128:131], v1, s[6:7] offset:0
	global_load_dwordx4 v[132:135], v1, s[6:7] offset:16
	global_load_dwordx4 v[136:139], v1, s[6:7] offset:2048
	global_load_dwordx4 v[140:143], v1, s[6:7] offset:2064
	global_load_dwordx4 v[144:147], v2, s[10:11]
	global_load_dwordx4 v[148:151], v2, s[10:11] offset:1024
	global_load_dwordx4 v[152:155], v2, s[12:13]
	global_load_dwordx4 v[156:159], v2, s[12:13] offset:1024
	s_add_u32 s6, s6, 0x1000
	s_addc_u32 s7, s7, 0
	s_add_u32 s10, s10, 0x800
	s_addc_u32 s11, s11, 0
	s_add_u32 s12, s12, 0x800
	s_addc_u32 s13, s13, 0
	global_load_dwordx4 v[160:163], v1, s[6:7] offset:0
	global_load_dwordx4 v[164:167], v1, s[6:7] offset:16
	global_load_dwordx4 v[168:171], v1, s[6:7] offset:2048
	global_load_dwordx4 v[172:175], v1, s[6:7] offset:2064
	global_load_dwordx4 v[176:179], v2, s[10:11]
	global_load_dwordx4 v[180:183], v2, s[10:11] offset:1024
	global_load_dwordx4 v[184:187], v2, s[12:13]
	global_load_dwordx4 v[188:191], v2, s[12:13] offset:1024
	s_add_u32 s6, s6, 0x1000
	s_addc_u32 s7, s7, 0
	s_add_u32 s10, s10, 0x800
	s_addc_u32 s11, s11, 0
	s_add_u32 s12, s12, 0x800
	s_addc_u32 s13, s13, 0
	s_waitcnt vmcnt(16)
	v_lshlrev_b32_e32 v208, 16, v112
	v_and_b32_e32 v209, 0xffff0000, v112
	v_lshlrev_b32_e32 v210, 16, v113
	v_and_b32_e32 v211, 0xffff0000, v113
	v_lshlrev_b32_e32 v212, 16, v114
	v_and_b32_e32 v213, 0xffff0000, v114
	v_lshlrev_b32_e32 v214, 16, v115
	v_and_b32_e32 v215, 0xffff0000, v115
	v_lshlrev_b32_e32 v216, 16, v116
	v_and_b32_e32 v217, 0xffff0000, v116
	v_lshlrev_b32_e32 v218, 16, v117
	v_and_b32_e32 v219, 0xffff0000, v117
	v_lshlrev_b32_e32 v220, 16, v118
	v_and_b32_e32 v221, 0xffff0000, v118
	v_lshlrev_b32_e32 v222, 16, v119
	v_and_b32_e32 v223, 0xffff0000, v119
	v_mul_f32_e32 v224, v208, v208
	v_fmac_f32_e32 v224, v209, v209
	v_fmac_f32_e32 v224, v210, v210
	v_fmac_f32_e32 v224, v211, v211
	v_fmac_f32_e32 v224, v212, v212
	v_fmac_f32_e32 v224, v213, v213
	v_fmac_f32_e32 v224, v214, v214
	v_fmac_f32_e32 v224, v215, v215
	v_fmac_f32_e32 v224, v216, v216
	v_fmac_f32_e32 v224, v217, v217
	v_fmac_f32_e32 v224, v218, v218
	v_fmac_f32_e32 v224, v219, v219
	v_fmac_f32_e32 v224, v220, v220
	v_fmac_f32_e32 v224, v221, v221
	v_fmac_f32_e32 v224, v222, v222
	v_fmac_f32_e32 v224, v223, v223
	s_nop 1
	v_add_f32_dpp v224, v224, v224 quad_perm:[1,0,3,2] row_mask:0xf bank_mask:0xf
	s_nop 1
	v_add_f32_dpp v224, v224, v224 quad_perm:[2,3,0,1] row_mask:0xf bank_mask:0xf
	s_nop 1
	v_add_f32_dpp v224, v224, v224 row_ror:4 row_mask:0xf bank_mask:0xf
	s_nop 1
	v_add_f32_dpp v224, v224, v224 row_ror:8 row_mask:0xf bank_mask:0xf
	s_nop 1
	v_readlane_b32 s20, v224, 0
	v_readlane_b32 s21, v224, 16
	v_readlane_b32 s22, v224, 32
	v_readlane_b32 s23, v224, 48
	s_nop 1
	v_mov_b32_e32 v225, s20
	v_add_f32_e32 v225, s21, v225
	v_add_f32_e32 v225, s22, v225
	v_add_f32_e32 v225, s23, v225
	v_mov_b32_e32 v226, 0x358637bd
	v_fmac_f32_e32 v226, 0x3a800000, v225
	v_rsq_f32_e32 v226, v226
	s_nop 0
	v_mul_f32_e32 v208, v208, v226
	v_mul_f32_e32 v209, v209, v226
	v_mul_f32_e32 v210, v210, v226
	v_mul_f32_e32 v211, v211, v226
	v_mul_f32_e32 v212, v212, v226
	v_mul_f32_e32 v213, v213, v226
	v_mul_f32_e32 v214, v214, v226
	v_mul_f32_e32 v215, v215, v226
	v_mul_f32_e32 v216, v216, v226
	v_mul_f32_e32 v217, v217, v226
	v_mul_f32_e32 v218, v218, v226
	v_mul_f32_e32 v219, v219, v226
	v_mul_f32_e32 v220, v220, v226
	v_mul_f32_e32 v221, v221, v226
	v_mul_f32_e32 v222, v222, v226
	v_mul_f32_e32 v223, v223, v226
	v_fmac_f32_e32 v96, v208, v40
	v_fmac_f32_e32 v97, v209, v41
	v_fmac_f32_e32 v98, v210, v42
	v_fmac_f32_e32 v99, v211, v43
; DI float shx(float v, int mask) { const int l = olane(); return __builtin_bit_cast(float, __builtin_amdgcn_ds_bpermute(((l ^ mask) & 63) << 2, __builtin_bit_cast(int, v))); }
; DI void row_phase(const bf16_t* msrc, const float* xsrc, float* xdst, const float* g_post, const float* g_next, bf16_t* hdst, const int gw) {
;     ...
;                 for (int j = 0; j < 4; ++j) { const u32x2 mw = *(const u32x2*)(msrc + (size_t)(rowb + r) * DM + lane * 4 + 256 * j);
;                     mv[r][j] = (f32x4){__uint_as_float(mw[0] << 16), __uint_as_float(mw[0] & 0xffff0000u), __uint_as_float(mw[1] << 16), __uint_as_float(mw[1] & 0xffff0000u)}; }
;             float ss[RB];
; #pragma unroll
;             for (int r = 0; r < RB; ++r) { ss[r] = 0.f;
; #pragma unroll
;                 for (int j = 0; j < 4; ++j) ss[r] += mv[r][j][0] * mv[r][j][0] + mv[r][j][1] * mv[r][j][1] + mv[r][j][2] * mv[r][j][2] + mv[r][j][3] * mv[r][j][3]; }
; #pragma unroll
;             for (int o = 32; o >= 1; o >>= 1)
; #pragma unroll
;                 for (int r = 0; r < RB; ++r) ss[r] += shx(ss[r], o);
; #pragma unroll
;             for (int j = 0; j < 4; ++j) { const f32x4 g = *(const f32x4*)(g_post + lane * 4 + 256 * j);
; #pragma unroll
;                 for (int r = 0; r < RB; ++r) { const float r1 = rsqrtf(ss[r] * (1.f / DM) + EPS); xv[r][j] = xv[r][j] + mv[r][j] * r1 * g; *(f32x4*)(xdst + (size_t)(rowb + r) * DM + lane * 4 + 256 * j) = xv[r][j]; } }
	v_fmac_f32_e32 v100, v212, v44
	v_fmac_f32_e32 v101, v213, v45
	v_fmac_f32_e32 v102, v214, v46
	v_fmac_f32_e32 v103, v215, v47
	v_fmac_f32_e32 v104, v216, v48
	v_fmac_f32_e32 v105, v217, v49
	v_fmac_f32_e32 v106, v218, v50
	v_fmac_f32_e32 v107, v219, v51
	v_fmac_f32_e32 v108, v220, v52
	v_fmac_f32_e32 v109, v221, v53
	v_fmac_f32_e32 v110, v222, v54
	v_fmac_f32_e32 v111, v223, v55
	v_lshlrev_b32_e32 v208, 16, v120
	v_and_b32_e32 v209, 0xffff0000, v120
	v_lshlrev_b32_e32 v210, 16, v121
	v_and_b32_e32 v211, 0xffff0000, v121
	v_lshlrev_b32_e32 v212, 16, v122
	v_and_b32_e32 v213, 0xffff0000, v122
	v_lshlrev_b32_e32 v214, 16, v123
	v_and_b32_e32 v215, 0xffff0000, v123
	v_lshlrev_b32_e32 v216, 16, v124
	v_and_b32_e32 v217, 0xffff0000, v124
	v_lshlrev_b32_e32 v218, 16, v125
	v_and_b32_e32 v219, 0xffff0000, v125
	v_lshlrev_b32_e32 v220, 16, v126
	v_and_b32_e32 v221, 0xffff0000, v126
	v_lshlrev_b32_e32 v222, 16, v127
	v_and_b32_e32 v223, 0xffff0000, v127
	v_mul_f32_e32 v224, v208, v208
	v_fmac_f32_e32 v224, v209, v209
	v_fmac_f32_e32 v224, v210, v210
	v_fmac_f32_e32 v224, v211, v211
	v_fmac_f32_e32 v224, v212, v212
	v_fmac_f32_e32 v224, v213, v213
	v_fmac_f32_e32 v224, v214, v214
	v_fmac_f32_e32 v224, v215, v215
	v_fmac_f32_e32 v224, v216, v216
	v_fmac_f32_e32 v224, v217, v217
	v_fmac_f32_e32 v224, v218, v218
	v_fmac_f32_e32 v224, v219, v219
	v_fmac_f32_e32 v224, v220, v220
	v_fmac_f32_e32 v224, v221, v221
	v_fmac_f32_e32 v224, v222, v222
	v_fmac_f32_e32 v224, v223, v223
	s_nop 1
	v_add_f32_dpp v224, v224, v224 quad_perm:[1,0,3,2] row_mask:0xf bank_mask:0xf
	s_nop 1
	v_add_f32_dpp v224, v224, v224 quad_perm:[2,3,0,1] row_mask:0xf bank_mask:0xf
	s_nop 1
	v_add_f32_dpp v224, v224, v224 row_ror:4 row_mask:0xf bank_mask:0xf
	s_nop 1
	v_add_f32_dpp v224, v224, v224 row_ror:8 row_mask:0xf bank_mask:0xf
	s_nop 1
	v_readlane_b32 s20, v224, 0
	v_readlane_b32 s21, v224, 16
	v_readlane_b32 s22, v224, 32
	v_readlane_b32 s23, v224, 48
	s_nop 1
	v_mov_b32_e32 v225, s20
	v_add_f32_e32 v225, s21, v225
	v_add_f32_e32 v225, s22, v225
	v_add_f32_e32 v225, s23, v225
	v_mov_b32_e32 v226, 0x358637bd
	v_fmac_f32_e32 v226, 0x3a800000, v225
	v_rsq_f32_e32 v226, v226
	s_nop 0
	v_mul_f32_e32 v208, v208, v226
	v_mul_f32_e32 v209, v209, v226
	v_mul_f32_e32 v210, v210, v226
	v_mul_f32_e32 v211, v211, v226
	v_mul_f32_e32 v212, v212, v226
	v_mul_f32_e32 v213, v213, v226
	v_mul_f32_e32 v214, v214, v226
	v_mul_f32_e32 v215, v215, v226
	v_mul_f32_e32 v216, v216, v226
	v_mul_f32_e32 v217, v217, v226
	v_mul_f32_e32 v218, v218, v226
	v_mul_f32_e32 v219, v219, v226
	v_mul_f32_e32 v220, v220, v226
	v_mul_f32_e32 v221, v221, v226
	v_mul_f32_e32 v222, v222, v226
	v_mul_f32_e32 v223, v223, v226
	v_fmac_f32_e32 v96, v208, v56
	v_fmac_f32_e32 v97, v209, v57
	v_fmac_f32_e32 v98, v210, v58
	v_fmac_f32_e32 v99, v211, v59
	v_fmac_f32_e32 v100, v212, v60
	v_fmac_f32_e32 v101, v213, v61
	v_fmac_f32_e32 v102, v214, v62
	v_fmac_f32_e32 v103, v215, v63
	v_fmac_f32_e32 v104, v216, v64
	v_fmac_f32_e32 v105, v217, v65
	v_fmac_f32_e32 v106, v218, v66
	v_fmac_f32_e32 v107, v219, v67
	v_fmac_f32_e32 v108, v220, v68
	v_fmac_f32_e32 v109, v221, v69
	v_fmac_f32_e32 v110, v222, v70
	v_fmac_f32_e32 v111, v223, v71
	global_store_dwordx4 v1, v[96:99], s[8:9] offset:0
	global_store_dwordx4 v1, v[100:103], s[8:9] offset:16
	global_store_dwordx4 v1, v[104:107], s[8:9] offset:2048
	global_store_dwordx4 v1, v[108:111], s[8:9] offset:2064
	s_add_u32 s8, s8, 0x1000
	s_addc_u32 s9, s9, 0
	global_load_dwordx4 v[96:99], v1, s[6:7] offset:0
	global_load_dwordx4 v[100:103], v1, s[6:7] offset:16
	global_load_dwordx4 v[104:107], v1, s[6:7] offset:2048
	global_load_dwordx4 v[108:111], v1, s[6:7] offset:2064
	global_load_dwordx4 v[112:115], v2, s[10:11]
	global_load_dwordx4 v[116:119], v2, s[10:11] offset:1024
	global_load_dwordx4 v[120:123], v2, s[12:13]
	global_load_dwordx4 v[124:127], v2, s[12:13] offset:1024
	s_add_u32 s6, s6, 0x1000
	s_addc_u32 s7, s7, 0
	s_add_u32 s10, s10, 0x800
	s_addc_u32 s11, s11, 0
	s_add_u32 s12, s12, 0x800
	s_addc_u32 s13, s13, 0
	s_waitcnt vmcnt(20)
	v_lshlrev_b32_e32 v208, 16, v144
	v_and_b32_e32 v209, 0xffff0000, v144
	v_lshlrev_b32_e32 v210, 16, v145
	v_and_b32_e32 v211, 0xffff0000, v145
	v_lshlrev_b32_e32 v212, 16, v146
	v_and_b32_e32 v213, 0xffff0000, v146
	v_lshlrev_b32_e32 v214, 16, v147
	v_and_b32_e32 v215, 0xffff0000, v147
	v_lshlrev_b32_e32 v216, 16, v148
	v_and_b32_e32 v217, 0xffff0000, v148
	v_lshlrev_b32_e32 v218, 16, v149
	v_and_b32_e32 v219, 0xffff0000, v149
	v_lshlrev_b32_e32 v220, 16, v150
	v_and_b32_e32 v221, 0xffff0000, v150
	v_lshlrev_b32_e32 v222, 16, v151
	v_and_b32_e32 v223, 0xffff0000, v151
	v_mul_f32_e32 v224, v208, v208
	v_fmac_f32_e32 v224, v209, v209
	v_fmac_f32_e32 v224, v210, v210
	v_fmac_f32_e32 v224, v211, v211
	v_fmac_f32_e32 v224, v212, v212
	v_fmac_f32_e32 v224, v213, v213
	v_fmac_f32_e32 v224, v214, v214
	v_fmac_f32_e32 v224, v215, v215
	v_fmac_f32_e32 v224, v216, v216
	v_fmac_f32_e32 v224, v217, v217
	v_fmac_f32_e32 v224, v218, v218
	v_fmac_f32_e32 v224, v219, v219
	v_fmac_f32_e32 v224, v220, v220
	v_fmac_f32_e32 v224, v221, v221
	v_fmac_f32_e32 v224, v222, v222
	v_fmac_f32_e32 v224, v223, v223
	s_nop 1
	v_add_f32_dpp v224, v224, v224 quad_perm:[1,0,3,2] row_mask:0xf bank_mask:0xf
	s_nop 1
	v_add_f32_dpp v224, v224, v224 quad_perm:[2,3,0,1] row_mask:0xf bank_mask:0xf
	s_nop 1
	v_add_f32_dpp v224, v224, v224 row_ror:4 row_mask:0xf bank_mask:0xf
	s_nop 1
	v_add_f32_dpp v224, v224, v224 row_ror:8 row_mask:0xf bank_mask:0xf
	s_nop 1
	v_readlane_b32 s20, v224, 0
	v_readlane_b32 s21, v224, 16
	v_readlane_b32 s22, v224, 32
	v_readlane_b32 s23, v224, 48
	s_nop 1
; DI float shx(float v, int mask) { const int l = olane(); return __builtin_bit_cast(float, __builtin_amdgcn_ds_bpermute(((l ^ mask) & 63) << 2, __builtin_bit_cast(int, v))); }
; DI void row_phase(const bf16_t* msrc, const float* xsrc, float* xdst, const float* g_post, const float* g_next, bf16_t* hdst, const int gw) {
;     ...
;                 for (int j = 0; j < 4; ++j) { const u32x2 mw = *(const u32x2*)(msrc + (size_t)(rowb + r) * DM + lane * 4 + 256 * j);
;                     mv[r][j] = (f32x4){__uint_as_float(mw[0] << 16), __uint_as_float(mw[0] & 0xffff0000u), __uint_as_float(mw[1] << 16), __uint_as_float(mw[1] & 0xffff0000u)}; }
;             float ss[RB];
; #pragma unroll
;             for (int r = 0; r < RB; ++r) { ss[r] = 0.f;
; #pragma unroll
;                 for (int j = 0; j < 4; ++j) ss[r] += mv[r][j][0] * mv[r][j][0] + mv[r][j][1] * mv[r][j][1] + mv[r][j][2] * mv[r][j][2] + mv[r][j][3] * mv[r][j][3]; }
; #pragma unroll
;             for (int o = 32; o >= 1; o >>= 1)
; #pragma unroll
;                 for (int r = 0; r < RB; ++r) ss[r] += shx(ss[r], o);
; #pragma unroll
;             for (int j = 0; j < 4; ++j) { const f32x4 g = *(const f32x4*)(g_post + lane * 4 + 256 * j);
; #pragma unroll
;                 for (int r = 0; r < RB; ++r) { const float r1 = rsqrtf(ss[r] * (1.f / DM) + EPS); xv[r][j] = xv[r][j] + mv[r][j] * r1 * g; *(f32x4*)(xdst + (size_t)(rowb + r) * DM + lane * 4 + 256 * j) = xv[r][j]; } }
	v_mov_b32_e32 v225, s20
	v_add_f32_e32 v225, s21, v225
	v_add_f32_e32 v225, s22, v225
	v_add_f32_e32 v225, s23, v225
	v_mov_b32_e32 v226, 0x358637bd
	v_fmac_f32_e32 v226, 0x3a800000, v225
	v_rsq_f32_e32 v226, v226
	s_nop 0
	v_mul_f32_e32 v208, v208, v226
	v_mul_f32_e32 v209, v209, v226
	v_mul_f32_e32 v210, v210, v226
	v_mul_f32_e32 v211, v211, v226
	v_mul_f32_e32 v212, v212, v226
	v_mul_f32_e32 v213, v213, v226
	v_mul_f32_e32 v214, v214, v226
	v_mul_f32_e32 v215, v215, v226
	v_mul_f32_e32 v216, v216, v226
	v_mul_f32_e32 v217, v217, v226
	v_mul_f32_e32 v218, v218, v226
	v_mul_f32_e32 v219, v219, v226
	v_mul_f32_e32 v220, v220, v226
	v_mul_f32_e32 v221, v221, v226
	v_mul_f32_e32 v222, v222, v226
	v_mul_f32_e32 v223, v223, v226
	v_fmac_f32_e32 v128, v208, v40
	v_fmac_f32_e32 v129, v209, v41
	v_fmac_f32_e32 v130, v210, v42
	v_fmac_f32_e32 v131, v211, v43
	v_fmac_f32_e32 v132, v212, v44
	v_fmac_f32_e32 v133, v213, v45
	v_fmac_f32_e32 v134, v214, v46
	v_fmac_f32_e32 v135, v215, v47
	v_fmac_f32_e32 v136, v216, v48
	v_fmac_f32_e32 v137, v217, v49
	v_fmac_f32_e32 v138, v218, v50
	v_fmac_f32_e32 v139, v219, v51
	v_fmac_f32_e32 v140, v220, v52
	v_fmac_f32_e32 v141, v221, v53
	v_fmac_f32_e32 v142, v222, v54
	v_fmac_f32_e32 v143, v223, v55
	v_lshlrev_b32_e32 v208, 16, v152
	v_and_b32_e32 v209, 0xffff0000, v152
	v_lshlrev_b32_e32 v210, 16, v153
	v_and_b32_e32 v211, 0xffff0000, v153
	v_lshlrev_b32_e32 v212, 16, v154
	v_and_b32_e32 v213, 0xffff0000, v154
	v_lshlrev_b32_e32 v214, 16, v155
	v_and_b32_e32 v215, 0xffff0000, v155
	v_lshlrev_b32_e32 v216, 16, v156
	v_and_b32_e32 v217, 0xffff0000, v156
	v_lshlrev_b32_e32 v218, 16, v157
	v_and_b32_e32 v219, 0xffff0000, v157
	v_lshlrev_b32_e32 v220, 16, v158
	v_and_b32_e32 v221, 0xffff0000, v158
	v_lshlrev_b32_e32 v222, 16, v159
	v_and_b32_e32 v223, 0xffff0000, v159
	v_mul_f32_e32 v224, v208, v208
	v_fmac_f32_e32 v224, v209, v209
	v_fmac_f32_e32 v224, v210, v210
	v_fmac_f32_e32 v224, v211, v211
	v_fmac_f32_e32 v224, v212, v212
	v_fmac_f32_e32 v224, v213, v213
	v_fmac_f32_e32 v224, v214, v214
	v_fmac_f32_e32 v224, v215, v215
	v_fmac_f32_e32 v224, v216, v216
	v_fmac_f32_e32 v224, v217, v217
	v_fmac_f32_e32 v224, v218, v218
	v_fmac_f32_e32 v224, v219, v219
	v_fmac_f32_e32 v224, v220, v220
	v_fmac_f32_e32 v224, v221, v221
	v_fmac_f32_e32 v224, v222, v222
	v_fmac_f32_e32 v224, v223, v223
	s_nop 1
	v_add_f32_dpp v224, v224, v224 quad_perm:[1,0,3,2] row_mask:0xf bank_mask:0xf
	s_nop 1
	v_add_f32_dpp v224, v224, v224 quad_perm:[2,3,0,1] row_mask:0xf bank_mask:0xf
	s_nop 1
	v_add_f32_dpp v224, v224, v224 row_ror:4 row_mask:0xf bank_mask:0xf
	s_nop 1
	v_add_f32_dpp v224, v224, v224 row_ror:8 row_mask:0xf bank_mask:0xf
	s_nop 1
	v_readlane_b32 s20, v224, 0
	v_readlane_b32 s21, v224, 16
	v_readlane_b32 s22, v224, 32
	v_readlane_b32 s23, v224, 48
	s_nop 1
	v_mov_b32_e32 v225, s20
	v_add_f32_e32 v225, s21, v225
	v_add_f32_e32 v225, s22, v225
	v_add_f32_e32 v225, s23, v225
	v_mov_b32_e32 v226, 0x358637bd
	v_fmac_f32_e32 v226, 0x3a800000, v225
	v_rsq_f32_e32 v226, v226
	s_nop 0
	v_mul_f32_e32 v208, v208, v226
	v_mul_f32_e32 v209, v209, v226
	v_mul_f32_e32 v210, v210, v226
	v_mul_f32_e32 v211, v211, v226
	v_mul_f32_e32 v212, v212, v226
	v_mul_f32_e32 v213, v213, v226
	v_mul_f32_e32 v214, v214, v226
	v_mul_f32_e32 v215, v215, v226
	v_mul_f32_e32 v216, v216, v226
	v_mul_f32_e32 v217, v217, v226
	v_mul_f32_e32 v218, v218, v226
	v_mul_f32_e32 v219, v219, v226
	v_mul_f32_e32 v220, v220, v226
	v_mul_f32_e32 v221, v221, v226
	v_mul_f32_e32 v222, v222, v226
	v_mul_f32_e32 v223, v223, v226
	v_fmac_f32_e32 v128, v208, v56
	v_fmac_f32_e32 v129, v209, v57
	v_fmac_f32_e32 v130, v210, v58
	v_fmac_f32_e32 v131, v211, v59
	v_fmac_f32_e32 v132, v212, v60
	v_fmac_f32_e32 v133, v213, v61
	v_fmac_f32_e32 v134, v214, v62
	v_fmac_f32_e32 v135, v215, v63
	v_fmac_f32_e32 v136, v216, v64
	v_fmac_f32_e32 v137, v217, v65
	v_fmac_f32_e32 v138, v218, v66
	v_fmac_f32_e32 v139, v219, v67
	v_fmac_f32_e32 v140, v220, v68
	v_fmac_f32_e32 v141, v221, v69
	v_fmac_f32_e32 v142, v222, v70
	v_fmac_f32_e32 v143, v223, v71
	global_store_dwordx4 v1, v[128:131], s[8:9] offset:0
	global_store_dwordx4 v1, v[132:135], s[8:9] offset:16
	global_store_dwordx4 v1, v[136:139], s[8:9] offset:2048
	global_store_dwordx4 v1, v[140:143], s[8:9] offset:2064
	s_add_u32 s8, s8, 0x1000
	s_addc_u32 s9, s9, 0
	global_load_dwordx4 v[128:131], v1, s[6:7] offset:0
	global_load_dwordx4 v[132:135], v1, s[6:7] offset:16
	global_load_dwordx4 v[136:139], v1, s[6:7] offset:2048
	global_load_dwordx4 v[140:143], v1, s[6:7] offset:2064
	global_load_dwordx4 v[144:147], v2, s[10:11]
	global_load_dwordx4 v[148:151], v2, s[10:11] offset:1024
	global_load_dwordx4 v[152:155], v2, s[12:13]
	global_load_dwordx4 v[156:159], v2, s[12:13] offset:1024
	s_add_u32 s6, s6, 0x1000
	s_addc_u32 s7, s7, 0
	s_add_u32 s10, s10, 0x800
	s_addc_u32 s11, s11, 0
	s_add_u32 s12, s12, 0x800
	s_addc_u32 s13, s13, 0
	s_waitcnt vmcnt(24)
; DI float shx(float v, int mask) { const int l = olane(); return __builtin_bit_cast(float, __builtin_amdgcn_ds_bpermute(((l ^ mask) & 63) << 2, __builtin_bit_cast(int, v))); }
; DI void row_phase(const bf16_t* msrc, const float* xsrc, float* xdst, const float* g_post, const float* g_next, bf16_t* hdst, const int gw) {
;     ...
;                 for (int j = 0; j < 4; ++j) { const u32x2 mw = *(const u32x2*)(msrc + (size_t)(rowb + r) * DM + lane * 4 + 256 * j);
;                     mv[r][j] = (f32x4){__uint_as_float(mw[0] << 16), __uint_as_float(mw[0] & 0xffff0000u), __uint_as_float(mw[1] << 16), __uint_as_float(mw[1] & 0xffff0000u)}; }
;             float ss[RB];
; #pragma unroll
;             for (int r = 0; r < RB; ++r) { ss[r] = 0.f;
; #pragma unroll
;                 for (int j = 0; j < 4; ++j) ss[r] += mv[r][j][0] * mv[r][j][0] + mv[r][j][1] * mv[r][j][1] + mv[r][j][2] * mv[r][j][2] + mv[r][j][3] * mv[r][j][3]; }
; #pragma unroll
;             for (int o = 32; o >= 1; o >>= 1)
; #pragma unroll
;                 for (int r = 0; r < RB; ++r) ss[r] += shx(ss[r], o);
; #pragma unroll
;             for (int j = 0; j < 4; ++j) { const f32x4 g = *(const f32x4*)(g_post + lane * 4 + 256 * j);
; #pragma unroll
;                 for (int r = 0; r < RB; ++r) { const float r1 = rsqrtf(ss[r] * (1.f / DM) + EPS); xv[r][j] = xv[r][j] + mv[r][j] * r1 * g; *(f32x4*)(xdst + (size_t)(rowb + r) * DM + lane * 4 + 256 * j) = xv[r][j]; } }
	v_lshlrev_b32_e32 v208, 16, v176
	v_and_b32_e32 v209, 0xffff0000, v176
	v_lshlrev_b32_e32 v210, 16, v177
	v_and_b32_e32 v211, 0xffff0000, v177
	v_lshlrev_b32_e32 v212, 16, v178
	v_and_b32_e32 v213, 0xffff0000, v178
	v_lshlrev_b32_e32 v214, 16, v179
	v_and_b32_e32 v215, 0xffff0000, v179
	v_lshlrev_b32_e32 v216, 16, v180
	v_and_b32_e32 v217, 0xffff0000, v180
	v_lshlrev_b32_e32 v218, 16, v181
	v_and_b32_e32 v219, 0xffff0000, v181
	v_lshlrev_b32_e32 v220, 16, v182
	v_and_b32_e32 v221, 0xffff0000, v182
	v_lshlrev_b32_e32 v222, 16, v183
	v_and_b32_e32 v223, 0xffff0000, v183
	v_mul_f32_e32 v224, v208, v208
	v_fmac_f32_e32 v224, v209, v209
	v_fmac_f32_e32 v224, v210, v210
	v_fmac_f32_e32 v224, v211, v211
	v_fmac_f32_e32 v224, v212, v212
	v_fmac_f32_e32 v224, v213, v213
	v_fmac_f32_e32 v224, v214, v214
	v_fmac_f32_e32 v224, v215, v215
	v_fmac_f32_e32 v224, v216, v216
	v_fmac_f32_e32 v224, v217, v217
	v_fmac_f32_e32 v224, v218, v218
	v_fmac_f32_e32 v224, v219, v219
	v_fmac_f32_e32 v224, v220, v220
	v_fmac_f32_e32 v224, v221, v221
	v_fmac_f32_e32 v224, v222, v222
	v_fmac_f32_e32 v224, v223, v223
	s_nop 1
	v_add_f32_dpp v224, v224, v224 quad_perm:[1,0,3,2] row_mask:0xf bank_mask:0xf
	s_nop 1
	v_add_f32_dpp v224, v224, v224 quad_perm:[2,3,0,1] row_mask:0xf bank_mask:0xf
	s_nop 1
	v_add_f32_dpp v224, v224, v224 row_ror:4 row_mask:0xf bank_mask:0xf
	s_nop 1
	v_add_f32_dpp v224, v224, v224 row_ror:8 row_mask:0xf bank_mask:0xf
	s_nop 1
	v_readlane_b32 s20, v224, 0
	v_readlane_b32 s21, v224, 16
	v_readlane_b32 s22, v224, 32
	v_readlane_b32 s23, v224, 48
	s_nop 1
	v_mov_b32_e32 v225, s20
	v_add_f32_e32 v225, s21, v225
	v_add_f32_e32 v225, s22, v225
	v_add_f32_e32 v225, s23, v225
	v_mov_b32_e32 v226, 0x358637bd
	v_fmac_f32_e32 v226, 0x3a800000, v225
	v_rsq_f32_e32 v226, v226
	s_nop 0
	v_mul_f32_e32 v208, v208, v226
	v_mul_f32_e32 v209, v209, v226
	v_mul_f32_e32 v210, v210, v226
	v_mul_f32_e32 v211, v211, v226
	v_mul_f32_e32 v212, v212, v226
	v_mul_f32_e32 v213, v213, v226
	v_mul_f32_e32 v214, v214, v226
	v_mul_f32_e32 v215, v215, v226
	v_mul_f32_e32 v216, v216, v226
	v_mul_f32_e32 v217, v217, v226
	v_mul_f32_e32 v218, v218, v226
	v_mul_f32_e32 v219, v219, v226
	v_mul_f32_e32 v220, v220, v226
	v_mul_f32_e32 v221, v221, v226
	v_mul_f32_e32 v222, v222, v226
	v_mul_f32_e32 v223, v223, v226
	v_fmac_f32_e32 v160, v208, v40
	v_fmac_f32_e32 v161, v209, v41
	v_fmac_f32_e32 v162, v210, v42
	v_fmac_f32_e32 v163, v211, v43
	v_fmac_f32_e32 v164, v212, v44
	v_fmac_f32_e32 v165, v213, v45
	v_fmac_f32_e32 v166, v214, v46
	v_fmac_f32_e32 v167, v215, v47
	v_fmac_f32_e32 v168, v216, v48
	v_fmac_f32_e32 v169, v217, v49
	v_fmac_f32_e32 v170, v218, v50
	v_fmac_f32_e32 v171, v219, v51
	v_fmac_f32_e32 v172, v220, v52
	v_fmac_f32_e32 v173, v221, v53
	v_fmac_f32_e32 v174, v222, v54
	v_fmac_f32_e32 v175, v223, v55
	v_lshlrev_b32_e32 v208, 16, v184
	v_and_b32_e32 v209, 0xffff0000, v184
	v_lshlrev_b32_e32 v210, 16, v185
	v_and_b32_e32 v211, 0xffff0000, v185
	v_lshlrev_b32_e32 v212, 16, v186
	v_and_b32_e32 v213, 0xffff0000, v186
	v_lshlrev_b32_e32 v214, 16, v187
	v_and_b32_e32 v215, 0xffff0000, v187
	v_lshlrev_b32_e32 v216, 16, v188
	v_and_b32_e32 v217, 0xffff0000, v188
	v_lshlrev_b32_e32 v218, 16, v189
	v_and_b32_e32 v219, 0xffff0000, v189
	v_lshlrev_b32_e32 v220, 16, v190
	v_and_b32_e32 v221, 0xffff0000, v190
	v_lshlrev_b32_e32 v222, 16, v191
	v_and_b32_e32 v223, 0xffff0000, v191
	v_mul_f32_e32 v224, v208, v208
	v_fmac_f32_e32 v224, v209, v209
	v_fmac_f32_e32 v224, v210, v210
	v_fmac_f32_e32 v224, v211, v211
	v_fmac_f32_e32 v224, v212, v212
	v_fmac_f32_e32 v224, v213, v213
	v_fmac_f32_e32 v224, v214, v214
	v_fmac_f32_e32 v224, v215, v215
	v_fmac_f32_e32 v224, v216, v216
	v_fmac_f32_e32 v224, v217, v217
	v_fmac_f32_e32 v224, v218, v218
	v_fmac_f32_e32 v224, v219, v219
	v_fmac_f32_e32 v224, v220, v220
	v_fmac_f32_e32 v224, v221, v221
	v_fmac_f32_e32 v224, v222, v222
	v_fmac_f32_e32 v224, v223, v223
	s_nop 1
	v_add_f32_dpp v224, v224, v224 quad_perm:[1,0,3,2] row_mask:0xf bank_mask:0xf
	s_nop 1
	v_add_f32_dpp v224, v224, v224 quad_perm:[2,3,0,1] row_mask:0xf bank_mask:0xf
	s_nop 1
	v_add_f32_dpp v224, v224, v224 row_ror:4 row_mask:0xf bank_mask:0xf
	s_nop 1
	v_add_f32_dpp v224, v224, v224 row_ror:8 row_mask:0xf bank_mask:0xf
	s_nop 1
	v_readlane_b32 s20, v224, 0
	v_readlane_b32 s21, v224, 16
	v_readlane_b32 s22, v224, 32
	v_readlane_b32 s23, v224, 48
	s_nop 1
	v_mov_b32_e32 v225, s20
	v_add_f32_e32 v225, s21, v225
	v_add_f32_e32 v225, s22, v225
	v_add_f32_e32 v225, s23, v225
	v_mov_b32_e32 v226, 0x358637bd
	v_fmac_f32_e32 v226, 0x3a800000, v225
	v_rsq_f32_e32 v226, v226
	s_nop 0
	v_mul_f32_e32 v208, v208, v226
	v_mul_f32_e32 v209, v209, v226
	v_mul_f32_e32 v210, v210, v226
	v_mul_f32_e32 v211, v211, v226
	v_mul_f32_e32 v212, v212, v226
	v_mul_f32_e32 v213, v213, v226
	v_mul_f32_e32 v214, v214, v226
	v_mul_f32_e32 v215, v215, v226
	v_mul_f32_e32 v216, v216, v226
	v_mul_f32_e32 v217, v217, v226
	v_mul_f32_e32 v218, v218, v226
	v_mul_f32_e32 v219, v219, v226
	v_mul_f32_e32 v220, v220, v226
	v_mul_f32_e32 v221, v221, v226
	v_mul_f32_e32 v222, v222, v226
	v_mul_f32_e32 v223, v223, v226
	v_fmac_f32_e32 v160, v208, v56
	v_fmac_f32_e32 v161, v209, v57
	v_fmac_f32_e32 v162, v210, v58
	v_fmac_f32_e32 v163, v211, v59
	v_fmac_f32_e32 v164, v212, v60
	v_fmac_f32_e32 v165, v213, v61
	v_fmac_f32_e32 v166, v214, v62
	v_fmac_f32_e32 v167, v215, v63
	v_fmac_f32_e32 v168, v216, v64
	v_fmac_f32_e32 v169, v217, v65
	v_fmac_f32_e32 v170, v218, v66
	v_fmac_f32_e32 v171, v219, v67
	v_fmac_f32_e32 v172, v220, v68
	v_fmac_f32_e32 v173, v221, v69
	v_fmac_f32_e32 v174, v222, v70
	v_fmac_f32_e32 v175, v223, v71
	global_store_dwordx4 v1, v[160:163], s[8:9] offset:0
	global_store_dwordx4 v1, v[164:167], s[8:9] offset:16
	global_store_dwordx4 v1, v[168:171], s[8:9] offset:2048
	global_store_dwordx4 v1, v[172:175], s[8:9] offset:2064
	s_add_u32 s8, s8, 0x1000
	s_addc_u32 s9, s9, 0
	global_load_dwordx4 v[160:163], v1, s[6:7] offset:0
	global_load_dwordx4 v[164:167], v1, s[6:7] offset:16
	global_load_dwordx4 v[168:171], v1, s[6:7] offset:2048
	global_load_dwordx4 v[172:175], v1, s[6:7] offset:2064
	global_load_dwordx4 v[176:179], v2, s[10:11]
	global_load_dwordx4 v[180:183], v2, s[10:11] offset:1024
	global_load_dwordx4 v[184:187], v2, s[12:13]
	global_load_dwordx4 v[188:191], v2, s[12:13] offset:1024
	s_add_u32 s6, s6, 0x1000
	s_addc_u32 s7, s7, 0
	s_add_u32 s10, s10, 0x800
	s_addc_u32 s11, s11, 0
	s_add_u32 s12, s12, 0x800
	s_addc_u32 s13, s13, 0
	s_waitcnt vmcnt(24)
; DI float shx(float v, int mask) { const int l = olane(); return __builtin_bit_cast(float, __builtin_amdgcn_ds_bpermute(((l ^ mask) & 63) << 2, __builtin_bit_cast(int, v))); }
; DI void row_phase(const bf16_t* msrc, const float* xsrc, float* xdst, const float* g_post, const float* g_next, bf16_t* hdst, const int gw) {
;     ...
;                 for (int j = 0; j < 4; ++j) { const u32x2 mw = *(const u32x2*)(msrc + (size_t)(rowb + r) * DM + lane * 4 + 256 * j);
;                     mv[r][j] = (f32x4){__uint_as_float(mw[0] << 16), __uint_as_float(mw[0] & 0xffff0000u), __uint_as_float(mw[1] << 16), __uint_as_float(mw[1] & 0xffff0000u)}; }
;             float ss[RB];
; #pragma unroll
;             for (int r = 0; r < RB; ++r) { ss[r] = 0.f;
; #pragma unroll
;                 for (int j = 0; j < 4; ++j) ss[r] += mv[r][j][0] * mv[r][j][0] + mv[r][j][1] * mv[r][j][1] + mv[r][j][2] * mv[r][j][2] + mv[r][j][3] * mv[r][j][3]; }
; #pragma unroll
;             for (int o = 32; o >= 1; o >>= 1)
; #pragma unroll
;                 for (int r = 0; r < RB; ++r) ss[r] += shx(ss[r], o);
; #pragma unroll
;             for (int j = 0; j < 4; ++j) { const f32x4 g = *(const f32x4*)(g_post + lane * 4 + 256 * j);
; #pragma unroll
;                 for (int r = 0; r < RB; ++r) { const float r1 = rsqrtf(ss[r] * (1.f / DM) + EPS); xv[r][j] = xv[r][j] + mv[r][j] * r1 * g; *(f32x4*)(xdst + (size_t)(rowb + r) * DM + lane * 4 + 256 * j) = xv[r][j]; } }
	v_lshlrev_b32_e32 v208, 16, v112
	v_and_b32_e32 v209, 0xffff0000, v112
	v_lshlrev_b32_e32 v210, 16, v113
	v_and_b32_e32 v211, 0xffff0000, v113
	v_lshlrev_b32_e32 v212, 16, v114
	v_and_b32_e32 v213, 0xffff0000, v114
	v_lshlrev_b32_e32 v214, 16, v115
	v_and_b32_e32 v215, 0xffff0000, v115
	v_lshlrev_b32_e32 v216, 16, v116
	v_and_b32_e32 v217, 0xffff0000, v116
	v_lshlrev_b32_e32 v218, 16, v117
	v_and_b32_e32 v219, 0xffff0000, v117
	v_lshlrev_b32_e32 v220, 16, v118
	v_and_b32_e32 v221, 0xffff0000, v118
	v_lshlrev_b32_e32 v222, 16, v119
	v_and_b32_e32 v223, 0xffff0000, v119
	v_mul_f32_e32 v224, v208, v208
	v_fmac_f32_e32 v224, v209, v209
	v_fmac_f32_e32 v224, v210, v210
	v_fmac_f32_e32 v224, v211, v211
	v_fmac_f32_e32 v224, v212, v212
	v_fmac_f32_e32 v224, v213, v213
	v_fmac_f32_e32 v224, v214, v214
	v_fmac_f32_e32 v224, v215, v215
	v_fmac_f32_e32 v224, v216, v216
	v_fmac_f32_e32 v224, v217, v217
	v_fmac_f32_e32 v224, v218, v218
	v_fmac_f32_e32 v224, v219, v219
	v_fmac_f32_e32 v224, v220, v220
	v_fmac_f32_e32 v224, v221, v221
	v_fmac_f32_e32 v224, v222, v222
	v_fmac_f32_e32 v224, v223, v223
	s_nop 1
	v_add_f32_dpp v224, v224, v224 quad_perm:[1,0,3,2] row_mask:0xf bank_mask:0xf
	s_nop 1
	v_add_f32_dpp v224, v224, v224 quad_perm:[2,3,0,1] row_mask:0xf bank_mask:0xf
	s_nop 1
	v_add_f32_dpp v224, v224, v224 row_ror:4 row_mask:0xf bank_mask:0xf
	s_nop 1
	v_add_f32_dpp v224, v224, v224 row_ror:8 row_mask:0xf bank_mask:0xf
	s_nop 1
	v_readlane_b32 s20, v224, 0
	v_readlane_b32 s21, v224, 16
	v_readlane_b32 s22, v224, 32
	v_readlane_b32 s23, v224, 48
	s_nop 1
	v_mov_b32_e32 v225, s20
	v_add_f32_e32 v225, s21, v225
	v_add_f32_e32 v225, s22, v225
	v_add_f32_e32 v225, s23, v225
	v_mov_b32_e32 v226, 0x358637bd
	v_fmac_f32_e32 v226, 0x3a800000, v225
	v_rsq_f32_e32 v226, v226
	s_nop 0
	v_mul_f32_e32 v208, v208, v226
	v_mul_f32_e32 v209, v209, v226
	v_mul_f32_e32 v210, v210, v226
	v_mul_f32_e32 v211, v211, v226
	v_mul_f32_e32 v212, v212, v226
	v_mul_f32_e32 v213, v213, v226
	v_mul_f32_e32 v214, v214, v226
	v_mul_f32_e32 v215, v215, v226
	v_mul_f32_e32 v216, v216, v226
	v_mul_f32_e32 v217, v217, v226
	v_mul_f32_e32 v218, v218, v226
	v_mul_f32_e32 v219, v219, v226
	v_mul_f32_e32 v220, v220, v226
	v_mul_f32_e32 v221, v221, v226
	v_mul_f32_e32 v222, v222, v226
	v_mul_f32_e32 v223, v223, v226
	v_fmac_f32_e32 v96, v208, v40
	v_fmac_f32_e32 v97, v209, v41
	v_fmac_f32_e32 v98, v210, v42
	v_fmac_f32_e32 v99, v211, v43
	v_fmac_f32_e32 v100, v212, v44
	v_fmac_f32_e32 v101, v213, v45
	v_fmac_f32_e32 v102, v214, v46
	v_fmac_f32_e32 v103, v215, v47
	v_fmac_f32_e32 v104, v216, v48
	v_fmac_f32_e32 v105, v217, v49
	v_fmac_f32_e32 v106, v218, v50
	v_fmac_f32_e32 v107, v219, v51
	v_fmac_f32_e32 v108, v220, v52
	v_fmac_f32_e32 v109, v221, v53
	v_fmac_f32_e32 v110, v222, v54
	v_fmac_f32_e32 v111, v223, v55
	v_lshlrev_b32_e32 v208, 16, v120
	v_and_b32_e32 v209, 0xffff0000, v120
	v_lshlrev_b32_e32 v210, 16, v121
	v_and_b32_e32 v211, 0xffff0000, v121
	v_lshlrev_b32_e32 v212, 16, v122
	v_and_b32_e32 v213, 0xffff0000, v122
	v_lshlrev_b32_e32 v214, 16, v123
	v_and_b32_e32 v215, 0xffff0000, v123
	v_lshlrev_b32_e32 v216, 16, v124
	v_and_b32_e32 v217, 0xffff0000, v124
	v_lshlrev_b32_e32 v218, 16, v125
	v_and_b32_e32 v219, 0xffff0000, v125
	v_lshlrev_b32_e32 v220, 16, v126
	v_and_b32_e32 v221, 0xffff0000, v126
	v_lshlrev_b32_e32 v222, 16, v127
	v_and_b32_e32 v223, 0xffff0000, v127
	v_mul_f32_e32 v224, v208, v208
	v_fmac_f32_e32 v224, v209, v209
	v_fmac_f32_e32 v224, v210, v210
	v_fmac_f32_e32 v224, v211, v211
	v_fmac_f32_e32 v224, v212, v212
	v_fmac_f32_e32 v224, v213, v213
	v_fmac_f32_e32 v224, v214, v214
	v_fmac_f32_e32 v224, v215, v215
	v_fmac_f32_e32 v224, v216, v216
	v_fmac_f32_e32 v224, v217, v217
	v_fmac_f32_e32 v224, v218, v218
	v_fmac_f32_e32 v224, v219, v219
	v_fmac_f32_e32 v224, v220, v220
	v_fmac_f32_e32 v224, v221, v221
	v_fmac_f32_e32 v224, v222, v222
	v_fmac_f32_e32 v224, v223, v223
	s_nop 1
	v_add_f32_dpp v224, v224, v224 quad_perm:[1,0,3,2] row_mask:0xf bank_mask:0xf
	s_nop 1
	v_add_f32_dpp v224, v224, v224 quad_perm:[2,3,0,1] row_mask:0xf bank_mask:0xf
	s_nop 1
	v_add_f32_dpp v224, v224, v224 row_ror:4 row_mask:0xf bank_mask:0xf
	s_nop 1
	v_add_f32_dpp v224, v224, v224 row_ror:8 row_mask:0xf bank_mask:0xf
	s_nop 1
	v_readlane_b32 s20, v224, 0
	v_readlane_b32 s21, v224, 16
	v_readlane_b32 s22, v224, 32
	v_readlane_b32 s23, v224, 48
	s_nop 1
	v_mov_b32_e32 v225, s20
	v_add_f32_e32 v225, s21, v225
	v_add_f32_e32 v225, s22, v225
	v_add_f32_e32 v225, s23, v225
	v_mov_b32_e32 v226, 0x358637bd
	v_fmac_f32_e32 v226, 0x3a800000, v225
	v_rsq_f32_e32 v226, v226
	s_nop 0
	v_mul_f32_e32 v208, v208, v226
	v_mul_f32_e32 v209, v209, v226
	v_mul_f32_e32 v210, v210, v226
	v_mul_f32_e32 v211, v211, v226
	v_mul_f32_e32 v212, v212, v226
	v_mul_f32_e32 v213, v213, v226
	v_mul_f32_e32 v214, v214, v226
	v_mul_f32_e32 v215, v215, v226
	v_mul_f32_e32 v216, v216, v226
	v_mul_f32_e32 v217, v217, v226
	v_mul_f32_e32 v218, v218, v226
	v_mul_f32_e32 v219, v219, v226
	v_mul_f32_e32 v220, v220, v226
	v_mul_f32_e32 v221, v221, v226
	v_mul_f32_e32 v222, v222, v226
	v_mul_f32_e32 v223, v223, v226
	v_fmac_f32_e32 v96, v208, v56
	v_fmac_f32_e32 v97, v209, v57
	v_fmac_f32_e32 v98, v210, v58
	v_fmac_f32_e32 v99, v211, v59
	v_fmac_f32_e32 v100, v212, v60
	v_fmac_f32_e32 v101, v213, v61
	v_fmac_f32_e32 v102, v214, v62
	v_fmac_f32_e32 v103, v215, v63
	v_fmac_f32_e32 v104, v216, v64
	v_fmac_f32_e32 v105, v217, v65
	v_fmac_f32_e32 v106, v218, v66
	v_fmac_f32_e32 v107, v219, v67
	v_fmac_f32_e32 v108, v220, v68
	v_fmac_f32_e32 v109, v221, v69
	v_fmac_f32_e32 v110, v222, v70
	v_fmac_f32_e32 v111, v223, v71
	global_store_dwordx4 v1, v[96:99], s[8:9] offset:0
	global_store_dwordx4 v1, v[100:103], s[8:9] offset:16
	global_store_dwordx4 v1, v[104:107], s[8:9] offset:2048
	global_store_dwordx4 v1, v[108:111], s[8:9] offset:2064
	s_add_u32 s8, s8, 0x1000
	s_addc_u32 s9, s9, 0
	global_load_dwordx4 v[96:99], v1, s[6:7] offset:0
	global_load_dwordx4 v[100:103], v1, s[6:7] offset:16
	global_load_dwordx4 v[104:107], v1, s[6:7] offset:2048
	global_load_dwordx4 v[108:111], v1, s[6:7] offset:2064
	global_load_dwordx4 v[112:115], v2, s[10:11]
	global_load_dwordx4 v[116:119], v2, s[10:11] offset:1024
	global_load_dwordx4 v[120:123], v2, s[12:13]
	global_load_dwordx4 v[124:127], v2, s[12:13] offset:1024
	s_add_u32 s6, s6, 0x1000
	s_addc_u32 s7, s7, 0
	s_add_u32 s10, s10, 0x800
	s_addc_u32 s11, s11, 0
	s_add_u32 s12, s12, 0x800
	s_addc_u32 s13, s13, 0
	s_waitcnt vmcnt(24)
; DI float shx(float v, int mask) { const int l = olane(); return __builtin_bit_cast(float, __builtin_amdgcn_ds_bpermute(((l ^ mask) & 63) << 2, __builtin_bit_cast(int, v))); }
; DI void row_phase(const bf16_t* msrc, const float* xsrc, float* xdst, const float* g_post, const float* g_next, bf16_t* hdst, const int gw) {
;     ...
;                 for (int j = 0; j < 4; ++j) { const u32x2 mw = *(const u32x2*)(msrc + (size_t)(rowb + r) * DM + lane * 4 + 256 * j);
;                     mv[r][j] = (f32x4){__uint_as_float(mw[0] << 16), __uint_as_float(mw[0] & 0xffff0000u), __uint_as_float(mw[1] << 16), __uint_as_float(mw[1] & 0xffff0000u)}; }
;             float ss[RB];
; #pragma unroll
;             for (int r = 0; r < RB; ++r) { ss[r] = 0.f;
; #pragma unroll
;                 for (int j = 0; j < 4; ++j) ss[r] += mv[r][j][0] * mv[r][j][0] + mv[r][j][1] * mv[r][j][1] + mv[r][j][2] * mv[r][j][2] + mv[r][j][3] * mv[r][j][3]; }
; #pragma unroll
;             for (int o = 32; o >= 1; o >>= 1)
; #pragma unroll
;                 for (int r = 0; r < RB; ++r) ss[r] += shx(ss[r], o);
; #pragma unroll
;             for (int j = 0; j < 4; ++j) { const f32x4 g = *(const f32x4*)(g_post + lane * 4 + 256 * j);
; #pragma unroll
;                 for (int r = 0; r < RB; ++r) { const float r1 = rsqrtf(ss[r] * (1.f / DM) + EPS); xv[r][j] = xv[r][j] + mv[r][j] * r1 * g; *(f32x4*)(xdst + (size_t)(rowb + r) * DM + lane * 4 + 256 * j) = xv[r][j]; } }
	v_lshlrev_b32_e32 v208, 16, v144
	v_and_b32_e32 v209, 0xffff0000, v144
	v_lshlrev_b32_e32 v210, 16, v145
	v_and_b32_e32 v211, 0xffff0000, v145
	v_lshlrev_b32_e32 v212, 16, v146
	v_and_b32_e32 v213, 0xffff0000, v146
	v_lshlrev_b32_e32 v214, 16, v147
	v_and_b32_e32 v215, 0xffff0000, v147
	v_lshlrev_b32_e32 v216, 16, v148
	v_and_b32_e32 v217, 0xffff0000, v148
	v_lshlrev_b32_e32 v218, 16, v149
	v_and_b32_e32 v219, 0xffff0000, v149
	v_lshlrev_b32_e32 v220, 16, v150
	v_and_b32_e32 v221, 0xffff0000, v150
	v_lshlrev_b32_e32 v222, 16, v151
	v_and_b32_e32 v223, 0xffff0000, v151
	v_mul_f32_e32 v224, v208, v208
	v_fmac_f32_e32 v224, v209, v209
	v_fmac_f32_e32 v224, v210, v210
	v_fmac_f32_e32 v224, v211, v211
	v_fmac_f32_e32 v224, v212, v212
	v_fmac_f32_e32 v224, v213, v213
	v_fmac_f32_e32 v224, v214, v214
	v_fmac_f32_e32 v224, v215, v215
	v_fmac_f32_e32 v224, v216, v216
	v_fmac_f32_e32 v224, v217, v217
	v_fmac_f32_e32 v224, v218, v218
	v_fmac_f32_e32 v224, v219, v219
	v_fmac_f32_e32 v224, v220, v220
	v_fmac_f32_e32 v224, v221, v221
	v_fmac_f32_e32 v224, v222, v222
	v_fmac_f32_e32 v224, v223, v223
	s_nop 1
	v_add_f32_dpp v224, v224, v224 quad_perm:[1,0,3,2] row_mask:0xf bank_mask:0xf
	s_nop 1
	v_add_f32_dpp v224, v224, v224 quad_perm:[2,3,0,1] row_mask:0xf bank_mask:0xf
	s_nop 1
	v_add_f32_dpp v224, v224, v224 row_ror:4 row_mask:0xf bank_mask:0xf
	s_nop 1
	v_add_f32_dpp v224, v224, v224 row_ror:8 row_mask:0xf bank_mask:0xf
	s_nop 1
	v_readlane_b32 s20, v224, 0
	v_readlane_b32 s21, v224, 16
	v_readlane_b32 s22, v224, 32
	v_readlane_b32 s23, v224, 48
	s_nop 1
	v_mov_b32_e32 v225, s20
	v_add_f32_e32 v225, s21, v225
	v_add_f32_e32 v225, s22, v225
	v_add_f32_e32 v225, s23, v225
	v_mov_b32_e32 v226, 0x358637bd
	v_fmac_f32_e32 v226, 0x3a800000, v225
	v_rsq_f32_e32 v226, v226
	s_nop 0
	v_mul_f32_e32 v208, v208, v226
	v_mul_f32_e32 v209, v209, v226
	v_mul_f32_e32 v210, v210, v226
	v_mul_f32_e32 v211, v211, v226
	v_mul_f32_e32 v212, v212, v226
	v_mul_f32_e32 v213, v213, v226
	v_mul_f32_e32 v214, v214, v226
	v_mul_f32_e32 v215, v215, v226
	v_mul_f32_e32 v216, v216, v226
	v_mul_f32_e32 v217, v217, v226
	v_mul_f32_e32 v218, v218, v226
	v_mul_f32_e32 v219, v219, v226
	v_mul_f32_e32 v220, v220, v226
	v_mul_f32_e32 v221, v221, v226
	v_mul_f32_e32 v222, v222, v226
	v_mul_f32_e32 v223, v223, v226
	v_fmac_f32_e32 v128, v208, v40
	v_fmac_f32_e32 v129, v209, v41
	v_fmac_f32_e32 v130, v210, v42
	v_fmac_f32_e32 v131, v211, v43
	v_fmac_f32_e32 v132, v212, v44
	v_fmac_f32_e32 v133, v213, v45
	v_fmac_f32_e32 v134, v214, v46
	v_fmac_f32_e32 v135, v215, v47
	v_fmac_f32_e32 v136, v216, v48
	v_fmac_f32_e32 v137, v217, v49
	v_fmac_f32_e32 v138, v218, v50
	v_fmac_f32_e32 v139, v219, v51
	v_fmac_f32_e32 v140, v220, v52
	v_fmac_f32_e32 v141, v221, v53
	v_fmac_f32_e32 v142, v222, v54
	v_fmac_f32_e32 v143, v223, v55
	v_lshlrev_b32_e32 v208, 16, v152
	v_and_b32_e32 v209, 0xffff0000, v152
	v_lshlrev_b32_e32 v210, 16, v153
	v_and_b32_e32 v211, 0xffff0000, v153
	v_lshlrev_b32_e32 v212, 16, v154
	v_and_b32_e32 v213, 0xffff0000, v154
	v_lshlrev_b32_e32 v214, 16, v155
	v_and_b32_e32 v215, 0xffff0000, v155
	v_lshlrev_b32_e32 v216, 16, v156
	v_and_b32_e32 v217, 0xffff0000, v156
	v_lshlrev_b32_e32 v218, 16, v157
	v_and_b32_e32 v219, 0xffff0000, v157
	v_lshlrev_b32_e32 v220, 16, v158
	v_and_b32_e32 v221, 0xffff0000, v158
	v_lshlrev_b32_e32 v222, 16, v159
	v_and_b32_e32 v223, 0xffff0000, v159
	v_mul_f32_e32 v224, v208, v208
	v_fmac_f32_e32 v224, v209, v209
	v_fmac_f32_e32 v224, v210, v210
	v_fmac_f32_e32 v224, v211, v211
	v_fmac_f32_e32 v224, v212, v212
	v_fmac_f32_e32 v224, v213, v213
	v_fmac_f32_e32 v224, v214, v214
	v_fmac_f32_e32 v224, v215, v215
	v_fmac_f32_e32 v224, v216, v216
	v_fmac_f32_e32 v224, v217, v217
	v_fmac_f32_e32 v224, v218, v218
	v_fmac_f32_e32 v224, v219, v219
	v_fmac_f32_e32 v224, v220, v220
	v_fmac_f32_e32 v224, v221, v221
	v_fmac_f32_e32 v224, v222, v222
	v_fmac_f32_e32 v224, v223, v223
	s_nop 1
	v_add_f32_dpp v224, v224, v224 quad_perm:[1,0,3,2] row_mask:0xf bank_mask:0xf
	s_nop 1
	v_add_f32_dpp v224, v224, v224 quad_perm:[2,3,0,1] row_mask:0xf bank_mask:0xf
	s_nop 1
	v_add_f32_dpp v224, v224, v224 row_ror:4 row_mask:0xf bank_mask:0xf
	s_nop 1
	v_add_f32_dpp v224, v224, v224 row_ror:8 row_mask:0xf bank_mask:0xf
	s_nop 1
	v_readlane_b32 s20, v224, 0
	v_readlane_b32 s21, v224, 16
	v_readlane_b32 s22, v224, 32
	v_readlane_b32 s23, v224, 48
	s_nop 1
	v_mov_b32_e32 v225, s20
	v_add_f32_e32 v225, s21, v225
	v_add_f32_e32 v225, s22, v225
	v_add_f32_e32 v225, s23, v225
	v_mov_b32_e32 v226, 0x358637bd
	v_fmac_f32_e32 v226, 0x3a800000, v225
	v_rsq_f32_e32 v226, v226
	s_nop 0
	v_mul_f32_e32 v208, v208, v226
	v_mul_f32_e32 v209, v209, v226
	v_mul_f32_e32 v210, v210, v226
	v_mul_f32_e32 v211, v211, v226
	v_mul_f32_e32 v212, v212, v226
	v_mul_f32_e32 v213, v213, v226
	v_mul_f32_e32 v214, v214, v226
	v_mul_f32_e32 v215, v215, v226
	v_mul_f32_e32 v216, v216, v226
	v_mul_f32_e32 v217, v217, v226
	v_mul_f32_e32 v218, v218, v226
	v_mul_f32_e32 v219, v219, v226
	v_mul_f32_e32 v220, v220, v226
	v_mul_f32_e32 v221, v221, v226
	v_mul_f32_e32 v222, v222, v226
	v_mul_f32_e32 v223, v223, v226
	v_fmac_f32_e32 v128, v208, v56
	v_fmac_f32_e32 v129, v209, v57
	v_fmac_f32_e32 v130, v210, v58
	v_fmac_f32_e32 v131, v211, v59
	v_fmac_f32_e32 v132, v212, v60
	v_fmac_f32_e32 v133, v213, v61
	v_fmac_f32_e32 v134, v214, v62
	v_fmac_f32_e32 v135, v215, v63
	v_fmac_f32_e32 v136, v216, v64
	v_fmac_f32_e32 v137, v217, v65
	v_fmac_f32_e32 v138, v218, v66
	v_fmac_f32_e32 v139, v219, v67
	v_fmac_f32_e32 v140, v220, v68
	v_fmac_f32_e32 v141, v221, v69
	v_fmac_f32_e32 v142, v222, v70
	v_fmac_f32_e32 v143, v223, v71
	global_store_dwordx4 v1, v[128:131], s[8:9] offset:0
	global_store_dwordx4 v1, v[132:135], s[8:9] offset:16
	global_store_dwordx4 v1, v[136:139], s[8:9] offset:2048
	global_store_dwordx4 v1, v[140:143], s[8:9] offset:2064
	s_add_u32 s8, s8, 0x1000
	s_addc_u32 s9, s9, 0
	global_load_dwordx4 v[128:131], v1, s[6:7] offset:0
	global_load_dwordx4 v[132:135], v1, s[6:7] offset:16
	global_load_dwordx4 v[136:139], v1, s[6:7] offset:2048
	global_load_dwordx4 v[140:143], v1, s[6:7] offset:2064
	global_load_dwordx4 v[144:147], v2, s[10:11]
	global_load_dwordx4 v[148:151], v2, s[10:11] offset:1024
	global_load_dwordx4 v[152:155], v2, s[12:13]
	global_load_dwordx4 v[156:159], v2, s[12:13] offset:1024
	s_add_u32 s6, s6, 0x1000
	s_addc_u32 s7, s7, 0
	s_add_u32 s10, s10, 0x800
	s_addc_u32 s11, s11, 0
	s_add_u32 s12, s12, 0x800
	s_addc_u32 s13, s13, 0
	s_waitcnt vmcnt(24)
; DI float shx(float v, int mask) { const int l = olane(); return __builtin_bit_cast(float, __builtin_amdgcn_ds_bpermute(((l ^ mask) & 63) << 2, __builtin_bit_cast(int, v))); }
; DI void row_phase(const bf16_t* msrc, const float* xsrc, float* xdst, const float* g_post, const float* g_next, bf16_t* hdst, const int gw) {
;     ...
;                 for (int j = 0; j < 4; ++j) { const u32x2 mw = *(const u32x2*)(msrc + (size_t)(rowb + r) * DM + lane * 4 + 256 * j);
;                     mv[r][j] = (f32x4){__uint_as_float(mw[0] << 16), __uint_as_float(mw[0] & 0xffff0000u), __uint_as_float(mw[1] << 16), __uint_as_float(mw[1] & 0xffff0000u)}; }
;             float ss[RB];
; #pragma unroll
;             for (int r = 0; r < RB; ++r) { ss[r] = 0.f;
; #pragma unroll
;                 for (int j = 0; j < 4; ++j) ss[r] += mv[r][j][0] * mv[r][j][0] + mv[r][j][1] * mv[r][j][1] + mv[r][j][2] * mv[r][j][2] + mv[r][j][3] * mv[r][j][3]; }
; #pragma unroll
;             for (int o = 32; o >= 1; o >>= 1)
; #pragma unroll
;                 for (int r = 0; r < RB; ++r) ss[r] += shx(ss[r], o);
; #pragma unroll
;             for (int j = 0; j < 4; ++j) { const f32x4 g = *(const f32x4*)(g_post + lane * 4 + 256 * j);
; #pragma unroll
;                 for (int r = 0; r < RB; ++r) { const float r1 = rsqrtf(ss[r] * (1.f / DM) + EPS); xv[r][j] = xv[r][j] + mv[r][j] * r1 * g; *(f32x4*)(xdst + (size_t)(rowb + r) * DM + lane * 4 + 256 * j) = xv[r][j]; } }
	v_lshlrev_b32_e32 v208, 16, v176
	v_and_b32_e32 v209, 0xffff0000, v176
	v_lshlrev_b32_e32 v210, 16, v177
	v_and_b32_e32 v211, 0xffff0000, v177
	v_lshlrev_b32_e32 v212, 16, v178
	v_and_b32_e32 v213, 0xffff0000, v178
	v_lshlrev_b32_e32 v214, 16, v179
	v_and_b32_e32 v215, 0xffff0000, v179
	v_lshlrev_b32_e32 v216, 16, v180
	v_and_b32_e32 v217, 0xffff0000, v180
	v_lshlrev_b32_e32 v218, 16, v181
	v_and_b32_e32 v219, 0xffff0000, v181
	v_lshlrev_b32_e32 v220, 16, v182
	v_and_b32_e32 v221, 0xffff0000, v182
	v_lshlrev_b32_e32 v222, 16, v183
	v_and_b32_e32 v223, 0xffff0000, v183
	v_mul_f32_e32 v224, v208, v208
	v_fmac_f32_e32 v224, v209, v209
	v_fmac_f32_e32 v224, v210, v210
	v_fmac_f32_e32 v224, v211, v211
	v_fmac_f32_e32 v224, v212, v212
	v_fmac_f32_e32 v224, v213, v213
	v_fmac_f32_e32 v224, v214, v214
	v_fmac_f32_e32 v224, v215, v215
	v_fmac_f32_e32 v224, v216, v216
	v_fmac_f32_e32 v224, v217, v217
	v_fmac_f32_e32 v224, v218, v218
	v_fmac_f32_e32 v224, v219, v219
	v_fmac_f32_e32 v224, v220, v220
	v_fmac_f32_e32 v224, v221, v221
	v_fmac_f32_e32 v224, v222, v222
	v_fmac_f32_e32 v224, v223, v223
	s_nop 1
	v_add_f32_dpp v224, v224, v224 quad_perm:[1,0,3,2] row_mask:0xf bank_mask:0xf
	s_nop 1
	v_add_f32_dpp v224, v224, v224 quad_perm:[2,3,0,1] row_mask:0xf bank_mask:0xf
	s_nop 1
	v_add_f32_dpp v224, v224, v224 row_ror:4 row_mask:0xf bank_mask:0xf
	s_nop 1
	v_add_f32_dpp v224, v224, v224 row_ror:8 row_mask:0xf bank_mask:0xf
	s_nop 1
	v_readlane_b32 s20, v224, 0
	v_readlane_b32 s21, v224, 16
	v_readlane_b32 s22, v224, 32
	v_readlane_b32 s23, v224, 48
	s_nop 1
	v_mov_b32_e32 v225, s20
	v_add_f32_e32 v225, s21, v225
	v_add_f32_e32 v225, s22, v225
	v_add_f32_e32 v225, s23, v225
	v_mov_b32_e32 v226, 0x358637bd
	v_fmac_f32_e32 v226, 0x3a800000, v225
	v_rsq_f32_e32 v226, v226
	s_nop 0
	v_mul_f32_e32 v208, v208, v226
	v_mul_f32_e32 v209, v209, v226
	v_mul_f32_e32 v210, v210, v226
	v_mul_f32_e32 v211, v211, v226
	v_mul_f32_e32 v212, v212, v226
	v_mul_f32_e32 v213, v213, v226
	v_mul_f32_e32 v214, v214, v226
	v_mul_f32_e32 v215, v215, v226
	v_mul_f32_e32 v216, v216, v226
	v_mul_f32_e32 v217, v217, v226
	v_mul_f32_e32 v218, v218, v226
	v_mul_f32_e32 v219, v219, v226
	v_mul_f32_e32 v220, v220, v226
	v_mul_f32_e32 v221, v221, v226
	v_mul_f32_e32 v222, v222, v226
	v_mul_f32_e32 v223, v223, v226
	v_fmac_f32_e32 v160, v208, v40
	v_fmac_f32_e32 v161, v209, v41
	v_fmac_f32_e32 v162, v210, v42
	v_fmac_f32_e32 v163, v211, v43
	v_fmac_f32_e32 v164, v212, v44
	v_fmac_f32_e32 v165, v213, v45
	v_fmac_f32_e32 v166, v214, v46
	v_fmac_f32_e32 v167, v215, v47
	v_fmac_f32_e32 v168, v216, v48
	v_fmac_f32_e32 v169, v217, v49
	v_fmac_f32_e32 v170, v218, v50
	v_fmac_f32_e32 v171, v219, v51
	v_fmac_f32_e32 v172, v220, v52
	v_fmac_f32_e32 v173, v221, v53
	v_fmac_f32_e32 v174, v222, v54
	v_fmac_f32_e32 v175, v223, v55
	v_lshlrev_b32_e32 v208, 16, v184
	v_and_b32_e32 v209, 0xffff0000, v184
	v_lshlrev_b32_e32 v210, 16, v185
	v_and_b32_e32 v211, 0xffff0000, v185
	v_lshlrev_b32_e32 v212, 16, v186
	v_and_b32_e32 v213, 0xffff0000, v186
	v_lshlrev_b32_e32 v214, 16, v187
	v_and_b32_e32 v215, 0xffff0000, v187
	v_lshlrev_b32_e32 v216, 16, v188
	v_and_b32_e32 v217, 0xffff0000, v188
	v_lshlrev_b32_e32 v218, 16, v189
	v_and_b32_e32 v219, 0xffff0000, v189
	v_lshlrev_b32_e32 v220, 16, v190
	v_and_b32_e32 v221, 0xffff0000, v190
	v_lshlrev_b32_e32 v222, 16, v191
	v_and_b32_e32 v223, 0xffff0000, v191
	v_mul_f32_e32 v224, v208, v208
	v_fmac_f32_e32 v224, v209, v209
	v_fmac_f32_e32 v224, v210, v210
	v_fmac_f32_e32 v224, v211, v211
	v_fmac_f32_e32 v224, v212, v212
	v_fmac_f32_e32 v224, v213, v213
	v_fmac_f32_e32 v224, v214, v214
	v_fmac_f32_e32 v224, v215, v215
	v_fmac_f32_e32 v224, v216, v216
	v_fmac_f32_e32 v224, v217, v217
	v_fmac_f32_e32 v224, v218, v218
	v_fmac_f32_e32 v224, v219, v219
	v_fmac_f32_e32 v224, v220, v220
	v_fmac_f32_e32 v224, v221, v221
	v_fmac_f32_e32 v224, v222, v222
	v_fmac_f32_e32 v224, v223, v223
	s_nop 1
	v_add_f32_dpp v224, v224, v224 quad_perm:[1,0,3,2] row_mask:0xf bank_mask:0xf
	s_nop 1
	v_add_f32_dpp v224, v224, v224 quad_perm:[2,3,0,1] row_mask:0xf bank_mask:0xf
	s_nop 1
	v_add_f32_dpp v224, v224, v224 row_ror:4 row_mask:0xf bank_mask:0xf
	s_nop 1
	v_add_f32_dpp v224, v224, v224 row_ror:8 row_mask:0xf bank_mask:0xf
	s_nop 1
	v_readlane_b32 s20, v224, 0
	v_readlane_b32 s21, v224, 16
	v_readlane_b32 s22, v224, 32
	v_readlane_b32 s23, v224, 48
	s_nop 1
	v_mov_b32_e32 v225, s20
	v_add_f32_e32 v225, s21, v225
	v_add_f32_e32 v225, s22, v225
	v_add_f32_e32 v225, s23, v225
	v_mov_b32_e32 v226, 0x358637bd
	v_fmac_f32_e32 v226, 0x3a800000, v225
	v_rsq_f32_e32 v226, v226
	s_nop 0
	v_mul_f32_e32 v208, v208, v226
	v_mul_f32_e32 v209, v209, v226
	v_mul_f32_e32 v210, v210, v226
	v_mul_f32_e32 v211, v211, v226
	v_mul_f32_e32 v212, v212, v226
	v_mul_f32_e32 v213, v213, v226
	v_mul_f32_e32 v214, v214, v226
	v_mul_f32_e32 v215, v215, v226
	v_mul_f32_e32 v216, v216, v226
	v_mul_f32_e32 v217, v217, v226
	v_mul_f32_e32 v218, v218, v226
	v_mul_f32_e32 v219, v219, v226
	v_mul_f32_e32 v220, v220, v226
	v_mul_f32_e32 v221, v221, v226
	v_mul_f32_e32 v222, v222, v226
	v_mul_f32_e32 v223, v223, v226
	v_fmac_f32_e32 v160, v208, v56
	v_fmac_f32_e32 v161, v209, v57
	v_fmac_f32_e32 v162, v210, v58
	v_fmac_f32_e32 v163, v211, v59
	v_fmac_f32_e32 v164, v212, v60
	v_fmac_f32_e32 v165, v213, v61
	v_fmac_f32_e32 v166, v214, v62
	v_fmac_f32_e32 v167, v215, v63
	v_fmac_f32_e32 v168, v216, v64
	v_fmac_f32_e32 v169, v217, v65
	v_fmac_f32_e32 v170, v218, v66
	v_fmac_f32_e32 v171, v219, v67
	v_fmac_f32_e32 v172, v220, v68
	v_fmac_f32_e32 v173, v221, v69
	v_fmac_f32_e32 v174, v222, v70
	v_fmac_f32_e32 v175, v223, v71
	global_store_dwordx4 v1, v[160:163], s[8:9] offset:0
	global_store_dwordx4 v1, v[164:167], s[8:9] offset:16
	global_store_dwordx4 v1, v[168:171], s[8:9] offset:2048
	global_store_dwordx4 v1, v[172:175], s[8:9] offset:2064
	s_add_u32 s8, s8, 0x1000
	s_addc_u32 s9, s9, 0
	s_waitcnt vmcnt(16)
; DI float shx(float v, int mask) { const int l = olane(); return __builtin_bit_cast(float, __builtin_amdgcn_ds_bpermute(((l ^ mask) & 63) << 2, __builtin_bit_cast(int, v))); }
; DI void row_phase(const bf16_t* msrc, const float* xsrc, float* xdst, const float* g_post, const float* g_next, bf16_t* hdst, const int gw) {
;     ...
;                 for (int j = 0; j < 4; ++j) { const u32x2 mw = *(const u32x2*)(msrc + (size_t)(rowb + r) * DM + lane * 4 + 256 * j);
;                     mv[r][j] = (f32x4){__uint_as_float(mw[0] << 16), __uint_as_float(mw[0] & 0xffff0000u), __uint_as_float(mw[1] << 16), __uint_as_float(mw[1] & 0xffff0000u)}; }
;             float ss[RB];
; #pragma unroll
;             for (int r = 0; r < RB; ++r) { ss[r] = 0.f;
; #pragma unroll
;                 for (int j = 0; j < 4; ++j) ss[r] += mv[r][j][0] * mv[r][j][0] + mv[r][j][1] * mv[r][j][1] + mv[r][j][2] * mv[r][j][2] + mv[r][j][3] * mv[r][j][3]; }
; #pragma unroll
;             for (int o = 32; o >= 1; o >>= 1)
; #pragma unroll
;                 for (int r = 0; r < RB; ++r) ss[r] += shx(ss[r], o);
; #pragma unroll
;             for (int j = 0; j < 4; ++j) { const f32x4 g = *(const f32x4*)(g_post + lane * 4 + 256 * j);
; #pragma unroll
;                 for (int r = 0; r < RB; ++r) { const float r1 = rsqrtf(ss[r] * (1.f / DM) + EPS); xv[r][j] = xv[r][j] + mv[r][j] * r1 * g; *(f32x4*)(xdst + (size_t)(rowb + r) * DM + lane * 4 + 256 * j) = xv[r][j]; } }
	v_lshlrev_b32_e32 v208, 16, v112
	v_and_b32_e32 v209, 0xffff0000, v112
	v_lshlrev_b32_e32 v210, 16, v113
	v_and_b32_e32 v211, 0xffff0000, v113
	v_lshlrev_b32_e32 v212, 16, v114
	v_and_b32_e32 v213, 0xffff0000, v114
	v_lshlrev_b32_e32 v214, 16, v115
	v_and_b32_e32 v215, 0xffff0000, v115
	v_lshlrev_b32_e32 v216, 16, v116
	v_and_b32_e32 v217, 0xffff0000, v116
	v_lshlrev_b32_e32 v218, 16, v117
	v_and_b32_e32 v219, 0xffff0000, v117
	v_lshlrev_b32_e32 v220, 16, v118
	v_and_b32_e32 v221, 0xffff0000, v118
	v_lshlrev_b32_e32 v222, 16, v119
	v_and_b32_e32 v223, 0xffff0000, v119
	v_mul_f32_e32 v224, v208, v208
	v_fmac_f32_e32 v224, v209, v209
	v_fmac_f32_e32 v224, v210, v210
	v_fmac_f32_e32 v224, v211, v211
	v_fmac_f32_e32 v224, v212, v212
	v_fmac_f32_e32 v224, v213, v213
	v_fmac_f32_e32 v224, v214, v214
	v_fmac_f32_e32 v224, v215, v215
	v_fmac_f32_e32 v224, v216, v216
	v_fmac_f32_e32 v224, v217, v217
	v_fmac_f32_e32 v224, v218, v218
	v_fmac_f32_e32 v224, v219, v219
	v_fmac_f32_e32 v224, v220, v220
	v_fmac_f32_e32 v224, v221, v221
	v_fmac_f32_e32 v224, v222, v222
	v_fmac_f32_e32 v224, v223, v223
	s_nop 1
	v_add_f32_dpp v224, v224, v224 quad_perm:[1,0,3,2] row_mask:0xf bank_mask:0xf
	s_nop 1
	v_add_f32_dpp v224, v224, v224 quad_perm:[2,3,0,1] row_mask:0xf bank_mask:0xf
	s_nop 1
	v_add_f32_dpp v224, v224, v224 row_ror:4 row_mask:0xf bank_mask:0xf
	s_nop 1
	v_add_f32_dpp v224, v224, v224 row_ror:8 row_mask:0xf bank_mask:0xf
	s_nop 1
	v_readlane_b32 s20, v224, 0
	v_readlane_b32 s21, v224, 16
	v_readlane_b32 s22, v224, 32
	v_readlane_b32 s23, v224, 48
	s_nop 1
	v_mov_b32_e32 v225, s20
	v_add_f32_e32 v225, s21, v225
	v_add_f32_e32 v225, s22, v225
	v_add_f32_e32 v225, s23, v225
	v_mov_b32_e32 v226, 0x358637bd
	v_fmac_f32_e32 v226, 0x3a800000, v225
	v_rsq_f32_e32 v226, v226
	s_nop 0
	v_mul_f32_e32 v208, v208, v226
	v_mul_f32_e32 v209, v209, v226
	v_mul_f32_e32 v210, v210, v226
	v_mul_f32_e32 v211, v211, v226
	v_mul_f32_e32 v212, v212, v226
	v_mul_f32_e32 v213, v213, v226
	v_mul_f32_e32 v214, v214, v226
	v_mul_f32_e32 v215, v215, v226
	v_mul_f32_e32 v216, v216, v226
	v_mul_f32_e32 v217, v217, v226
	v_mul_f32_e32 v218, v218, v226
	v_mul_f32_e32 v219, v219, v226
	v_mul_f32_e32 v220, v220, v226
	v_mul_f32_e32 v221, v221, v226
	v_mul_f32_e32 v222, v222, v226
	v_mul_f32_e32 v223, v223, v226
	v_fmac_f32_e32 v96, v208, v40
	v_fmac_f32_e32 v97, v209, v41
	v_fmac_f32_e32 v98, v210, v42
	v_fmac_f32_e32 v99, v211, v43
	v_fmac_f32_e32 v100, v212, v44
	v_fmac_f32_e32 v101, v213, v45
	v_fmac_f32_e32 v102, v214, v46
	v_fmac_f32_e32 v103, v215, v47
	v_fmac_f32_e32 v104, v216, v48
	v_fmac_f32_e32 v105, v217, v49
	v_fmac_f32_e32 v106, v218, v50
	v_fmac_f32_e32 v107, v219, v51
	v_fmac_f32_e32 v108, v220, v52
	v_fmac_f32_e32 v109, v221, v53
	v_fmac_f32_e32 v110, v222, v54
	v_fmac_f32_e32 v111, v223, v55
	v_lshlrev_b32_e32 v208, 16, v120
	v_and_b32_e32 v209, 0xffff0000, v120
	v_lshlrev_b32_e32 v210, 16, v121
	v_and_b32_e32 v211, 0xffff0000, v121
	v_lshlrev_b32_e32 v212, 16, v122
	v_and_b32_e32 v213, 0xffff0000, v122
	v_lshlrev_b32_e32 v214, 16, v123
	v_and_b32_e32 v215, 0xffff0000, v123
	v_lshlrev_b32_e32 v216, 16, v124
	v_and_b32_e32 v217, 0xffff0000, v124
	v_lshlrev_b32_e32 v218, 16, v125
	v_and_b32_e32 v219, 0xffff0000, v125
	v_lshlrev_b32_e32 v220, 16, v126
	v_and_b32_e32 v221, 0xffff0000, v126
	v_lshlrev_b32_e32 v222, 16, v127
	v_and_b32_e32 v223, 0xffff0000, v127
	v_mul_f32_e32 v224, v208, v208
	v_fmac_f32_e32 v224, v209, v209
	v_fmac_f32_e32 v224, v210, v210
	v_fmac_f32_e32 v224, v211, v211
	v_fmac_f32_e32 v224, v212, v212
	v_fmac_f32_e32 v224, v213, v213
	v_fmac_f32_e32 v224, v214, v214
	v_fmac_f32_e32 v224, v215, v215
	v_fmac_f32_e32 v224, v216, v216
	v_fmac_f32_e32 v224, v217, v217
	v_fmac_f32_e32 v224, v218, v218
	v_fmac_f32_e32 v224, v219, v219
	v_fmac_f32_e32 v224, v220, v220
	v_fmac_f32_e32 v224, v221, v221
	v_fmac_f32_e32 v224, v222, v222
	v_fmac_f32_e32 v224, v223, v223
	s_nop 1
	v_add_f32_dpp v224, v224, v224 quad_perm:[1,0,3,2] row_mask:0xf bank_mask:0xf
	s_nop 1
	v_add_f32_dpp v224, v224, v224 quad_perm:[2,3,0,1] row_mask:0xf bank_mask:0xf
	s_nop 1
	v_add_f32_dpp v224, v224, v224 row_ror:4 row_mask:0xf bank_mask:0xf
	s_nop 1
	v_add_f32_dpp v224, v224, v224 row_ror:8 row_mask:0xf bank_mask:0xf
	s_nop 1
	v_readlane_b32 s20, v224, 0
	v_readlane_b32 s21, v224, 16
	v_readlane_b32 s22, v224, 32
	v_readlane_b32 s23, v224, 48
	s_nop 1
	v_mov_b32_e32 v225, s20
	v_add_f32_e32 v225, s21, v225
	v_add_f32_e32 v225, s22, v225
	v_add_f32_e32 v225, s23, v225
	v_mov_b32_e32 v226, 0x358637bd
	v_fmac_f32_e32 v226, 0x3a800000, v225
	v_rsq_f32_e32 v226, v226
	s_nop 0
	v_mul_f32_e32 v208, v208, v226
	v_mul_f32_e32 v209, v209, v226
	v_mul_f32_e32 v210, v210, v226
	v_mul_f32_e32 v211, v211, v226
	v_mul_f32_e32 v212, v212, v226
	v_mul_f32_e32 v213, v213, v226
	v_mul_f32_e32 v214, v214, v226
	v_mul_f32_e32 v215, v215, v226
	v_mul_f32_e32 v216, v216, v226
	v_mul_f32_e32 v217, v217, v226
	v_mul_f32_e32 v218, v218, v226
	v_mul_f32_e32 v219, v219, v226
	v_mul_f32_e32 v220, v220, v226
	v_mul_f32_e32 v221, v221, v226
	v_mul_f32_e32 v222, v222, v226
	v_mul_f32_e32 v223, v223, v226
	v_fmac_f32_e32 v96, v208, v56
	v_fmac_f32_e32 v97, v209, v57
	v_fmac_f32_e32 v98, v210, v58
	v_fmac_f32_e32 v99, v211, v59
	v_fmac_f32_e32 v100, v212, v60
	v_fmac_f32_e32 v101, v213, v61
	v_fmac_f32_e32 v102, v214, v62
	v_fmac_f32_e32 v103, v215, v63
	v_fmac_f32_e32 v104, v216, v64
	v_fmac_f32_e32 v105, v217, v65
	v_fmac_f32_e32 v106, v218, v66
	v_fmac_f32_e32 v107, v219, v67
	v_fmac_f32_e32 v108, v220, v68
	v_fmac_f32_e32 v109, v221, v69
	v_fmac_f32_e32 v110, v222, v70
	v_fmac_f32_e32 v111, v223, v71
	global_store_dwordx4 v1, v[96:99], s[8:9] offset:0
	global_store_dwordx4 v1, v[100:103], s[8:9] offset:16
	global_store_dwordx4 v1, v[104:107], s[8:9] offset:2048
	global_store_dwordx4 v1, v[108:111], s[8:9] offset:2064
	s_add_u32 s8, s8, 0x1000
	s_addc_u32 s9, s9, 0
	s_waitcnt vmcnt(8)
; DI float shx(float v, int mask) { const int l = olane(); return __builtin_bit_cast(float, __builtin_amdgcn_ds_bpermute(((l ^ mask) & 63) << 2, __builtin_bit_cast(int, v))); }
; DI void row_phase(const bf16_t* msrc, const float* xsrc, float* xdst, const float* g_post, const float* g_next, bf16_t* hdst, const int gw) {
;     ...
;                 for (int j = 0; j < 4; ++j) { const u32x2 mw = *(const u32x2*)(msrc + (size_t)(rowb + r) * DM + lane * 4 + 256 * j);
;                     mv[r][j] = (f32x4){__uint_as_float(mw[0] << 16), __uint_as_float(mw[0] & 0xffff0000u), __uint_as_float(mw[1] << 16), __uint_as_float(mw[1] & 0xffff0000u)}; }
;             float ss[RB];
; #pragma unroll
;             for (int r = 0; r < RB; ++r) { ss[r] = 0.f;
; #pragma unroll
;                 for (int j = 0; j < 4; ++j) ss[r] += mv[r][j][0] * mv[r][j][0] + mv[r][j][1] * mv[r][j][1] + mv[r][j][2] * mv[r][j][2] + mv[r][j][3] * mv[r][j][3]; }
; #pragma unroll
;             for (int o = 32; o >= 1; o >>= 1)
; #pragma unroll
;                 for (int r = 0; r < RB; ++r) ss[r] += shx(ss[r], o);
; #pragma unroll
;             for (int j = 0; j < 4; ++j) { const f32x4 g = *(const f32x4*)(g_post + lane * 4 + 256 * j);
; #pragma unroll
;                 for (int r = 0; r < RB; ++r) { const float r1 = rsqrtf(ss[r] * (1.f / DM) + EPS); xv[r][j] = xv[r][j] + mv[r][j] * r1 * g; *(f32x4*)(xdst + (size_t)(rowb + r) * DM + lane * 4 + 256 * j) = xv[r][j]; } }
	v_lshlrev_b32_e32 v208, 16, v144
	v_and_b32_e32 v209, 0xffff0000, v144
	v_lshlrev_b32_e32 v210, 16, v145
	v_and_b32_e32 v211, 0xffff0000, v145
	v_lshlrev_b32_e32 v212, 16, v146
	v_and_b32_e32 v213, 0xffff0000, v146
	v_lshlrev_b32_e32 v214, 16, v147
	v_and_b32_e32 v215, 0xffff0000, v147
	v_lshlrev_b32_e32 v216, 16, v148
	v_and_b32_e32 v217, 0xffff0000, v148
	v_lshlrev_b32_e32 v218, 16, v149
	v_and_b32_e32 v219, 0xffff0000, v149
	v_lshlrev_b32_e32 v220, 16, v150
	v_and_b32_e32 v221, 0xffff0000, v150
	v_lshlrev_b32_e32 v222, 16, v151
	v_and_b32_e32 v223, 0xffff0000, v151
	v_mul_f32_e32 v224, v208, v208
	v_fmac_f32_e32 v224, v209, v209
	v_fmac_f32_e32 v224, v210, v210
	v_fmac_f32_e32 v224, v211, v211
	v_fmac_f32_e32 v224, v212, v212
	v_fmac_f32_e32 v224, v213, v213
	v_fmac_f32_e32 v224, v214, v214
	v_fmac_f32_e32 v224, v215, v215
	v_fmac_f32_e32 v224, v216, v216
	v_fmac_f32_e32 v224, v217, v217
	v_fmac_f32_e32 v224, v218, v218
	v_fmac_f32_e32 v224, v219, v219
	v_fmac_f32_e32 v224, v220, v220
	v_fmac_f32_e32 v224, v221, v221
	v_fmac_f32_e32 v224, v222, v222
	v_fmac_f32_e32 v224, v223, v223
	s_nop 1
	v_add_f32_dpp v224, v224, v224 quad_perm:[1,0,3,2] row_mask:0xf bank_mask:0xf
	s_nop 1
	v_add_f32_dpp v224, v224, v224 quad_perm:[2,3,0,1] row_mask:0xf bank_mask:0xf
	s_nop 1
	v_add_f32_dpp v224, v224, v224 row_ror:4 row_mask:0xf bank_mask:0xf
	s_nop 1
	v_add_f32_dpp v224, v224, v224 row_ror:8 row_mask:0xf bank_mask:0xf
	s_nop 1
	v_readlane_b32 s20, v224, 0
	v_readlane_b32 s21, v224, 16
	v_readlane_b32 s22, v224, 32
	v_readlane_b32 s23, v224, 48
	s_nop 1
	v_mov_b32_e32 v225, s20
	v_add_f32_e32 v225, s21, v225
	v_add_f32_e32 v225, s22, v225
	v_add_f32_e32 v225, s23, v225
	v_mov_b32_e32 v226, 0x358637bd
	v_fmac_f32_e32 v226, 0x3a800000, v225
	v_rsq_f32_e32 v226, v226
	s_nop 0
	v_mul_f32_e32 v208, v208, v226
	v_mul_f32_e32 v209, v209, v226
	v_mul_f32_e32 v210, v210, v226
	v_mul_f32_e32 v211, v211, v226
	v_mul_f32_e32 v212, v212, v226
	v_mul_f32_e32 v213, v213, v226
	v_mul_f32_e32 v214, v214, v226
	v_mul_f32_e32 v215, v215, v226
	v_mul_f32_e32 v216, v216, v226
	v_mul_f32_e32 v217, v217, v226
	v_mul_f32_e32 v218, v218, v226
	v_mul_f32_e32 v219, v219, v226
	v_mul_f32_e32 v220, v220, v226
	v_mul_f32_e32 v221, v221, v226
	v_mul_f32_e32 v222, v222, v226
	v_mul_f32_e32 v223, v223, v226
	v_fmac_f32_e32 v128, v208, v40
	v_fmac_f32_e32 v129, v209, v41
	v_fmac_f32_e32 v130, v210, v42
	v_fmac_f32_e32 v131, v211, v43
	v_fmac_f32_e32 v132, v212, v44
	v_fmac_f32_e32 v133, v213, v45
	v_fmac_f32_e32 v134, v214, v46
	v_fmac_f32_e32 v135, v215, v47
	v_fmac_f32_e32 v136, v216, v48
	v_fmac_f32_e32 v137, v217, v49
	v_fmac_f32_e32 v138, v218, v50
	v_fmac_f32_e32 v139, v219, v51
	v_fmac_f32_e32 v140, v220, v52
	v_fmac_f32_e32 v141, v221, v53
	v_fmac_f32_e32 v142, v222, v54
	v_fmac_f32_e32 v143, v223, v55
	v_lshlrev_b32_e32 v208, 16, v152
	v_and_b32_e32 v209, 0xffff0000, v152
	v_lshlrev_b32_e32 v210, 16, v153
	v_and_b32_e32 v211, 0xffff0000, v153
	v_lshlrev_b32_e32 v212, 16, v154
	v_and_b32_e32 v213, 0xffff0000, v154
	v_lshlrev_b32_e32 v214, 16, v155
	v_and_b32_e32 v215, 0xffff0000, v155
	v_lshlrev_b32_e32 v216, 16, v156
	v_and_b32_e32 v217, 0xffff0000, v156
	v_lshlrev_b32_e32 v218, 16, v157
	v_and_b32_e32 v219, 0xffff0000, v157
	v_lshlrev_b32_e32 v220, 16, v158
	v_and_b32_e32 v221, 0xffff0000, v158
	v_lshlrev_b32_e32 v222, 16, v159
	v_and_b32_e32 v223, 0xffff0000, v159
	v_mul_f32_e32 v224, v208, v208
	v_fmac_f32_e32 v224, v209, v209
	v_fmac_f32_e32 v224, v210, v210
	v_fmac_f32_e32 v224, v211, v211
	v_fmac_f32_e32 v224, v212, v212
	v_fmac_f32_e32 v224, v213, v213
	v_fmac_f32_e32 v224, v214, v214
	v_fmac_f32_e32 v224, v215, v215
	v_fmac_f32_e32 v224, v216, v216
	v_fmac_f32_e32 v224, v217, v217
	v_fmac_f32_e32 v224, v218, v218
	v_fmac_f32_e32 v224, v219, v219
	v_fmac_f32_e32 v224, v220, v220
	v_fmac_f32_e32 v224, v221, v221
	v_fmac_f32_e32 v224, v222, v222
	v_fmac_f32_e32 v224, v223, v223
	s_nop 1
	v_add_f32_dpp v224, v224, v224 quad_perm:[1,0,3,2] row_mask:0xf bank_mask:0xf
	s_nop 1
	v_add_f32_dpp v224, v224, v224 quad_perm:[2,3,0,1] row_mask:0xf bank_mask:0xf
	s_nop 1
	v_add_f32_dpp v224, v224, v224 row_ror:4 row_mask:0xf bank_mask:0xf
	s_nop 1
	v_add_f32_dpp v224, v224, v224 row_ror:8 row_mask:0xf bank_mask:0xf
	s_nop 1
	v_readlane_b32 s20, v224, 0
	v_readlane_b32 s21, v224, 16
	v_readlane_b32 s22, v224, 32
	v_readlane_b32 s23, v224, 48
	s_nop 1
	v_mov_b32_e32 v225, s20
	v_add_f32_e32 v225, s21, v225
	v_add_f32_e32 v225, s22, v225
	v_add_f32_e32 v225, s23, v225
	v_mov_b32_e32 v226, 0x358637bd
	v_fmac_f32_e32 v226, 0x3a800000, v225
	v_rsq_f32_e32 v226, v226
	s_nop 0
	v_mul_f32_e32 v208, v208, v226
	v_mul_f32_e32 v209, v209, v226
	v_mul_f32_e32 v210, v210, v226
	v_mul_f32_e32 v211, v211, v226
	v_mul_f32_e32 v212, v212, v226
	v_mul_f32_e32 v213, v213, v226
	v_mul_f32_e32 v214, v214, v226
	v_mul_f32_e32 v215, v215, v226
	v_mul_f32_e32 v216, v216, v226
	v_mul_f32_e32 v217, v217, v226
	v_mul_f32_e32 v218, v218, v226
	v_mul_f32_e32 v219, v219, v226
	v_mul_f32_e32 v220, v220, v226
	v_mul_f32_e32 v221, v221, v226
	v_mul_f32_e32 v222, v222, v226
	v_mul_f32_e32 v223, v223, v226
	v_fmac_f32_e32 v128, v208, v56
	v_fmac_f32_e32 v129, v209, v57
	v_fmac_f32_e32 v130, v210, v58
	v_fmac_f32_e32 v131, v211, v59
	v_fmac_f32_e32 v132, v212, v60
	v_fmac_f32_e32 v133, v213, v61
	v_fmac_f32_e32 v134, v214, v62
	v_fmac_f32_e32 v135, v215, v63
	v_fmac_f32_e32 v136, v216, v64
	v_fmac_f32_e32 v137, v217, v65
	v_fmac_f32_e32 v138, v218, v66
	v_fmac_f32_e32 v139, v219, v67
	v_fmac_f32_e32 v140, v220, v68
	v_fmac_f32_e32 v141, v221, v69
	v_fmac_f32_e32 v142, v222, v70
	v_fmac_f32_e32 v143, v223, v71
	global_store_dwordx4 v1, v[128:131], s[8:9] offset:0
	global_store_dwordx4 v1, v[132:135], s[8:9] offset:16
	global_store_dwordx4 v1, v[136:139], s[8:9] offset:2048
	global_store_dwordx4 v1, v[140:143], s[8:9] offset:2064
	s_add_u32 s8, s8, 0x1000
	s_addc_u32 s9, s9, 0
	v_readlane_b32 s4, v3, 0
	v_readlane_b32 s5, v3, 1
	v_readlane_b32 s6, v3, 2
	v_readlane_b32 s7, v3, 3
	v_readlane_b32 s8, v3, 4
	v_readlane_b32 s9, v3, 5
	v_readlane_b32 s10, v3, 6
	v_readlane_b32 s11, v3, 7
	v_readlane_b32 s12, v3, 8
	v_readlane_b32 s13, v3, 9
	v_readlane_b32 s14, v3, 10
	v_readlane_b32 s15, v3, 11
	v_readlane_b32 s16, v3, 12
	v_readlane_b32 s17, v3, 13
	v_readlane_b32 s18, v3, 14
	v_readlane_b32 s19, v3, 15
	v_readlane_b32 s20, v3, 16
	v_readlane_b32 s21, v3, 17
	v_readlane_b32 s22, v3, 18
	v_readlane_b32 s23, v3, 19
	v_readlane_b32 s24, v3, 20
	v_readlane_b32 s25, v3, 21
	s_mov_b32 s6, 0x358637bd
	s_mov_b64 s[34:35], 0
	s_branch .LBB0_74

; DI int olane() { int l; asm volatile("v_mbcnt_lo_u32_b32 %0, -1, 0\n\tv_mbcnt_hi_u32_b32 %0, -1, %0" : "=v"(l)); return l; }
; DI unsigned xb_ld(unsigned* p)              { return __hip_atomic_load(p, __ATOMIC_RELAXED, __HIP_MEMORY_SCOPE_AGENT); }
; DI void xcd_barrier_complete(unsigned* bar, unsigned x, unsigned& nloc, unsigned& nx) {
;     const unsigned G = gridDim.x * gridDim.y * gridDim.z;
;     unsigned sum, cnt, mine, sp = 0u;
;     for (;;) {
;         sum = 0u; cnt = 0u; mine = 0u;
; #pragma unroll
;         for (unsigned j = 0; j < 16; ++j) { const unsigned c = xb_ld(&bar[XB_XCNT(j)]); sum += c; cnt += (c > 0u) ? 1u : 0u; mine = (j == x) ? c : mine; }
;         if (sum == G) break;
;         __builtin_amdgcn_s_sleep(1);
;         if ((++sp & 255u) == 0u) { if (xb_ld(&bar[XB_TMO])) break; if (sp > XB_SPIN_CAP) { atomicAdd(&bar[XB_TMO], 1u); break; } }
;     }
;     nloc = mine > 0u ? mine : 1u; nx = cnt > 0u ? cnt : 1u;
; }
; DI void xcd_barrier(const XcdBarrier& b, const int gw) {
;     asm volatile("s_waitcnt vmcnt(0)" ::: "memory");
;     __syncthreads();
;     if (gw == 0 && olane() == 0) {
;         unsigned* bar = b.bar;
;         __builtin_amdgcn_s_waitcnt(0);
;         unsigned nloc = b.st[0], nx = b.st[1];
;         if (nloc == 0u) { xcd_barrier_complete(bar, b.x, nloc, nx); b.st[0] = nloc; b.st[1] = nx; }
.LBB0_511:
	v_readlane_b32 s98, v254, 2
	v_readlane_b32 s99, v254, 3
	v_mov_b32_e32 v17, 0x280
	s_nop 4
	global_load_dword v20, v17, s[98:99] offset:0 sc1
	global_load_dword v21, v17, s[98:99] offset:4 sc1
	global_load_dword v22, v17, s[98:99] offset:8 sc1
	global_load_dword v23, v17, s[98:99] offset:12 sc1
	global_load_dword v24, v17, s[98:99] offset:16 sc1
	global_load_dword v25, v17, s[98:99] offset:20 sc1
	global_load_dword v26, v17, s[98:99] offset:24 sc1
	global_load_dword v27, v17, s[98:99] offset:28 sc1
	v_xor_b32_e32 v18, 32, v0
	v_xor_b32_e32 v19, 32, v1
	v_or_b32_e32 v18, v18, v19
	v_xor_b32_e32 v19, 32, v2
	v_or_b32_e32 v18, v18, v19
	v_xor_b32_e32 v19, 32, v3
	v_or_b32_e32 v18, v18, v19
	v_xor_b32_e32 v19, 32, v4
	v_or_b32_e32 v18, v18, v19
	v_xor_b32_e32 v19, 32, v5
	v_or_b32_e32 v18, v18, v19
	v_xor_b32_e32 v19, 32, v6
	v_or_b32_e32 v18, v18, v19
	v_xor_b32_e32 v19, 32, v7
	v_or_b32_e32 v18, v18, v19
	v_or_b32_e32 v18, v18, v8
	v_or_b32_e32 v18, v18, v9
	v_or_b32_e32 v18, v18, v10
	v_or_b32_e32 v18, v18, v11
	v_or_b32_e32 v18, v18, v12
	v_or_b32_e32 v18, v18, v13
	v_or_b32_e32 v18, v18, v14
	v_or_b32_e32 v18, v18, v15
	s_waitcnt vmcnt(0)
	v_add_u32_e32 v19, -1, v20
	v_and_b32_e32 v19, v19, v20
	v_or_b32_e32 v18, v18, v19
	v_cmp_eq_u32_e32 vcc, 0, v20
	s_nop 1
	v_cndmask_b32_e64 v19, 0, 1, vcc
	v_or_b32_e32 v18, v18, v19
	v_add_u32_e32 v19, -1, v21
	v_and_b32_e32 v19, v19, v21
	v_or_b32_e32 v18, v18, v19
	v_cmp_eq_u32_e32 vcc, 0, v21
	s_nop 1
	v_cndmask_b32_e64 v19, 0, 1, vcc
	v_or_b32_e32 v18, v18, v19
	v_add_u32_e32 v19, -1, v22
	v_and_b32_e32 v19, v19, v22
	v_or_b32_e32 v18, v18, v19
	v_cmp_eq_u32_e32 vcc, 0, v22
	s_nop 1
	v_cndmask_b32_e64 v19, 0, 1, vcc
	v_or_b32_e32 v18, v18, v19
	v_add_u32_e32 v19, -1, v23
	v_and_b32_e32 v19, v19, v23
	v_or_b32_e32 v18, v18, v19
	v_cmp_eq_u32_e32 vcc, 0, v23
	s_nop 1
	v_cndmask_b32_e64 v19, 0, 1, vcc
	v_or_b32_e32 v18, v18, v19
	v_add_u32_e32 v19, -1, v24
	v_and_b32_e32 v19, v19, v24
	v_or_b32_e32 v18, v18, v19
	v_cmp_eq_u32_e32 vcc, 0, v24
	s_nop 1
	v_cndmask_b32_e64 v19, 0, 1, vcc
	v_or_b32_e32 v18, v18, v19
	v_add_u32_e32 v19, -1, v25
	v_and_b32_e32 v19, v19, v25
	v_or_b32_e32 v18, v18, v19
	v_cmp_eq_u32_e32 vcc, 0, v25
	s_nop 1
	v_cndmask_b32_e64 v19, 0, 1, vcc
	v_or_b32_e32 v18, v18, v19
	v_add_u32_e32 v19, -1, v26
	v_and_b32_e32 v19, v19, v26
	v_or_b32_e32 v18, v18, v19
	v_cmp_eq_u32_e32 vcc, 0, v26
	s_nop 1
	v_cndmask_b32_e64 v19, 0, 1, vcc
	v_or_b32_e32 v18, v18, v19
	v_add_u32_e32 v19, -1, v27
	v_and_b32_e32 v19, v19, v27
	v_or_b32_e32 v18, v18, v19
	v_cmp_eq_u32_e32 vcc, 0, v27
	s_nop 1
	v_cndmask_b32_e64 v19, 0, 1, vcc
	v_or_b32_e32 v18, v18, v19
	v_cmp_eq_u32_e32 vcc, 0, v18
	s_nop 1
	v_cndmask_b32_e64 v18, 0, 1, vcc
	v_mov_b32_e32 v19, 0x20048
	ds_write_b32 v19, v18
	s_cmp_eq_u32 s12, 0
	s_cselect_b64 vcc, -1, 0
	s_cmp_eq_u32 s12, 1
	v_cndmask_b32_e32 v16, 0, v0, vcc
	s_cselect_b64 vcc, -1, 0
	s_cmp_eq_u32 s12, 2
	v_cndmask_b32_e32 v16, v16, v1, vcc
	s_cselect_b64 vcc, -1, 0
	s_cmp_eq_u32 s12, 3
	v_cndmask_b32_e32 v16, v16, v2, vcc
	s_cselect_b64 vcc, -1, 0
	s_cmp_eq_u32 s12, 4
	v_cndmask_b32_e32 v16, v16, v3, vcc
	s_cselect_b64 vcc, -1, 0
	s_cmp_eq_u32 s12, 5
	v_cndmask_b32_e32 v16, v16, v4, vcc
	s_cselect_b64 vcc, -1, 0
	s_cmp_eq_u32 s12, 6
	v_cndmask_b32_e32 v16, v16, v5, vcc
	s_cselect_b64 vcc, -1, 0
	s_cmp_eq_u32 s12, 7
	v_cndmask_b32_e32 v16, v16, v6, vcc
	s_cselect_b64 vcc, -1, 0
	s_cmp_eq_u32 s12, 8
	v_cndmask_b32_e32 v16, v16, v7, vcc
	s_cselect_b64 vcc, -1, 0
	s_cmp_eq_u32 s12, 9
	v_cndmask_b32_e32 v16, v16, v8, vcc
	s_cselect_b64 vcc, -1, 0
	s_cmp_eq_u32 s12, 10
	v_cndmask_b32_e32 v16, v16, v9, vcc
	s_cselect_b64 vcc, -1, 0
	s_cmp_eq_u32 s12, 11
	v_cndmask_b32_e32 v16, v16, v10, vcc
	s_cselect_b64 vcc, -1, 0
	s_cmp_eq_u32 s12, 12
	v_cndmask_b32_e32 v16, v16, v11, vcc
	s_cselect_b64 vcc, -1, 0
	s_cmp_eq_u32 s12, 13
	v_cndmask_b32_e32 v16, v16, v12, vcc
	s_cselect_b64 vcc, -1, 0
	s_cmp_eq_u32 s12, 14
	v_cndmask_b32_e32 v16, v16, v13, vcc
	s_cselect_b64 vcc, -1, 0
	s_cmp_eq_u32 s12, 15
	v_cndmask_b32_e32 v16, v16, v14, vcc
	s_cselect_b64 vcc, -1, 0
	v_cndmask_b32_e32 v16, v16, v15, vcc
	v_cmp_ne_u32_e32 vcc, 0, v0
	s_nop 1
	v_cndmask_b32_e64 v0, 0, 1, vcc
	v_cmp_ne_u32_e32 vcc, 0, v1
	s_nop 1
	v_addc_co_u32_e32 v0, vcc, 0, v0, vcc
	v_cmp_ne_u32_e32 vcc, 0, v2
	v_max_u32_e32 v2, 1, v16
	s_nop 0
	v_cndmask_b32_e64 v1, 0, 1, vcc
	v_cmp_ne_u32_e32 vcc, 0, v3
	s_nop 1
	v_addc_co_u32_e32 v0, vcc, v0, v1, vcc
	v_cmp_ne_u32_e32 vcc, 0, v4
	s_nop 1
	v_cndmask_b32_e64 v1, 0, 1, vcc
	v_cmp_ne_u32_e32 vcc, 0, v5
	s_nop 1
	v_addc_co_u32_e32 v0, vcc, v0, v1, vcc
	v_cmp_ne_u32_e32 vcc, 0, v6
	s_nop 1
	v_cndmask_b32_e64 v1, 0, 1, vcc
	v_cmp_ne_u32_e32 vcc, 0, v7
	s_nop 1
	v_addc_co_u32_e32 v0, vcc, v0, v1, vcc
	v_cmp_ne_u32_e32 vcc, 0, v8
	s_nop 1
	v_cndmask_b32_e64 v1, 0, 1, vcc
	v_cmp_ne_u32_e32 vcc, 0, v9
	s_nop 1
	v_addc_co_u32_e32 v0, vcc, v0, v1, vcc
	v_cmp_ne_u32_e32 vcc, 0, v10
	s_nop 1
	v_cndmask_b32_e64 v1, 0, 1, vcc
	v_cmp_ne_u32_e32 vcc, 0, v11
	s_nop 1
	v_addc_co_u32_e32 v0, vcc, v0, v1, vcc
	v_cmp_ne_u32_e32 vcc, 0, v12
	s_nop 1
	v_cndmask_b32_e64 v1, 0, 1, vcc
	v_cmp_ne_u32_e32 vcc, 0, v13
	s_nop 1
	v_addc_co_u32_e32 v0, vcc, v0, v1, vcc
	v_cmp_ne_u32_e32 vcc, 0, v14
	s_nop 1
	v_cndmask_b32_e64 v1, 0, 1, vcc
	v_cmp_ne_u32_e32 vcc, 0, v15
	s_nop 1
	v_addc_co_u32_e32 v0, vcc, v0, v1, vcc
	v_mov_b32_e32 v1, 0x20040
	v_max_u32_e32 v0, 1, v0
	ds_write_b32 v1, v2
	v_mov_b32_e32 v1, 0x20044
	ds_write_b32 v1, v0

; DI unsigned xb_ld(unsigned* p)              { return __hip_atomic_load(p, __ATOMIC_RELAXED, __HIP_MEMORY_SCOPE_AGENT); }
; DI unsigned xb_add(unsigned* p, unsigned v) { return __hip_atomic_fetch_add(p, v, __ATOMIC_RELAXED, __HIP_MEMORY_SCOPE_AGENT); }
; #define XB_SPIN(cond, bar) do { unsigned _sp = 0; while (cond) { __builtin_amdgcn_s_sleep(1); \
;     if ((++_sp & 255u) == 0u) { if (xb_ld(&(bar)[XB_TMO])) break; if (_sp > XB_SPIN_CAP) { atomicAdd(&(bar)[XB_TMO], 1u); break; } } } } while (0)
; DI void xcd_barrier(const XcdBarrier& b, const int gw) {
;     ...
;         const unsigned old = xb_add(&bar[XB_XSUB(b.x)], 1u);
;         const unsigned gen = old / nloc;
;         if (old + 1u == (gen + 1u) * nloc) {
;             __builtin_amdgcn_fence(__ATOMIC_RELEASE, "agent");
;             asm volatile("s_waitcnt vmcnt(0)" ::: "memory");
;             const unsigned og = xb_add(&bar[XB_TOP], 1u);
;             const unsigned tg = og / nx;
;             if (og + 1u == (tg + 1u) * nx) xb_add(&bar[XB_TOPGEN], 1u);
;             else XB_SPIN(xb_ld(&bar[XB_TOPGEN]) == tg, bar);
;             __builtin_amdgcn_fence(__ATOMIC_ACQUIRE, "agent");
;             xb_add(&bar[XB_XGEN(b.x)], 1u);
.LBB0_528:
	s_andn2_saveexec_b64 s[8:9], s[8:9]
	s_cbranch_execz .LBB0_548
	s_mov_b64 s[8:9], exec
	s_add_i32 s98, s36, -1
	s_lshr_b32 s98, 0x1f3e7cf8, s98
	s_bitcmp1_b32 s98, 0
	s_cbranch_scc0 .Lxb_global
	v_mov_b32_e32 v1, 0x20048
	ds_read_b32 v1, v1
	s_waitcnt lgkmcnt(0)
	v_readfirstlane_b32 s98, v1
	s_cmp_lg_u32 s98, 0
	s_cbranch_scc1 .LBB0_545
.Lxb_global:
	buffer_wbl2 sc1
	s_waitcnt lgkmcnt(0)
	s_waitcnt vmcnt(0)
	v_mbcnt_lo_u32_b32 v1, s8, 0
	v_mbcnt_hi_u32_b32 v1, s9, v1
	v_cmp_eq_u32_e32 vcc, 0, v1
	s_and_saveexec_b64 s[10:11], vcc
	s_cbranch_execz .LBB0_531
	s_bcnt1_i32_b64 s8, s[8:9]
	v_mov_b32_e32 v2, s8
	v_readlane_b32 s8, v254, 50
	v_readlane_b32 s9, v254, 51
	s_nop 4
	global_atomic_add v2, v33, v2, s[8:9] sc0
